# bundle + back-edge rotation + all K-loop LDS-DMA loads in SGPR-base form (no per-load 64-bit VALU adds)
# speedup vs baseline: 1.0151x; 1.0024x over previous
.LBB0_287:
	s_add_u32 s4, s26, 0x11c00000
	s_addc_u32 s5, s27, 0
	s_lshl_b32 s6, s6, 5
	s_and_b32 s12, s6, 0x60
	s_mov_b64 s[6:7], 0x80
	s_add_i32 m0, s35, 0x18000
	v_lshl_add_u64 v[8:9], v[8:9], 0, s[6:7]
	s_lshl_b32 s9, s8, 13
	s_lshl_b32 s13, s12, 7
	s_waitcnt vmcnt(2)
	s_barrier
	global_load_lds_dwordx4 v[8:9], off
	v_lshl_add_u64 v[6:7], v[6:7], 0, s[6:7]
	s_add_i32 m0, s35, 0x1a000
	s_add_i32 s64, s35, 0x8000
	s_add_i32 s65, s35, 0xa000
	global_load_lds_dwordx4 v[6:7], off
	v_lshl_add_u64 v[2:3], v[2:3], 0, s[6:7]
	s_mov_b32 m0, s64
	s_add_u32 s10, s42, 0x80080
	global_load_lds_dwordx4 v[2:3], off
	v_lshl_add_u64 v[2:3], v[4:5], 0, s[6:7]
	s_mov_b32 m0, s65
	s_addc_u32 s11, s43, 0
	global_load_lds_dwordx4 v[2:3], off
	s_add_i32 m0, s35, 0x1c000
	s_nop 0
	global_load_lds_dwordx4 v134, s[10:11]
	s_add_i32 m0, s35, 0x1e000
	s_sext_i32_i16 s73, s2
	global_load_lds_dwordx4 v130, s[10:11]
	v_and_b32_e32 v1, 15, v0
	v_lshlrev_b32_e32 v2, 1, v13
	v_lshlrev_b32_e32 v3, 2, v0
	v_lshlrev_b32_e32 v4, 6, v0
	s_movk_i32 s2, 0x3c0
	v_lshl_or_b32 v150, s8, 6, v1
	v_lshl_or_b32 v1, v1, 6, v2
	v_and_b32_e32 v3, 32, v3
	v_and_or_b32 v2, v4, s2, v2
	v_bitop3_b32 v151, s13, v2, v3 bitop3:0xf6
	v_lshlrev_b32_e32 v2, 9, v0
	v_bitop3_b32 v1, v1, s9, v3 bitop3:0xde
	v_and_b32_e32 v2, 0x30000, v2
	v_lshlrev_b32_e32 v3, 12, v14
	v_or3_b32 v2, v11, v2, v3
	v_add_u32_e32 v138, v2, v12
	v_lshlrev_b32_e32 v2, 5, v10
	s_waitcnt vmcnt(6)
	s_cmpk_lt_u32 s3, 0x100
	v_and_b32_e32 v2, 0x70000, v2
	s_cselect_b64 s[8:9], -1, 0
	v_or3_b32 v2, v11, v2, v3
	s_add_i32 s70, 0, 0x10000
	s_add_i32 s71, 0, 0x14000
	s_mov_b32 s66, 0
	s_ashr_i32 s67, s33, 31
	v_or_b32_e32 v152, s12, v13
	v_mov_b32_e32 v139, v135
	v_add_u32_e32 v140, v2, v12
	v_mov_b32_e32 v141, v135
	v_mov_b64_e32 v[142:143], 0x1600
	v_mov_b64_e32 v[144:145], 0x15ff
	v_add_u32_e32 v153, s70, v151
	v_add_u32_e32 v154, s71, v151
	v_add_u32_e32 v155, 0, v1
	s_movk_i32 s72, 0x2c00
	s_barrier
	s_branch .LBB0_290

.LBB0_292:
	s_ashr_i32 s13, s12, 31
	s_lshl_b64 s[14:15], s[12:13], 20
	s_add_u32 s14, s19, s14
	s_addc_u32 s15, s22, s15
	s_and_b64 s[16:17], s[2:3], exec
	s_cselect_b32 s13, s15, s41
	s_cselect_b32 s74, s14, s40
	s_ashr_i32 s11, s10, 31
	s_lshl_b64 s[16:17], s[10:11], 20
	s_add_u32 s16, s23, s16
	s_addc_u32 s17, s28, s17
	s_and_b64 s[54:55], s[2:3], exec
	s_cselect_b32 s11, s17, s43
	s_cselect_b32 s75, s16, s42
	s_add_u32 s40, s40, 0x80080
	s_addc_u32 s41, s41, 0
	s_add_u32 s76, s42, 0x100
	s_addc_u32 s77, s43, 0
	s_mov_b32 s78, -2
	ds_read_b128 v[146:149], v153
	ds_read_b128 v[156:159], v153 offset:1024
	ds_read_b128 v[160:163], v153 offset:2048
	ds_read_b128 v[164:167], v153 offset:3072
	ds_read_b128 v[168:171], v154
	ds_read_b128 v[172:175], v154 offset:1024
	ds_read_b128 v[180:183], v154 offset:2048
	ds_read_b128 v[184:187], v154 offset:3072
	s_add_u32 s42, s40, 0xfff80080
	s_addc_u32 s43, s41, -1
	s_cmp_eq_u32 s78, 28
	s_cselect_b32 s55, s13, s43
	s_cselect_b32 s54, s74, s42
	s_cselect_b32 s43, s11, s77
	s_cselect_b32 s42, s75, s76
	s_add_i32 m0, s35, 0xc000
	ds_read_b128 v[188:191], v155
	ds_read_b128 v[192:195], v155 offset:1024
	ds_read_b128 v[196:199], v155 offset:2048
	ds_read_b128 v[200:203], v155 offset:3072
	ds_read_b128 v[204:207], v155 offset:4096
	ds_read_b128 v[208:211], v155 offset:5120
	ds_read_b128 v[212:215], v155 offset:6144
	ds_read_b128 v[216:219], v155 offset:7168
	global_load_lds_dwordx4 v138, s[40:41]
	s_add_i32 m0, s35, 0xe000
	s_nop 0
	global_load_lds_dwordx4 v140, s[40:41]
	s_waitcnt vmcnt(8)
	s_waitcnt lgkmcnt(0)
	s_setprio 1
	s_barrier
	v_mfma_f32_16x16x32_bf16 v[126:129], v[146:149], v[188:191], 0
	v_mfma_f32_16x16x32_bf16 v[118:121], v[160:163], v[188:191], 0
	v_mfma_f32_16x16x32_bf16 v[110:113], v[146:149], v[196:199], 0
	v_mfma_f32_16x16x32_bf16 v[102:105], v[160:163], v[196:199], 0
	v_mfma_f32_16x16x32_bf16 v[94:97], v[146:149], v[204:207], 0
	v_mfma_f32_16x16x32_bf16 v[86:89], v[160:163], v[204:207], 0
	v_mfma_f32_16x16x32_bf16 v[78:81], v[146:149], v[212:215], 0
	v_mfma_f32_16x16x32_bf16 v[70:73], v[160:163], v[212:215], 0
	v_mfma_f32_16x16x32_bf16 v[126:129], v[156:159], v[192:195], v[126:129]
	v_mfma_f32_16x16x32_bf16 v[118:121], v[164:167], v[192:195], v[118:121]
	v_mfma_f32_16x16x32_bf16 v[110:113], v[156:159], v[200:203], v[110:113]
	v_mfma_f32_16x16x32_bf16 v[102:105], v[164:167], v[200:203], v[102:105]
	v_mfma_f32_16x16x32_bf16 v[94:97], v[156:159], v[208:211], v[94:97]
	v_mfma_f32_16x16x32_bf16 v[86:89], v[164:167], v[208:211], v[86:89]
	v_mfma_f32_16x16x32_bf16 v[78:81], v[156:159], v[216:219], v[78:81]
	v_mfma_f32_16x16x32_bf16 v[70:73], v[164:167], v[216:219], v[70:73]
	s_setprio 0
	s_setprio 1
	v_mfma_f32_16x16x32_bf16 v[122:125], v[168:171], v[188:191], 0
	v_mfma_f32_16x16x32_bf16 v[114:117], v[180:183], v[188:191], 0
	v_mfma_f32_16x16x32_bf16 v[106:109], v[168:171], v[196:199], 0
	v_mfma_f32_16x16x32_bf16 v[98:101], v[180:183], v[196:199], 0
	v_mfma_f32_16x16x32_bf16 v[90:93], v[168:171], v[204:207], 0
	v_mfma_f32_16x16x32_bf16 v[82:85], v[180:183], v[204:207], 0
	v_mfma_f32_16x16x32_bf16 v[74:77], v[168:171], v[212:215], 0
	v_mfma_f32_16x16x32_bf16 v[66:69], v[180:183], v[212:215], 0
	v_mfma_f32_16x16x32_bf16 v[122:125], v[172:175], v[192:195], v[122:125]
	v_mfma_f32_16x16x32_bf16 v[114:117], v[184:187], v[192:195], v[114:117]
	v_mfma_f32_16x16x32_bf16 v[106:109], v[172:175], v[200:203], v[106:109]
	v_mfma_f32_16x16x32_bf16 v[98:101], v[184:187], v[200:203], v[98:101]
	v_mfma_f32_16x16x32_bf16 v[90:93], v[172:175], v[208:211], v[90:93]
	v_mfma_f32_16x16x32_bf16 v[82:85], v[184:187], v[208:211], v[82:85]
	v_mfma_f32_16x16x32_bf16 v[74:77], v[172:175], v[216:219], v[74:77]
	v_mfma_f32_16x16x32_bf16 v[66:69], v[184:187], v[216:219], v[66:69]
	s_barrier
	s_setprio 0
	s_add_i32 s79, s70, s29
	s_add_u32 s98, s42, 0x80
	s_addc_u32 s99, s43, 0
	s_mov_b32 m0, s79
	ds_read_b128 v[188:191], v155 offset:16384
	ds_read_b128 v[192:195], v155 offset:17408
	ds_read_b128 v[196:199], v155 offset:18432
	ds_read_b128 v[200:203], v155 offset:19456
	ds_read_b128 v[204:207], v155 offset:20480
	ds_read_b128 v[208:211], v155 offset:21504
	ds_read_b128 v[212:215], v155 offset:22528
	ds_read_b128 v[216:219], v155 offset:23552
	global_load_lds_dwordx4 v134, s[42:43]
	s_add_i32 m0, s79, 0x2000
	s_add_u32 s80, s42, 0x80000
	s_addc_u32 s81, s43, 0
	s_add_i32 s79, s71, s29
	global_load_lds_dwordx4 v130, s[42:43]
	s_mov_b32 m0, s79
	s_nop 0
	global_load_lds_dwordx4 v134, s[80:81]
	s_add_i32 m0, s79, 0x2000
	s_nop 0
	global_load_lds_dwordx4 v130, s[80:81]
	s_add_u32 s100, s54, 0x80
	s_addc_u32 s101, s55, 0
	s_mov_b32 m0, s35
	s_nop 0
	global_load_lds_dwordx4 v136, s[54:55]
	s_mov_b32 m0, s57
	s_nop 0
	global_load_lds_dwordx4 v132, s[54:55]
	s_waitcnt vmcnt(8)
	s_waitcnt lgkmcnt(0)
	s_setprio 1
	s_barrier
	v_mfma_f32_16x16x32_bf16 v[62:65], v[146:149], v[188:191], 0
	v_mfma_f32_16x16x32_bf16 v[54:57], v[160:163], v[188:191], 0
	v_mfma_f32_16x16x32_bf16 v[46:49], v[146:149], v[196:199], 0
	v_mfma_f32_16x16x32_bf16 v[38:41], v[160:163], v[196:199], 0
	v_mfma_f32_16x16x32_bf16 v[30:33], v[146:149], v[204:207], 0
	v_mfma_f32_16x16x32_bf16 v[22:25], v[160:163], v[204:207], 0
	v_mfma_f32_16x16x32_bf16 v[14:17], v[146:149], v[212:215], 0
	v_mfma_f32_16x16x32_bf16 v[6:9], v[160:163], v[212:215], 0
	v_mfma_f32_16x16x32_bf16 v[62:65], v[156:159], v[192:195], v[62:65]
	v_mfma_f32_16x16x32_bf16 v[54:57], v[164:167], v[192:195], v[54:57]
	v_mfma_f32_16x16x32_bf16 v[46:49], v[156:159], v[200:203], v[46:49]
	v_mfma_f32_16x16x32_bf16 v[38:41], v[164:167], v[200:203], v[38:41]
	v_mfma_f32_16x16x32_bf16 v[30:33], v[156:159], v[208:211], v[30:33]
	v_mfma_f32_16x16x32_bf16 v[22:25], v[164:167], v[208:211], v[22:25]
	v_mfma_f32_16x16x32_bf16 v[14:17], v[156:159], v[216:219], v[14:17]
	v_mfma_f32_16x16x32_bf16 v[6:9], v[164:167], v[216:219], v[6:9]
	s_setprio 0
	s_setprio 1
	v_mfma_f32_16x16x32_bf16 v[58:61], v[168:171], v[188:191], 0
	v_mfma_f32_16x16x32_bf16 v[50:53], v[180:183], v[188:191], 0
	v_mfma_f32_16x16x32_bf16 v[42:45], v[168:171], v[196:199], 0
	v_mfma_f32_16x16x32_bf16 v[34:37], v[180:183], v[196:199], 0
	v_mfma_f32_16x16x32_bf16 v[26:29], v[168:171], v[204:207], 0
	v_mfma_f32_16x16x32_bf16 v[18:21], v[180:183], v[204:207], 0
	v_mfma_f32_16x16x32_bf16 v[10:13], v[168:171], v[212:215], 0
	v_mfma_f32_16x16x32_bf16 v[2:5], v[180:183], v[212:215], 0
	v_mfma_f32_16x16x32_bf16 v[58:61], v[172:175], v[192:195], v[58:61]
	v_mfma_f32_16x16x32_bf16 v[50:53], v[184:187], v[192:195], v[50:53]
	v_mfma_f32_16x16x32_bf16 v[42:45], v[172:175], v[200:203], v[42:45]
	v_mfma_f32_16x16x32_bf16 v[34:37], v[184:187], v[200:203], v[34:37]
	v_mfma_f32_16x16x32_bf16 v[26:29], v[172:175], v[208:211], v[26:29]
	v_mfma_f32_16x16x32_bf16 v[18:21], v[184:187], v[208:211], v[18:21]
	v_mfma_f32_16x16x32_bf16 v[10:13], v[172:175], v[216:219], v[10:13]
	v_mfma_f32_16x16x32_bf16 v[2:5], v[184:187], v[216:219], v[2:5]
	s_barrier
	s_setprio 0
	s_add_i32 s79, 0, 0x18000
	v_add_u32_e32 v1, s79, v151
	s_add_i32 s80, 0, 0x1c000
	ds_read_b128 v[146:149], v1
	ds_read_b128 v[156:159], v1 offset:1024
	ds_read_b128 v[160:163], v1 offset:2048
	ds_read_b128 v[164:167], v1 offset:3072
	v_add_u32_e32 v1, s80, v151
	ds_read_b128 v[168:171], v1
	ds_read_b128 v[172:175], v1 offset:1024
	ds_read_b128 v[180:183], v1 offset:2048
	ds_read_b128 v[184:187], v1 offset:3072
	s_add_u32 s54, s54, 0x80000
	s_addc_u32 s55, s55, 0
	s_mov_b32 m0, s58
	ds_read_b128 v[188:191], v155 offset:32768
	ds_read_b128 v[192:195], v155 offset:33792
	ds_read_b128 v[196:199], v155 offset:34816
	ds_read_b128 v[200:203], v155 offset:35840
	ds_read_b128 v[204:207], v155 offset:36864
	ds_read_b128 v[208:211], v155 offset:37888
	ds_read_b128 v[212:215], v155 offset:38912
	ds_read_b128 v[216:219], v155 offset:39936
	global_load_lds_dwordx4 v136, s[54:55]
	s_mov_b32 m0, s59
	s_nop 0
	global_load_lds_dwordx4 v132, s[54:55]
	s_waitcnt vmcnt(8)
	s_waitcnt lgkmcnt(0)
	s_setprio 1
	s_barrier
	v_mfma_f32_16x16x32_bf16 v[126:129], v[146:149], v[188:191], v[126:129]
	v_mfma_f32_16x16x32_bf16 v[118:121], v[160:163], v[188:191], v[118:121]
	v_mfma_f32_16x16x32_bf16 v[110:113], v[146:149], v[196:199], v[110:113]
	v_mfma_f32_16x16x32_bf16 v[102:105], v[160:163], v[196:199], v[102:105]
	v_mfma_f32_16x16x32_bf16 v[94:97], v[146:149], v[204:207], v[94:97]
	v_mfma_f32_16x16x32_bf16 v[86:89], v[160:163], v[204:207], v[86:89]
	v_mfma_f32_16x16x32_bf16 v[78:81], v[146:149], v[212:215], v[78:81]
	v_mfma_f32_16x16x32_bf16 v[70:73], v[160:163], v[212:215], v[70:73]
	v_mfma_f32_16x16x32_bf16 v[126:129], v[156:159], v[192:195], v[126:129]
	v_mfma_f32_16x16x32_bf16 v[118:121], v[164:167], v[192:195], v[118:121]
	v_mfma_f32_16x16x32_bf16 v[110:113], v[156:159], v[200:203], v[110:113]
	v_mfma_f32_16x16x32_bf16 v[102:105], v[164:167], v[200:203], v[102:105]
	v_mfma_f32_16x16x32_bf16 v[94:97], v[156:159], v[208:211], v[94:97]
	v_mfma_f32_16x16x32_bf16 v[86:89], v[164:167], v[208:211], v[86:89]
	v_mfma_f32_16x16x32_bf16 v[78:81], v[156:159], v[216:219], v[78:81]
	v_mfma_f32_16x16x32_bf16 v[70:73], v[164:167], v[216:219], v[70:73]
	s_setprio 0
	s_setprio 1
	v_mfma_f32_16x16x32_bf16 v[122:125], v[168:171], v[188:191], v[122:125]
	v_mfma_f32_16x16x32_bf16 v[114:117], v[180:183], v[188:191], v[114:117]
	v_mfma_f32_16x16x32_bf16 v[106:109], v[168:171], v[196:199], v[106:109]
	v_mfma_f32_16x16x32_bf16 v[98:101], v[180:183], v[196:199], v[98:101]
	v_mfma_f32_16x16x32_bf16 v[90:93], v[168:171], v[204:207], v[90:93]
	v_mfma_f32_16x16x32_bf16 v[82:85], v[180:183], v[204:207], v[82:85]
	v_mfma_f32_16x16x32_bf16 v[74:77], v[168:171], v[212:215], v[74:77]
	v_mfma_f32_16x16x32_bf16 v[66:69], v[180:183], v[212:215], v[66:69]
	v_mfma_f32_16x16x32_bf16 v[122:125], v[172:175], v[192:195], v[122:125]
	v_mfma_f32_16x16x32_bf16 v[114:117], v[184:187], v[192:195], v[114:117]
	v_mfma_f32_16x16x32_bf16 v[106:109], v[172:175], v[200:203], v[106:109]
	v_mfma_f32_16x16x32_bf16 v[98:101], v[184:187], v[200:203], v[98:101]
	v_mfma_f32_16x16x32_bf16 v[90:93], v[172:175], v[208:211], v[90:93]
	v_mfma_f32_16x16x32_bf16 v[82:85], v[184:187], v[208:211], v[82:85]
	v_mfma_f32_16x16x32_bf16 v[74:77], v[172:175], v[216:219], v[74:77]
	v_mfma_f32_16x16x32_bf16 v[66:69], v[184:187], v[216:219], v[66:69]
	s_barrier
	s_setprio 0
	s_add_i32 s54, s79, s29
	s_mov_b32 m0, s54
	ds_read_b128 v[188:191], v155 offset:49152
	ds_read_b128 v[192:195], v155 offset:50176
	ds_read_b128 v[196:199], v155 offset:51200
	ds_read_b128 v[200:203], v155 offset:52224
	ds_read_b128 v[204:207], v155 offset:53248
	ds_read_b128 v[208:211], v155 offset:54272
	ds_read_b128 v[212:215], v155 offset:55296
	ds_read_b128 v[216:219], v155 offset:56320
	global_load_lds_dwordx4 v134, s[98:99]
	s_add_i32 m0, s54, 0x2000
	s_add_u32 s42, s42, 0x80080
	s_addc_u32 s43, s43, 0
	s_add_i32 s54, s80, s29
	global_load_lds_dwordx4 v130, s[98:99]
	s_mov_b32 m0, s54
	s_nop 0
	global_load_lds_dwordx4 v134, s[42:43]
	s_add_i32 m0, s54, 0x2000
	s_nop 0
	global_load_lds_dwordx4 v130, s[42:43]
	s_mov_b32 m0, s64
	s_nop 0
	global_load_lds_dwordx4 v136, s[100:101]
	s_mov_b32 m0, s65
	s_nop 0
	global_load_lds_dwordx4 v132, s[100:101]
	s_waitcnt vmcnt(8)
	s_waitcnt lgkmcnt(0)
	s_setprio 1
	s_barrier
	v_mfma_f32_16x16x32_bf16 v[62:65], v[146:149], v[188:191], v[62:65]
	v_mfma_f32_16x16x32_bf16 v[54:57], v[160:163], v[188:191], v[54:57]
	v_mfma_f32_16x16x32_bf16 v[46:49], v[146:149], v[196:199], v[46:49]
	v_mfma_f32_16x16x32_bf16 v[38:41], v[160:163], v[196:199], v[38:41]
	v_mfma_f32_16x16x32_bf16 v[30:33], v[146:149], v[204:207], v[30:33]
	v_mfma_f32_16x16x32_bf16 v[22:25], v[160:163], v[204:207], v[22:25]
	v_mfma_f32_16x16x32_bf16 v[14:17], v[146:149], v[212:215], v[14:17]
	v_mfma_f32_16x16x32_bf16 v[6:9], v[160:163], v[212:215], v[6:9]
	v_mfma_f32_16x16x32_bf16 v[62:65], v[156:159], v[192:195], v[62:65]
	v_mfma_f32_16x16x32_bf16 v[54:57], v[164:167], v[192:195], v[54:57]
	v_mfma_f32_16x16x32_bf16 v[46:49], v[156:159], v[200:203], v[46:49]
	v_mfma_f32_16x16x32_bf16 v[38:41], v[164:167], v[200:203], v[38:41]
	v_mfma_f32_16x16x32_bf16 v[30:33], v[156:159], v[208:211], v[30:33]
	v_mfma_f32_16x16x32_bf16 v[22:25], v[164:167], v[208:211], v[22:25]
	v_mfma_f32_16x16x32_bf16 v[14:17], v[156:159], v[216:219], v[14:17]
	v_mfma_f32_16x16x32_bf16 v[6:9], v[164:167], v[216:219], v[6:9]
	s_setprio 0
	s_setprio 1
	v_mfma_f32_16x16x32_bf16 v[58:61], v[168:171], v[188:191], v[58:61]
	v_mfma_f32_16x16x32_bf16 v[50:53], v[180:183], v[188:191], v[50:53]
	v_mfma_f32_16x16x32_bf16 v[42:45], v[168:171], v[196:199], v[42:45]
	v_mfma_f32_16x16x32_bf16 v[34:37], v[180:183], v[196:199], v[34:37]
	v_mfma_f32_16x16x32_bf16 v[26:29], v[168:171], v[204:207], v[26:29]
	v_mfma_f32_16x16x32_bf16 v[18:21], v[180:183], v[204:207], v[18:21]
	v_mfma_f32_16x16x32_bf16 v[10:13], v[168:171], v[212:215], v[10:13]
	v_mfma_f32_16x16x32_bf16 v[2:5], v[180:183], v[212:215], v[2:5]
	v_mfma_f32_16x16x32_bf16 v[58:61], v[172:175], v[192:195], v[58:61]
	v_mfma_f32_16x16x32_bf16 v[50:53], v[184:187], v[192:195], v[50:53]
	v_mfma_f32_16x16x32_bf16 v[42:45], v[172:175], v[200:203], v[42:45]
	v_mfma_f32_16x16x32_bf16 v[34:37], v[184:187], v[200:203], v[34:37]
	v_mfma_f32_16x16x32_bf16 v[26:29], v[172:175], v[208:211], v[26:29]
	v_mfma_f32_16x16x32_bf16 v[18:21], v[184:187], v[208:211], v[18:21]
	v_mfma_f32_16x16x32_bf16 v[10:13], v[172:175], v[216:219], v[10:13]
	v_mfma_f32_16x16x32_bf16 v[2:5], v[184:187], v[216:219], v[2:5]
	s_barrier
	s_setprio 0
	s_add_i32 s78, s78, 2
	s_add_u32 s40, s40, 0x100
	s_addc_u32 s41, s41, 0
	s_add_u32 s76, s76, 0x100
	s_addc_u32 s77, s77, 0
	s_cmp_gt_u32 s78, 29
.LBB0_293:
	ds_read_b128 v[146:149], v153
	ds_read_b128 v[156:159], v153 offset:1024
	ds_read_b128 v[160:163], v153 offset:2048
	ds_read_b128 v[164:167], v153 offset:3072
	ds_read_b128 v[168:171], v154
	ds_read_b128 v[172:175], v154 offset:1024
	ds_read_b128 v[180:183], v154 offset:2048
	ds_read_b128 v[184:187], v154 offset:3072
	s_add_u32 s42, s40, 0xfff80080
	s_addc_u32 s43, s41, -1
	s_cmp_eq_u32 s78, 28
	s_cselect_b32 s55, s13, s43
	s_cselect_b32 s54, s74, s42
	s_cselect_b32 s43, s11, s77
	s_cselect_b32 s42, s75, s76
	s_add_i32 m0, s35, 0xc000
	ds_read_b128 v[188:191], v155
	ds_read_b128 v[192:195], v155 offset:1024
	ds_read_b128 v[196:199], v155 offset:2048
	ds_read_b128 v[200:203], v155 offset:3072
	ds_read_b128 v[204:207], v155 offset:4096
	ds_read_b128 v[208:211], v155 offset:5120
	ds_read_b128 v[212:215], v155 offset:6144
	ds_read_b128 v[216:219], v155 offset:7168
	global_load_lds_dwordx4 v138, s[40:41]
	s_add_i32 m0, s35, 0xe000
	s_nop 0
	global_load_lds_dwordx4 v140, s[40:41]
	s_waitcnt vmcnt(8)
	s_waitcnt lgkmcnt(0)
	s_setprio 1
	s_barrier
	v_mfma_f32_16x16x32_bf16 v[126:129], v[146:149], v[188:191], v[126:129]
	v_mfma_f32_16x16x32_bf16 v[118:121], v[160:163], v[188:191], v[118:121]
	v_mfma_f32_16x16x32_bf16 v[110:113], v[146:149], v[196:199], v[110:113]
	v_mfma_f32_16x16x32_bf16 v[102:105], v[160:163], v[196:199], v[102:105]
	v_mfma_f32_16x16x32_bf16 v[94:97], v[146:149], v[204:207], v[94:97]
	v_mfma_f32_16x16x32_bf16 v[86:89], v[160:163], v[204:207], v[86:89]
	v_mfma_f32_16x16x32_bf16 v[78:81], v[146:149], v[212:215], v[78:81]
	v_mfma_f32_16x16x32_bf16 v[70:73], v[160:163], v[212:215], v[70:73]
	v_mfma_f32_16x16x32_bf16 v[126:129], v[156:159], v[192:195], v[126:129]
	v_mfma_f32_16x16x32_bf16 v[118:121], v[164:167], v[192:195], v[118:121]
	v_mfma_f32_16x16x32_bf16 v[110:113], v[156:159], v[200:203], v[110:113]
	v_mfma_f32_16x16x32_bf16 v[102:105], v[164:167], v[200:203], v[102:105]
	v_mfma_f32_16x16x32_bf16 v[94:97], v[156:159], v[208:211], v[94:97]
	v_mfma_f32_16x16x32_bf16 v[86:89], v[164:167], v[208:211], v[86:89]
	v_mfma_f32_16x16x32_bf16 v[78:81], v[156:159], v[216:219], v[78:81]
	v_mfma_f32_16x16x32_bf16 v[70:73], v[164:167], v[216:219], v[70:73]
	s_setprio 0
	s_setprio 1
	v_mfma_f32_16x16x32_bf16 v[122:125], v[168:171], v[188:191], v[122:125]
	v_mfma_f32_16x16x32_bf16 v[114:117], v[180:183], v[188:191], v[114:117]
	v_mfma_f32_16x16x32_bf16 v[106:109], v[168:171], v[196:199], v[106:109]
	v_mfma_f32_16x16x32_bf16 v[98:101], v[180:183], v[196:199], v[98:101]
	v_mfma_f32_16x16x32_bf16 v[90:93], v[168:171], v[204:207], v[90:93]
	v_mfma_f32_16x16x32_bf16 v[82:85], v[180:183], v[204:207], v[82:85]
	v_mfma_f32_16x16x32_bf16 v[74:77], v[168:171], v[212:215], v[74:77]
	v_mfma_f32_16x16x32_bf16 v[66:69], v[180:183], v[212:215], v[66:69]
	v_mfma_f32_16x16x32_bf16 v[122:125], v[172:175], v[192:195], v[122:125]
	v_mfma_f32_16x16x32_bf16 v[114:117], v[184:187], v[192:195], v[114:117]
	v_mfma_f32_16x16x32_bf16 v[106:109], v[172:175], v[200:203], v[106:109]
	v_mfma_f32_16x16x32_bf16 v[98:101], v[184:187], v[200:203], v[98:101]
	v_mfma_f32_16x16x32_bf16 v[90:93], v[172:175], v[208:211], v[90:93]
	v_mfma_f32_16x16x32_bf16 v[82:85], v[184:187], v[208:211], v[82:85]
	v_mfma_f32_16x16x32_bf16 v[74:77], v[172:175], v[216:219], v[74:77]
	v_mfma_f32_16x16x32_bf16 v[66:69], v[184:187], v[216:219], v[66:69]
	s_barrier
	s_setprio 0
	s_add_i32 s79, s70, s29
	s_add_u32 s98, s42, 0x80
	s_addc_u32 s99, s43, 0
	s_mov_b32 m0, s79
	ds_read_b128 v[188:191], v155 offset:16384
	ds_read_b128 v[192:195], v155 offset:17408
	ds_read_b128 v[196:199], v155 offset:18432
	ds_read_b128 v[200:203], v155 offset:19456
	ds_read_b128 v[204:207], v155 offset:20480
	ds_read_b128 v[208:211], v155 offset:21504
	ds_read_b128 v[212:215], v155 offset:22528
	ds_read_b128 v[216:219], v155 offset:23552
	global_load_lds_dwordx4 v134, s[42:43]
	s_add_i32 m0, s79, 0x2000
	s_add_u32 s80, s42, 0x80000
	s_addc_u32 s81, s43, 0
	s_add_i32 s79, s71, s29
	global_load_lds_dwordx4 v130, s[42:43]
	s_mov_b32 m0, s79
	s_nop 0
	global_load_lds_dwordx4 v134, s[80:81]
	s_add_i32 m0, s79, 0x2000
	s_nop 0
	global_load_lds_dwordx4 v130, s[80:81]
	s_add_u32 s100, s54, 0x80
	s_addc_u32 s101, s55, 0
	s_mov_b32 m0, s35
	s_nop 0
	global_load_lds_dwordx4 v136, s[54:55]
	s_mov_b32 m0, s57
	s_nop 0
	global_load_lds_dwordx4 v132, s[54:55]
	s_waitcnt vmcnt(8)
	s_waitcnt lgkmcnt(0)
	s_setprio 1
	s_barrier
	v_mfma_f32_16x16x32_bf16 v[62:65], v[146:149], v[188:191], v[62:65]
	v_mfma_f32_16x16x32_bf16 v[54:57], v[160:163], v[188:191], v[54:57]
	v_mfma_f32_16x16x32_bf16 v[46:49], v[146:149], v[196:199], v[46:49]
	v_mfma_f32_16x16x32_bf16 v[38:41], v[160:163], v[196:199], v[38:41]
	v_mfma_f32_16x16x32_bf16 v[30:33], v[146:149], v[204:207], v[30:33]
	v_mfma_f32_16x16x32_bf16 v[22:25], v[160:163], v[204:207], v[22:25]
	v_mfma_f32_16x16x32_bf16 v[14:17], v[146:149], v[212:215], v[14:17]
	v_mfma_f32_16x16x32_bf16 v[6:9], v[160:163], v[212:215], v[6:9]
	v_mfma_f32_16x16x32_bf16 v[62:65], v[156:159], v[192:195], v[62:65]
	v_mfma_f32_16x16x32_bf16 v[54:57], v[164:167], v[192:195], v[54:57]
	v_mfma_f32_16x16x32_bf16 v[46:49], v[156:159], v[200:203], v[46:49]
	v_mfma_f32_16x16x32_bf16 v[38:41], v[164:167], v[200:203], v[38:41]
	v_mfma_f32_16x16x32_bf16 v[30:33], v[156:159], v[208:211], v[30:33]
	v_mfma_f32_16x16x32_bf16 v[22:25], v[164:167], v[208:211], v[22:25]
	v_mfma_f32_16x16x32_bf16 v[14:17], v[156:159], v[216:219], v[14:17]
	v_mfma_f32_16x16x32_bf16 v[6:9], v[164:167], v[216:219], v[6:9]
	s_setprio 0
	s_setprio 1
	v_mfma_f32_16x16x32_bf16 v[58:61], v[168:171], v[188:191], v[58:61]
	v_mfma_f32_16x16x32_bf16 v[50:53], v[180:183], v[188:191], v[50:53]
	v_mfma_f32_16x16x32_bf16 v[42:45], v[168:171], v[196:199], v[42:45]
	v_mfma_f32_16x16x32_bf16 v[34:37], v[180:183], v[196:199], v[34:37]
	v_mfma_f32_16x16x32_bf16 v[26:29], v[168:171], v[204:207], v[26:29]
	v_mfma_f32_16x16x32_bf16 v[18:21], v[180:183], v[204:207], v[18:21]
	v_mfma_f32_16x16x32_bf16 v[10:13], v[168:171], v[212:215], v[10:13]
	v_mfma_f32_16x16x32_bf16 v[2:5], v[180:183], v[212:215], v[2:5]
	v_mfma_f32_16x16x32_bf16 v[58:61], v[172:175], v[192:195], v[58:61]
	v_mfma_f32_16x16x32_bf16 v[50:53], v[184:187], v[192:195], v[50:53]
	v_mfma_f32_16x16x32_bf16 v[42:45], v[172:175], v[200:203], v[42:45]
	v_mfma_f32_16x16x32_bf16 v[34:37], v[184:187], v[200:203], v[34:37]
	v_mfma_f32_16x16x32_bf16 v[26:29], v[172:175], v[208:211], v[26:29]
	v_mfma_f32_16x16x32_bf16 v[18:21], v[184:187], v[208:211], v[18:21]
	v_mfma_f32_16x16x32_bf16 v[10:13], v[172:175], v[216:219], v[10:13]
	v_mfma_f32_16x16x32_bf16 v[2:5], v[184:187], v[216:219], v[2:5]
	s_barrier
	s_setprio 0
	s_add_i32 s79, 0, 0x18000
	v_add_u32_e32 v1, s79, v151
	s_add_i32 s80, 0, 0x1c000
	ds_read_b128 v[146:149], v1
	ds_read_b128 v[156:159], v1 offset:1024
	ds_read_b128 v[160:163], v1 offset:2048
	ds_read_b128 v[164:167], v1 offset:3072
	v_add_u32_e32 v1, s80, v151
	ds_read_b128 v[168:171], v1
	ds_read_b128 v[172:175], v1 offset:1024
	ds_read_b128 v[180:183], v1 offset:2048
	ds_read_b128 v[184:187], v1 offset:3072
	s_add_u32 s54, s54, 0x80000
	s_addc_u32 s55, s55, 0
	s_mov_b32 m0, s58
	ds_read_b128 v[188:191], v155 offset:32768
	ds_read_b128 v[192:195], v155 offset:33792
	ds_read_b128 v[196:199], v155 offset:34816
	ds_read_b128 v[200:203], v155 offset:35840
	ds_read_b128 v[204:207], v155 offset:36864
	ds_read_b128 v[208:211], v155 offset:37888
	ds_read_b128 v[212:215], v155 offset:38912
	ds_read_b128 v[216:219], v155 offset:39936
	global_load_lds_dwordx4 v136, s[54:55]
	s_mov_b32 m0, s59
	s_nop 0
	global_load_lds_dwordx4 v132, s[54:55]
	s_waitcnt vmcnt(8)
	s_waitcnt lgkmcnt(0)
	s_setprio 1
	s_barrier
	v_mfma_f32_16x16x32_bf16 v[126:129], v[146:149], v[188:191], v[126:129]
	v_mfma_f32_16x16x32_bf16 v[118:121], v[160:163], v[188:191], v[118:121]
	v_mfma_f32_16x16x32_bf16 v[110:113], v[146:149], v[196:199], v[110:113]
	v_mfma_f32_16x16x32_bf16 v[102:105], v[160:163], v[196:199], v[102:105]
	v_mfma_f32_16x16x32_bf16 v[94:97], v[146:149], v[204:207], v[94:97]
	v_mfma_f32_16x16x32_bf16 v[86:89], v[160:163], v[204:207], v[86:89]
	v_mfma_f32_16x16x32_bf16 v[78:81], v[146:149], v[212:215], v[78:81]
	v_mfma_f32_16x16x32_bf16 v[70:73], v[160:163], v[212:215], v[70:73]
	v_mfma_f32_16x16x32_bf16 v[126:129], v[156:159], v[192:195], v[126:129]
	v_mfma_f32_16x16x32_bf16 v[118:121], v[164:167], v[192:195], v[118:121]
	v_mfma_f32_16x16x32_bf16 v[110:113], v[156:159], v[200:203], v[110:113]
	v_mfma_f32_16x16x32_bf16 v[102:105], v[164:167], v[200:203], v[102:105]
	v_mfma_f32_16x16x32_bf16 v[94:97], v[156:159], v[208:211], v[94:97]
	v_mfma_f32_16x16x32_bf16 v[86:89], v[164:167], v[208:211], v[86:89]
	v_mfma_f32_16x16x32_bf16 v[78:81], v[156:159], v[216:219], v[78:81]
	v_mfma_f32_16x16x32_bf16 v[70:73], v[164:167], v[216:219], v[70:73]
	s_setprio 0
	s_setprio 1
	v_mfma_f32_16x16x32_bf16 v[122:125], v[168:171], v[188:191], v[122:125]
	v_mfma_f32_16x16x32_bf16 v[114:117], v[180:183], v[188:191], v[114:117]
	v_mfma_f32_16x16x32_bf16 v[106:109], v[168:171], v[196:199], v[106:109]
	v_mfma_f32_16x16x32_bf16 v[98:101], v[180:183], v[196:199], v[98:101]
	v_mfma_f32_16x16x32_bf16 v[90:93], v[168:171], v[204:207], v[90:93]
	v_mfma_f32_16x16x32_bf16 v[82:85], v[180:183], v[204:207], v[82:85]
	v_mfma_f32_16x16x32_bf16 v[74:77], v[168:171], v[212:215], v[74:77]
	v_mfma_f32_16x16x32_bf16 v[66:69], v[180:183], v[212:215], v[66:69]
	v_mfma_f32_16x16x32_bf16 v[122:125], v[172:175], v[192:195], v[122:125]
	v_mfma_f32_16x16x32_bf16 v[114:117], v[184:187], v[192:195], v[114:117]
	v_mfma_f32_16x16x32_bf16 v[106:109], v[172:175], v[200:203], v[106:109]
	v_mfma_f32_16x16x32_bf16 v[98:101], v[184:187], v[200:203], v[98:101]
	v_mfma_f32_16x16x32_bf16 v[90:93], v[172:175], v[208:211], v[90:93]
	v_mfma_f32_16x16x32_bf16 v[82:85], v[184:187], v[208:211], v[82:85]
	v_mfma_f32_16x16x32_bf16 v[74:77], v[172:175], v[216:219], v[74:77]
	v_mfma_f32_16x16x32_bf16 v[66:69], v[184:187], v[216:219], v[66:69]
	s_barrier
	s_setprio 0
	s_add_i32 s54, s79, s29
	s_mov_b32 m0, s54
	ds_read_b128 v[188:191], v155 offset:49152
	ds_read_b128 v[192:195], v155 offset:50176
	ds_read_b128 v[196:199], v155 offset:51200
	ds_read_b128 v[200:203], v155 offset:52224
	ds_read_b128 v[204:207], v155 offset:53248
	ds_read_b128 v[208:211], v155 offset:54272
	ds_read_b128 v[212:215], v155 offset:55296
	ds_read_b128 v[216:219], v155 offset:56320
	global_load_lds_dwordx4 v134, s[98:99]
	s_add_i32 m0, s54, 0x2000
	s_add_u32 s42, s42, 0x80080
	s_addc_u32 s43, s43, 0
	s_add_i32 s54, s80, s29
	global_load_lds_dwordx4 v130, s[98:99]
	s_mov_b32 m0, s54
	s_nop 0
	global_load_lds_dwordx4 v134, s[42:43]
	s_add_i32 m0, s54, 0x2000
	s_nop 0
	global_load_lds_dwordx4 v130, s[42:43]
	s_mov_b32 m0, s64
	s_nop 0
	global_load_lds_dwordx4 v136, s[100:101]
	s_mov_b32 m0, s65
	s_nop 0
	global_load_lds_dwordx4 v132, s[100:101]
	s_add_i32 s78, s78, 2
	s_add_u32 s40, s40, 0x100
	s_addc_u32 s41, s41, 0
	s_add_u32 s76, s76, 0x100
	s_addc_u32 s77, s77, 0
	s_cmp_gt_u32 s78, 29
	s_waitcnt vmcnt(8)
	s_waitcnt lgkmcnt(0)
	s_setprio 1
	s_barrier
	v_mfma_f32_16x16x32_bf16 v[62:65], v[146:149], v[188:191], v[62:65]
	v_mfma_f32_16x16x32_bf16 v[54:57], v[160:163], v[188:191], v[54:57]
	v_mfma_f32_16x16x32_bf16 v[46:49], v[146:149], v[196:199], v[46:49]
	v_mfma_f32_16x16x32_bf16 v[38:41], v[160:163], v[196:199], v[38:41]
	v_mfma_f32_16x16x32_bf16 v[30:33], v[146:149], v[204:207], v[30:33]
	v_mfma_f32_16x16x32_bf16 v[22:25], v[160:163], v[204:207], v[22:25]
	v_mfma_f32_16x16x32_bf16 v[14:17], v[146:149], v[212:215], v[14:17]
	v_mfma_f32_16x16x32_bf16 v[6:9], v[160:163], v[212:215], v[6:9]
	v_mfma_f32_16x16x32_bf16 v[62:65], v[156:159], v[192:195], v[62:65]
	v_mfma_f32_16x16x32_bf16 v[54:57], v[164:167], v[192:195], v[54:57]
	v_mfma_f32_16x16x32_bf16 v[46:49], v[156:159], v[200:203], v[46:49]
	v_mfma_f32_16x16x32_bf16 v[38:41], v[164:167], v[200:203], v[38:41]
	v_mfma_f32_16x16x32_bf16 v[30:33], v[156:159], v[208:211], v[30:33]
	v_mfma_f32_16x16x32_bf16 v[22:25], v[164:167], v[208:211], v[22:25]
	v_mfma_f32_16x16x32_bf16 v[14:17], v[156:159], v[216:219], v[14:17]
	v_mfma_f32_16x16x32_bf16 v[6:9], v[164:167], v[216:219], v[6:9]
	s_setprio 0
	s_setprio 1
	v_mfma_f32_16x16x32_bf16 v[58:61], v[168:171], v[188:191], v[58:61]
	v_mfma_f32_16x16x32_bf16 v[50:53], v[180:183], v[188:191], v[50:53]
	v_mfma_f32_16x16x32_bf16 v[42:45], v[168:171], v[196:199], v[42:45]
	v_mfma_f32_16x16x32_bf16 v[34:37], v[180:183], v[196:199], v[34:37]
	v_mfma_f32_16x16x32_bf16 v[26:29], v[168:171], v[204:207], v[26:29]
	v_mfma_f32_16x16x32_bf16 v[18:21], v[180:183], v[204:207], v[18:21]
	v_mfma_f32_16x16x32_bf16 v[10:13], v[168:171], v[212:215], v[10:13]
	v_mfma_f32_16x16x32_bf16 v[2:5], v[180:183], v[212:215], v[2:5]
	v_mfma_f32_16x16x32_bf16 v[58:61], v[172:175], v[192:195], v[58:61]
	v_mfma_f32_16x16x32_bf16 v[50:53], v[184:187], v[192:195], v[50:53]
	v_mfma_f32_16x16x32_bf16 v[42:45], v[172:175], v[200:203], v[42:45]
	v_mfma_f32_16x16x32_bf16 v[34:37], v[184:187], v[200:203], v[34:37]
	v_mfma_f32_16x16x32_bf16 v[26:29], v[172:175], v[208:211], v[26:29]
	v_mfma_f32_16x16x32_bf16 v[18:21], v[184:187], v[208:211], v[18:21]
	v_mfma_f32_16x16x32_bf16 v[10:13], v[172:175], v[216:219], v[10:13]
	v_mfma_f32_16x16x32_bf16 v[2:5], v[184:187], v[216:219], v[2:5]
	s_barrier
	s_setprio 0
	s_cbranch_scc0 .LBB0_293
	s_and_b64 vcc, exec, s[8:9]
	s_cbranch_vccz .LBB0_296
	s_barrier

.LBB0_365:
	s_add_u32 s14, s26, 0x8000000
	s_addc_u32 s15, s27, 0
	s_lshl_b32 s70, s2, 6
	s_lshl_b32 s5, s2, 13
	s_lshl_b32 s2, s3, 5
	s_mov_b64 s[16:17], 0x80
	s_and_b32 s10, s2, 0x60
	s_add_i32 m0, s31, 0x18000
	v_lshl_add_u64 v[8:9], v[8:9], 0, s[16:17]
	s_lshl_b32 s6, s10, 7
	s_waitcnt vmcnt(2)
	s_barrier
	global_load_lds_dwordx4 v[8:9], off
	v_lshl_add_u64 v[6:7], v[6:7], 0, s[16:17]
	s_add_i32 m0, s31, 0x1a000
	s_add_i32 s71, s31, 0x8000
	s_add_i32 s72, s31, 0xa000
	global_load_lds_dwordx4 v[6:7], off
	v_lshl_add_u64 v[2:3], v[2:3], 0, s[16:17]
	s_mov_b32 m0, s71
	s_add_u32 s2, s56, 0x160080
	global_load_lds_dwordx4 v[2:3], off
	v_lshl_add_u64 v[2:3], v[4:5], 0, s[16:17]
	s_mov_b32 m0, s72
	s_addc_u32 s3, s57, 0
	global_load_lds_dwordx4 v[2:3], off
	s_add_i32 m0, s31, 0x1c000
	s_nop 0
	global_load_lds_dwordx4 v182, s[2:3]
	s_add_i32 m0, s31, 0x1e000
	v_bfe_u32 v1, v0, 4, 2
	global_load_lds_dwordx4 v186, s[2:3]
	v_and_b32_e32 v179, 15, v0
	v_lshlrev_b32_e32 v2, 4, v1
	v_lshlrev_b32_e32 v4, 2, v0
	v_lshlrev_b32_e32 v5, 6, v0
	s_movk_i32 s2, 0x3c0
	v_lshl_or_b32 v3, v179, 6, v2
	v_and_b32_e32 v4, 32, v4
	v_and_or_b32 v2, v5, s2, v2
	s_cmpk_lt_u32 s4, 0x100
	v_bitop3_b32 v3, v3, s5, v4 bitop3:0xde
	v_bitop3_b32 v206, s6, v2, v4 bitop3:0xf6
	s_cselect_b64 s[34:35], -1, 0
	v_cmp_eq_u32_e64 s[2:3], 0, v1
	v_cmp_eq_u32_e64 s[4:5], 1, v1
	v_cmp_eq_u32_e64 s[6:7], 2, v1
	v_cmp_eq_u32_e64 s[8:9], 3, v1
	s_ashr_i32 s73, s33, 31
	s_ashr_i32 s74, s18, 31
	v_lshl_or_b32 v207, v1, 3, s10
	v_add_u16_e32 v1, v10, v11
	s_waitcnt vmcnt(6)
	s_cmp_lg_u64 s[26:27], 0
	v_lshrrev_b16_e32 v1, 1, v1
	s_cselect_b64 s[40:41], -1, 0
	v_add_lshl_u32 v188, v12, v1, 1
	v_add_lshl_u32 v190, v13, v1, 1
	s_add_i32 s75, 0, 0x10000
	s_add_i32 s76, 0, 0x14000
	v_mbcnt_lo_u32_b32 v1, -1, 0
	v_mov_b32_e32 v189, v183
	v_mov_b32_e32 v191, v183
	v_mov_b64_e32 v[192:193], 0x400
	v_mov_b64_e32 v[194:195], 0x3ff
	v_add_u32_e32 v208, s75, v206
	v_add_u32_e32 v209, s76, v206
	v_add_u32_e32 v210, 0, v3
	v_mbcnt_hi_u32_b32 v211, -1, v1
	s_barrier
	s_branch .LBB0_368

.LBB0_378:
	s_add_u32 s12, s58, 0x160080
	s_addc_u32 s13, s59, 0
	s_add_u32 s81, s56, 0x100
	s_addc_u32 s82, s57, 0
	s_mov_b32 s83, -2
	ds_read_b128 v[130:133], v208
	ds_read_b128 v[134:137], v208 offset:1024
	ds_read_b128 v[138:141], v208 offset:2048
	ds_read_b128 v[142:145], v208 offset:3072
	ds_read_b128 v[146:149], v209
	ds_read_b128 v[150:153], v209 offset:1024
	ds_read_b128 v[154:157], v209 offset:2048
	ds_read_b128 v[158:161], v209 offset:3072
	s_add_u32 s56, s12, 0xffea0080
	s_addc_u32 s57, s13, -1
	s_cmpk_eq_i32 s83, 0x54
	s_cselect_b32 s59, s43, s57
	s_cselect_b32 s58, s42, s56
	s_cselect_b32 s57, s55, s82
	s_cselect_b32 s56, s54, s81
	s_add_i32 m0, s31, 0xc000
	ds_read_b128 v[162:165], v210
	ds_read_b128 v[166:169], v210 offset:1024
	ds_read_b128 v[170:173], v210 offset:2048
	ds_read_b128 v[174:177], v210 offset:3072
	ds_read_b128 v[196:199], v210 offset:4096
	ds_read_b128 v[200:203], v210 offset:5120
	ds_read_b128 v[212:215], v210 offset:6144
	ds_read_b128 v[216:219], v210 offset:7168
	global_load_lds_dwordx4 v188, s[12:13]
	s_add_i32 m0, s31, 0xe000
	s_nop 0
	global_load_lds_dwordx4 v190, s[12:13]
	s_waitcnt vmcnt(8)
	s_waitcnt lgkmcnt(0)
	s_setprio 1
	s_barrier
	v_mfma_f32_16x16x32_bf16 v[126:129], v[130:133], v[162:165], 0
	v_mfma_f32_16x16x32_bf16 v[122:125], v[138:141], v[162:165], 0
	v_mfma_f32_16x16x32_bf16 v[110:113], v[130:133], v[170:173], 0
	v_mfma_f32_16x16x32_bf16 v[106:109], v[138:141], v[170:173], 0
	v_mfma_f32_16x16x32_bf16 v[94:97], v[130:133], v[196:199], 0
	v_mfma_f32_16x16x32_bf16 v[90:93], v[138:141], v[196:199], 0
	v_mfma_f32_16x16x32_bf16 v[78:81], v[130:133], v[212:215], 0
	v_mfma_f32_16x16x32_bf16 v[74:77], v[138:141], v[212:215], 0
	v_mfma_f32_16x16x32_bf16 v[126:129], v[134:137], v[166:169], v[126:129]
	v_mfma_f32_16x16x32_bf16 v[122:125], v[142:145], v[166:169], v[122:125]
	v_mfma_f32_16x16x32_bf16 v[110:113], v[134:137], v[174:177], v[110:113]
	v_mfma_f32_16x16x32_bf16 v[106:109], v[142:145], v[174:177], v[106:109]
	v_mfma_f32_16x16x32_bf16 v[94:97], v[134:137], v[200:203], v[94:97]
	v_mfma_f32_16x16x32_bf16 v[90:93], v[142:145], v[200:203], v[90:93]
	v_mfma_f32_16x16x32_bf16 v[78:81], v[134:137], v[216:219], v[78:81]
	v_mfma_f32_16x16x32_bf16 v[74:77], v[142:145], v[216:219], v[74:77]
	s_setprio 0
	s_setprio 1
	v_mfma_f32_16x16x32_bf16 v[118:121], v[146:149], v[162:165], 0
	v_mfma_f32_16x16x32_bf16 v[114:117], v[154:157], v[162:165], 0
	v_mfma_f32_16x16x32_bf16 v[102:105], v[146:149], v[170:173], 0
	v_mfma_f32_16x16x32_bf16 v[98:101], v[154:157], v[170:173], 0
	v_mfma_f32_16x16x32_bf16 v[86:89], v[146:149], v[196:199], 0
	v_mfma_f32_16x16x32_bf16 v[82:85], v[154:157], v[196:199], 0
	v_mfma_f32_16x16x32_bf16 v[70:73], v[146:149], v[212:215], 0
	v_mfma_f32_16x16x32_bf16 v[66:69], v[154:157], v[212:215], 0
	v_mfma_f32_16x16x32_bf16 v[118:121], v[150:153], v[166:169], v[118:121]
	v_mfma_f32_16x16x32_bf16 v[114:117], v[158:161], v[166:169], v[114:117]
	v_mfma_f32_16x16x32_bf16 v[102:105], v[150:153], v[174:177], v[102:105]
	v_mfma_f32_16x16x32_bf16 v[98:101], v[158:161], v[174:177], v[98:101]
	v_mfma_f32_16x16x32_bf16 v[86:89], v[150:153], v[200:203], v[86:89]
	v_mfma_f32_16x16x32_bf16 v[82:85], v[158:161], v[200:203], v[82:85]
	v_mfma_f32_16x16x32_bf16 v[70:73], v[150:153], v[216:219], v[70:73]
	v_mfma_f32_16x16x32_bf16 v[66:69], v[158:161], v[216:219], v[66:69]
	s_barrier
	s_setprio 0
	s_add_i32 s85, s75, s29
	s_add_u32 s98, s56, 0x80
	s_addc_u32 s99, s57, 0
	s_mov_b32 m0, s85
	ds_read_b128 v[162:165], v210 offset:16384
	ds_read_b128 v[166:169], v210 offset:17408
	ds_read_b128 v[170:173], v210 offset:18432
	ds_read_b128 v[174:177], v210 offset:19456
	ds_read_b128 v[196:199], v210 offset:20480
	ds_read_b128 v[200:203], v210 offset:21504
	ds_read_b128 v[212:215], v210 offset:22528
	ds_read_b128 v[216:219], v210 offset:23552
	global_load_lds_dwordx4 v182, s[56:57]
	s_add_i32 m0, s85, 0x2000
	s_add_u32 s88, s56, 0x160000
	s_addc_u32 s89, s57, 0
	s_add_i32 s85, s76, s29
	global_load_lds_dwordx4 v186, s[56:57]
	s_mov_b32 m0, s85
	s_nop 0
	global_load_lds_dwordx4 v182, s[88:89]
	s_add_i32 m0, s85, 0x2000
	s_nop 0
	global_load_lds_dwordx4 v186, s[88:89]
	s_add_u32 s100, s58, 0x80
	s_addc_u32 s101, s59, 0
	s_mov_b32 m0, s31
	s_nop 0
	global_load_lds_dwordx4 v180, s[58:59]
	s_mov_b32 m0, s64
	s_nop 0
	global_load_lds_dwordx4 v184, s[58:59]
	s_waitcnt vmcnt(8)
	s_waitcnt lgkmcnt(0)
	s_setprio 1
	s_barrier
	v_mfma_f32_16x16x32_bf16 v[62:65], v[130:133], v[162:165], 0
	v_mfma_f32_16x16x32_bf16 v[58:61], v[138:141], v[162:165], 0
	v_mfma_f32_16x16x32_bf16 v[46:49], v[130:133], v[170:173], 0
	v_mfma_f32_16x16x32_bf16 v[42:45], v[138:141], v[170:173], 0
	v_mfma_f32_16x16x32_bf16 v[30:33], v[130:133], v[196:199], 0
	v_mfma_f32_16x16x32_bf16 v[26:29], v[138:141], v[196:199], 0
	v_mfma_f32_16x16x32_bf16 v[14:17], v[130:133], v[212:215], 0
	v_mfma_f32_16x16x32_bf16 v[10:13], v[138:141], v[212:215], 0
	v_mfma_f32_16x16x32_bf16 v[62:65], v[134:137], v[166:169], v[62:65]
	v_mfma_f32_16x16x32_bf16 v[58:61], v[142:145], v[166:169], v[58:61]
	v_mfma_f32_16x16x32_bf16 v[46:49], v[134:137], v[174:177], v[46:49]
	v_mfma_f32_16x16x32_bf16 v[42:45], v[142:145], v[174:177], v[42:45]
	v_mfma_f32_16x16x32_bf16 v[30:33], v[134:137], v[200:203], v[30:33]
	v_mfma_f32_16x16x32_bf16 v[26:29], v[142:145], v[200:203], v[26:29]
	v_mfma_f32_16x16x32_bf16 v[14:17], v[134:137], v[216:219], v[14:17]
	v_mfma_f32_16x16x32_bf16 v[10:13], v[142:145], v[216:219], v[10:13]
	s_setprio 0
	s_setprio 1
	v_mfma_f32_16x16x32_bf16 v[54:57], v[146:149], v[162:165], 0
	v_mfma_f32_16x16x32_bf16 v[50:53], v[154:157], v[162:165], 0
	v_mfma_f32_16x16x32_bf16 v[38:41], v[146:149], v[170:173], 0
	v_mfma_f32_16x16x32_bf16 v[34:37], v[154:157], v[170:173], 0
	v_mfma_f32_16x16x32_bf16 v[22:25], v[146:149], v[196:199], 0
	v_mfma_f32_16x16x32_bf16 v[18:21], v[154:157], v[196:199], 0
	v_mfma_f32_16x16x32_bf16 v[6:9], v[146:149], v[212:215], 0
	v_mfma_f32_16x16x32_bf16 v[2:5], v[154:157], v[212:215], 0
	v_mfma_f32_16x16x32_bf16 v[54:57], v[150:153], v[166:169], v[54:57]
	v_mfma_f32_16x16x32_bf16 v[50:53], v[158:161], v[166:169], v[50:53]
	v_mfma_f32_16x16x32_bf16 v[38:41], v[150:153], v[174:177], v[38:41]
	v_mfma_f32_16x16x32_bf16 v[34:37], v[158:161], v[174:177], v[34:37]
	v_mfma_f32_16x16x32_bf16 v[22:25], v[150:153], v[200:203], v[22:25]
	v_mfma_f32_16x16x32_bf16 v[18:21], v[158:161], v[200:203], v[18:21]
	v_mfma_f32_16x16x32_bf16 v[6:9], v[150:153], v[216:219], v[6:9]
	v_mfma_f32_16x16x32_bf16 v[2:5], v[158:161], v[216:219], v[2:5]
	s_barrier
	s_setprio 0
	s_add_i32 s85, 0, 0x18000
	v_add_u32_e32 v1, s85, v206
	s_add_i32 s87, 0, 0x1c000
	ds_read_b128 v[130:133], v1
	ds_read_b128 v[134:137], v1 offset:1024
	ds_read_b128 v[138:141], v1 offset:2048
	ds_read_b128 v[142:145], v1 offset:3072
	v_add_u32_e32 v1, s87, v206
	ds_read_b128 v[146:149], v1
	ds_read_b128 v[150:153], v1 offset:1024
	ds_read_b128 v[154:157], v1 offset:2048
	ds_read_b128 v[158:161], v1 offset:3072
	s_add_u32 s58, s58, 0x160000
	s_addc_u32 s59, s59, 0
	s_mov_b32 m0, s65
	ds_read_b128 v[162:165], v210 offset:32768
	ds_read_b128 v[166:169], v210 offset:33792
	ds_read_b128 v[170:173], v210 offset:34816
	ds_read_b128 v[174:177], v210 offset:35840
	ds_read_b128 v[196:199], v210 offset:36864
	ds_read_b128 v[200:203], v210 offset:37888
	ds_read_b128 v[212:215], v210 offset:38912
	ds_read_b128 v[216:219], v210 offset:39936
	global_load_lds_dwordx4 v180, s[58:59]
	s_mov_b32 m0, s66
	s_nop 0
	global_load_lds_dwordx4 v184, s[58:59]
	s_waitcnt vmcnt(8)
	s_waitcnt lgkmcnt(0)
	s_setprio 1
	s_barrier
	v_mfma_f32_16x16x32_bf16 v[126:129], v[130:133], v[162:165], v[126:129]
	v_mfma_f32_16x16x32_bf16 v[122:125], v[138:141], v[162:165], v[122:125]
	v_mfma_f32_16x16x32_bf16 v[110:113], v[130:133], v[170:173], v[110:113]
	v_mfma_f32_16x16x32_bf16 v[106:109], v[138:141], v[170:173], v[106:109]
	v_mfma_f32_16x16x32_bf16 v[94:97], v[130:133], v[196:199], v[94:97]
	v_mfma_f32_16x16x32_bf16 v[90:93], v[138:141], v[196:199], v[90:93]
	v_mfma_f32_16x16x32_bf16 v[78:81], v[130:133], v[212:215], v[78:81]
	v_mfma_f32_16x16x32_bf16 v[74:77], v[138:141], v[212:215], v[74:77]
	v_mfma_f32_16x16x32_bf16 v[126:129], v[134:137], v[166:169], v[126:129]
	v_mfma_f32_16x16x32_bf16 v[122:125], v[142:145], v[166:169], v[122:125]
	v_mfma_f32_16x16x32_bf16 v[110:113], v[134:137], v[174:177], v[110:113]
	v_mfma_f32_16x16x32_bf16 v[106:109], v[142:145], v[174:177], v[106:109]
	v_mfma_f32_16x16x32_bf16 v[94:97], v[134:137], v[200:203], v[94:97]
	v_mfma_f32_16x16x32_bf16 v[90:93], v[142:145], v[200:203], v[90:93]
	v_mfma_f32_16x16x32_bf16 v[78:81], v[134:137], v[216:219], v[78:81]
	v_mfma_f32_16x16x32_bf16 v[74:77], v[142:145], v[216:219], v[74:77]
	s_setprio 0
	s_setprio 1
	v_mfma_f32_16x16x32_bf16 v[118:121], v[146:149], v[162:165], v[118:121]
	v_mfma_f32_16x16x32_bf16 v[114:117], v[154:157], v[162:165], v[114:117]
	v_mfma_f32_16x16x32_bf16 v[102:105], v[146:149], v[170:173], v[102:105]
	v_mfma_f32_16x16x32_bf16 v[98:101], v[154:157], v[170:173], v[98:101]
	v_mfma_f32_16x16x32_bf16 v[86:89], v[146:149], v[196:199], v[86:89]
	v_mfma_f32_16x16x32_bf16 v[82:85], v[154:157], v[196:199], v[82:85]
	v_mfma_f32_16x16x32_bf16 v[70:73], v[146:149], v[212:215], v[70:73]
	v_mfma_f32_16x16x32_bf16 v[66:69], v[154:157], v[212:215], v[66:69]
	v_mfma_f32_16x16x32_bf16 v[118:121], v[150:153], v[166:169], v[118:121]
	v_mfma_f32_16x16x32_bf16 v[114:117], v[158:161], v[166:169], v[114:117]
	v_mfma_f32_16x16x32_bf16 v[102:105], v[150:153], v[174:177], v[102:105]
	v_mfma_f32_16x16x32_bf16 v[98:101], v[158:161], v[174:177], v[98:101]
	v_mfma_f32_16x16x32_bf16 v[86:89], v[150:153], v[200:203], v[86:89]
	v_mfma_f32_16x16x32_bf16 v[82:85], v[158:161], v[200:203], v[82:85]
	v_mfma_f32_16x16x32_bf16 v[70:73], v[150:153], v[216:219], v[70:73]
	v_mfma_f32_16x16x32_bf16 v[66:69], v[158:161], v[216:219], v[66:69]
	s_barrier
	s_setprio 0
	s_add_i32 s58, s85, s29
	s_mov_b32 m0, s58
	ds_read_b128 v[162:165], v210 offset:49152
	ds_read_b128 v[166:169], v210 offset:50176
	ds_read_b128 v[170:173], v210 offset:51200
	ds_read_b128 v[174:177], v210 offset:52224
	ds_read_b128 v[196:199], v210 offset:53248
	ds_read_b128 v[200:203], v210 offset:54272
	ds_read_b128 v[212:215], v210 offset:55296
	ds_read_b128 v[216:219], v210 offset:56320
	global_load_lds_dwordx4 v182, s[98:99]
	s_add_i32 m0, s58, 0x2000
	s_add_u32 s56, s56, 0x160080
	s_addc_u32 s57, s57, 0
	s_add_i32 s58, s87, s29
	global_load_lds_dwordx4 v186, s[98:99]
	s_mov_b32 m0, s58
	s_nop 0
	global_load_lds_dwordx4 v182, s[56:57]
	s_add_i32 m0, s58, 0x2000
	s_nop 0
	global_load_lds_dwordx4 v186, s[56:57]
	s_mov_b32 m0, s71
	s_nop 0
	global_load_lds_dwordx4 v180, s[100:101]
	s_mov_b32 m0, s72
	s_nop 0
	global_load_lds_dwordx4 v184, s[100:101]
	s_waitcnt vmcnt(8)
	s_waitcnt lgkmcnt(0)
	s_setprio 1
	s_barrier
	v_mfma_f32_16x16x32_bf16 v[62:65], v[130:133], v[162:165], v[62:65]
	v_mfma_f32_16x16x32_bf16 v[58:61], v[138:141], v[162:165], v[58:61]
	v_mfma_f32_16x16x32_bf16 v[46:49], v[130:133], v[170:173], v[46:49]
	v_mfma_f32_16x16x32_bf16 v[42:45], v[138:141], v[170:173], v[42:45]
	v_mfma_f32_16x16x32_bf16 v[30:33], v[130:133], v[196:199], v[30:33]
	v_mfma_f32_16x16x32_bf16 v[26:29], v[138:141], v[196:199], v[26:29]
	v_mfma_f32_16x16x32_bf16 v[14:17], v[130:133], v[212:215], v[14:17]
	v_mfma_f32_16x16x32_bf16 v[10:13], v[138:141], v[212:215], v[10:13]
	v_mfma_f32_16x16x32_bf16 v[62:65], v[134:137], v[166:169], v[62:65]
	v_mfma_f32_16x16x32_bf16 v[58:61], v[142:145], v[166:169], v[58:61]
	v_mfma_f32_16x16x32_bf16 v[46:49], v[134:137], v[174:177], v[46:49]
	v_mfma_f32_16x16x32_bf16 v[42:45], v[142:145], v[174:177], v[42:45]
	v_mfma_f32_16x16x32_bf16 v[30:33], v[134:137], v[200:203], v[30:33]
	v_mfma_f32_16x16x32_bf16 v[26:29], v[142:145], v[200:203], v[26:29]
	v_mfma_f32_16x16x32_bf16 v[14:17], v[134:137], v[216:219], v[14:17]
	v_mfma_f32_16x16x32_bf16 v[10:13], v[142:145], v[216:219], v[10:13]
	s_setprio 0
	s_setprio 1
	v_mfma_f32_16x16x32_bf16 v[54:57], v[146:149], v[162:165], v[54:57]
	v_mfma_f32_16x16x32_bf16 v[50:53], v[154:157], v[162:165], v[50:53]
	v_mfma_f32_16x16x32_bf16 v[38:41], v[146:149], v[170:173], v[38:41]
	v_mfma_f32_16x16x32_bf16 v[34:37], v[154:157], v[170:173], v[34:37]
	v_mfma_f32_16x16x32_bf16 v[22:25], v[146:149], v[196:199], v[22:25]
	v_mfma_f32_16x16x32_bf16 v[18:21], v[154:157], v[196:199], v[18:21]
	v_mfma_f32_16x16x32_bf16 v[6:9], v[146:149], v[212:215], v[6:9]
	v_mfma_f32_16x16x32_bf16 v[2:5], v[154:157], v[212:215], v[2:5]
	v_mfma_f32_16x16x32_bf16 v[54:57], v[150:153], v[166:169], v[54:57]
	v_mfma_f32_16x16x32_bf16 v[50:53], v[158:161], v[166:169], v[50:53]
	v_mfma_f32_16x16x32_bf16 v[38:41], v[150:153], v[174:177], v[38:41]
	v_mfma_f32_16x16x32_bf16 v[34:37], v[158:161], v[174:177], v[34:37]
	v_mfma_f32_16x16x32_bf16 v[22:25], v[150:153], v[200:203], v[22:25]
	v_mfma_f32_16x16x32_bf16 v[18:21], v[158:161], v[200:203], v[18:21]
	v_mfma_f32_16x16x32_bf16 v[6:9], v[150:153], v[216:219], v[6:9]
	v_mfma_f32_16x16x32_bf16 v[2:5], v[158:161], v[216:219], v[2:5]
	s_barrier
	s_setprio 0
	s_add_i32 s83, s83, 2
	s_add_u32 s12, s12, 0x100
	s_addc_u32 s13, s13, 0
	s_add_u32 s81, s81, 0x100
	s_addc_u32 s82, s82, 0
	s_cmpk_gt_u32 s83, 0x55
.LBB0_379:
	ds_read_b128 v[130:133], v208
	ds_read_b128 v[134:137], v208 offset:1024
	ds_read_b128 v[138:141], v208 offset:2048
	ds_read_b128 v[142:145], v208 offset:3072
	ds_read_b128 v[146:149], v209
	ds_read_b128 v[150:153], v209 offset:1024
	ds_read_b128 v[154:157], v209 offset:2048
	ds_read_b128 v[158:161], v209 offset:3072
	s_add_u32 s56, s12, 0xffea0080
	s_addc_u32 s57, s13, -1
	s_cmpk_eq_i32 s83, 0x54
	s_cselect_b32 s59, s43, s57
	s_cselect_b32 s58, s42, s56
	s_cselect_b32 s57, s55, s82
	s_cselect_b32 s56, s54, s81
	s_add_i32 m0, s31, 0xc000
	ds_read_b128 v[162:165], v210
	ds_read_b128 v[166:169], v210 offset:1024
	ds_read_b128 v[170:173], v210 offset:2048
	ds_read_b128 v[174:177], v210 offset:3072
	ds_read_b128 v[196:199], v210 offset:4096
	ds_read_b128 v[200:203], v210 offset:5120
	ds_read_b128 v[212:215], v210 offset:6144
	ds_read_b128 v[216:219], v210 offset:7168
	global_load_lds_dwordx4 v188, s[12:13]
	s_add_i32 m0, s31, 0xe000
	s_nop 0
	global_load_lds_dwordx4 v190, s[12:13]
	s_waitcnt vmcnt(8)
	s_waitcnt lgkmcnt(0)
	s_setprio 1
	s_barrier
	v_mfma_f32_16x16x32_bf16 v[126:129], v[130:133], v[162:165], v[126:129]
	v_mfma_f32_16x16x32_bf16 v[122:125], v[138:141], v[162:165], v[122:125]
	v_mfma_f32_16x16x32_bf16 v[110:113], v[130:133], v[170:173], v[110:113]
	v_mfma_f32_16x16x32_bf16 v[106:109], v[138:141], v[170:173], v[106:109]
	v_mfma_f32_16x16x32_bf16 v[94:97], v[130:133], v[196:199], v[94:97]
	v_mfma_f32_16x16x32_bf16 v[90:93], v[138:141], v[196:199], v[90:93]
	v_mfma_f32_16x16x32_bf16 v[78:81], v[130:133], v[212:215], v[78:81]
	v_mfma_f32_16x16x32_bf16 v[74:77], v[138:141], v[212:215], v[74:77]
	v_mfma_f32_16x16x32_bf16 v[126:129], v[134:137], v[166:169], v[126:129]
	v_mfma_f32_16x16x32_bf16 v[122:125], v[142:145], v[166:169], v[122:125]
	v_mfma_f32_16x16x32_bf16 v[110:113], v[134:137], v[174:177], v[110:113]
	v_mfma_f32_16x16x32_bf16 v[106:109], v[142:145], v[174:177], v[106:109]
	v_mfma_f32_16x16x32_bf16 v[94:97], v[134:137], v[200:203], v[94:97]
	v_mfma_f32_16x16x32_bf16 v[90:93], v[142:145], v[200:203], v[90:93]
	v_mfma_f32_16x16x32_bf16 v[78:81], v[134:137], v[216:219], v[78:81]
	v_mfma_f32_16x16x32_bf16 v[74:77], v[142:145], v[216:219], v[74:77]
	s_setprio 0
	s_setprio 1
	v_mfma_f32_16x16x32_bf16 v[118:121], v[146:149], v[162:165], v[118:121]
	v_mfma_f32_16x16x32_bf16 v[114:117], v[154:157], v[162:165], v[114:117]
	v_mfma_f32_16x16x32_bf16 v[102:105], v[146:149], v[170:173], v[102:105]
	v_mfma_f32_16x16x32_bf16 v[98:101], v[154:157], v[170:173], v[98:101]
	v_mfma_f32_16x16x32_bf16 v[86:89], v[146:149], v[196:199], v[86:89]
	v_mfma_f32_16x16x32_bf16 v[82:85], v[154:157], v[196:199], v[82:85]
	v_mfma_f32_16x16x32_bf16 v[70:73], v[146:149], v[212:215], v[70:73]
	v_mfma_f32_16x16x32_bf16 v[66:69], v[154:157], v[212:215], v[66:69]
	v_mfma_f32_16x16x32_bf16 v[118:121], v[150:153], v[166:169], v[118:121]
	v_mfma_f32_16x16x32_bf16 v[114:117], v[158:161], v[166:169], v[114:117]
	v_mfma_f32_16x16x32_bf16 v[102:105], v[150:153], v[174:177], v[102:105]
	v_mfma_f32_16x16x32_bf16 v[98:101], v[158:161], v[174:177], v[98:101]
	v_mfma_f32_16x16x32_bf16 v[86:89], v[150:153], v[200:203], v[86:89]
	v_mfma_f32_16x16x32_bf16 v[82:85], v[158:161], v[200:203], v[82:85]
	v_mfma_f32_16x16x32_bf16 v[70:73], v[150:153], v[216:219], v[70:73]
	v_mfma_f32_16x16x32_bf16 v[66:69], v[158:161], v[216:219], v[66:69]
	s_barrier
	s_setprio 0
	s_add_i32 s85, s75, s29
	s_add_u32 s98, s56, 0x80
	s_addc_u32 s99, s57, 0
	s_mov_b32 m0, s85
	ds_read_b128 v[162:165], v210 offset:16384
	ds_read_b128 v[166:169], v210 offset:17408
	ds_read_b128 v[170:173], v210 offset:18432
	ds_read_b128 v[174:177], v210 offset:19456
	ds_read_b128 v[196:199], v210 offset:20480
	ds_read_b128 v[200:203], v210 offset:21504
	ds_read_b128 v[212:215], v210 offset:22528
	ds_read_b128 v[216:219], v210 offset:23552
	global_load_lds_dwordx4 v182, s[56:57]
	s_add_i32 m0, s85, 0x2000
	s_add_u32 s88, s56, 0x160000
	s_addc_u32 s89, s57, 0
	s_add_i32 s85, s76, s29
	global_load_lds_dwordx4 v186, s[56:57]
	s_mov_b32 m0, s85
	s_nop 0
	global_load_lds_dwordx4 v182, s[88:89]
	s_add_i32 m0, s85, 0x2000
	s_nop 0
	global_load_lds_dwordx4 v186, s[88:89]
	s_add_u32 s100, s58, 0x80
	s_addc_u32 s101, s59, 0
	s_mov_b32 m0, s31
	s_nop 0
	global_load_lds_dwordx4 v180, s[58:59]
	s_mov_b32 m0, s64
	s_nop 0
	global_load_lds_dwordx4 v184, s[58:59]
	s_waitcnt vmcnt(8)
	s_waitcnt lgkmcnt(0)
	s_setprio 1
	s_barrier
	v_mfma_f32_16x16x32_bf16 v[62:65], v[130:133], v[162:165], v[62:65]
	v_mfma_f32_16x16x32_bf16 v[58:61], v[138:141], v[162:165], v[58:61]
	v_mfma_f32_16x16x32_bf16 v[46:49], v[130:133], v[170:173], v[46:49]
	v_mfma_f32_16x16x32_bf16 v[42:45], v[138:141], v[170:173], v[42:45]
	v_mfma_f32_16x16x32_bf16 v[30:33], v[130:133], v[196:199], v[30:33]
	v_mfma_f32_16x16x32_bf16 v[26:29], v[138:141], v[196:199], v[26:29]
	v_mfma_f32_16x16x32_bf16 v[14:17], v[130:133], v[212:215], v[14:17]
	v_mfma_f32_16x16x32_bf16 v[10:13], v[138:141], v[212:215], v[10:13]
	v_mfma_f32_16x16x32_bf16 v[62:65], v[134:137], v[166:169], v[62:65]
	v_mfma_f32_16x16x32_bf16 v[58:61], v[142:145], v[166:169], v[58:61]
	v_mfma_f32_16x16x32_bf16 v[46:49], v[134:137], v[174:177], v[46:49]
	v_mfma_f32_16x16x32_bf16 v[42:45], v[142:145], v[174:177], v[42:45]
	v_mfma_f32_16x16x32_bf16 v[30:33], v[134:137], v[200:203], v[30:33]
	v_mfma_f32_16x16x32_bf16 v[26:29], v[142:145], v[200:203], v[26:29]
	v_mfma_f32_16x16x32_bf16 v[14:17], v[134:137], v[216:219], v[14:17]
	v_mfma_f32_16x16x32_bf16 v[10:13], v[142:145], v[216:219], v[10:13]
	s_setprio 0
	s_setprio 1
	v_mfma_f32_16x16x32_bf16 v[54:57], v[146:149], v[162:165], v[54:57]
	v_mfma_f32_16x16x32_bf16 v[50:53], v[154:157], v[162:165], v[50:53]
	v_mfma_f32_16x16x32_bf16 v[38:41], v[146:149], v[170:173], v[38:41]
	v_mfma_f32_16x16x32_bf16 v[34:37], v[154:157], v[170:173], v[34:37]
	v_mfma_f32_16x16x32_bf16 v[22:25], v[146:149], v[196:199], v[22:25]
	v_mfma_f32_16x16x32_bf16 v[18:21], v[154:157], v[196:199], v[18:21]
	v_mfma_f32_16x16x32_bf16 v[6:9], v[146:149], v[212:215], v[6:9]
	v_mfma_f32_16x16x32_bf16 v[2:5], v[154:157], v[212:215], v[2:5]
	v_mfma_f32_16x16x32_bf16 v[54:57], v[150:153], v[166:169], v[54:57]
	v_mfma_f32_16x16x32_bf16 v[50:53], v[158:161], v[166:169], v[50:53]
	v_mfma_f32_16x16x32_bf16 v[38:41], v[150:153], v[174:177], v[38:41]
	v_mfma_f32_16x16x32_bf16 v[34:37], v[158:161], v[174:177], v[34:37]
	v_mfma_f32_16x16x32_bf16 v[22:25], v[150:153], v[200:203], v[22:25]
	v_mfma_f32_16x16x32_bf16 v[18:21], v[158:161], v[200:203], v[18:21]
	v_mfma_f32_16x16x32_bf16 v[6:9], v[150:153], v[216:219], v[6:9]
	v_mfma_f32_16x16x32_bf16 v[2:5], v[158:161], v[216:219], v[2:5]
	s_barrier
	s_setprio 0
	s_add_i32 s85, 0, 0x18000
	v_add_u32_e32 v1, s85, v206
	s_add_i32 s87, 0, 0x1c000
	ds_read_b128 v[130:133], v1
	ds_read_b128 v[134:137], v1 offset:1024
	ds_read_b128 v[138:141], v1 offset:2048
	ds_read_b128 v[142:145], v1 offset:3072
	v_add_u32_e32 v1, s87, v206
	ds_read_b128 v[146:149], v1
	ds_read_b128 v[150:153], v1 offset:1024
	ds_read_b128 v[154:157], v1 offset:2048
	ds_read_b128 v[158:161], v1 offset:3072
	s_add_u32 s58, s58, 0x160000
	s_addc_u32 s59, s59, 0
	s_mov_b32 m0, s65
	ds_read_b128 v[162:165], v210 offset:32768
	ds_read_b128 v[166:169], v210 offset:33792
	ds_read_b128 v[170:173], v210 offset:34816
	ds_read_b128 v[174:177], v210 offset:35840
	ds_read_b128 v[196:199], v210 offset:36864
	ds_read_b128 v[200:203], v210 offset:37888
	ds_read_b128 v[212:215], v210 offset:38912
	ds_read_b128 v[216:219], v210 offset:39936
	global_load_lds_dwordx4 v180, s[58:59]
	v_lshl_add_u64 v[226:227], s[58:59], 0, v[184:185]
	s_mov_b32 m0, s66
	s_nop 0
	global_load_lds_dwordx4 v[226:227], off
	s_waitcnt vmcnt(8)
	s_waitcnt lgkmcnt(0)
	s_setprio 1
	s_barrier
	v_mfma_f32_16x16x32_bf16 v[126:129], v[130:133], v[162:165], v[126:129]
	v_mfma_f32_16x16x32_bf16 v[122:125], v[138:141], v[162:165], v[122:125]
	v_mfma_f32_16x16x32_bf16 v[110:113], v[130:133], v[170:173], v[110:113]
	v_mfma_f32_16x16x32_bf16 v[106:109], v[138:141], v[170:173], v[106:109]
	v_mfma_f32_16x16x32_bf16 v[94:97], v[130:133], v[196:199], v[94:97]
	v_mfma_f32_16x16x32_bf16 v[90:93], v[138:141], v[196:199], v[90:93]
	v_mfma_f32_16x16x32_bf16 v[78:81], v[130:133], v[212:215], v[78:81]
	v_mfma_f32_16x16x32_bf16 v[74:77], v[138:141], v[212:215], v[74:77]
	v_mfma_f32_16x16x32_bf16 v[126:129], v[134:137], v[166:169], v[126:129]
	v_mfma_f32_16x16x32_bf16 v[122:125], v[142:145], v[166:169], v[122:125]
	v_mfma_f32_16x16x32_bf16 v[110:113], v[134:137], v[174:177], v[110:113]
	v_mfma_f32_16x16x32_bf16 v[106:109], v[142:145], v[174:177], v[106:109]
	v_mfma_f32_16x16x32_bf16 v[94:97], v[134:137], v[200:203], v[94:97]
	v_mfma_f32_16x16x32_bf16 v[90:93], v[142:145], v[200:203], v[90:93]
	v_mfma_f32_16x16x32_bf16 v[78:81], v[134:137], v[216:219], v[78:81]
	v_mfma_f32_16x16x32_bf16 v[74:77], v[142:145], v[216:219], v[74:77]
	s_setprio 0
	s_setprio 1
	v_mfma_f32_16x16x32_bf16 v[118:121], v[146:149], v[162:165], v[118:121]
	v_mfma_f32_16x16x32_bf16 v[114:117], v[154:157], v[162:165], v[114:117]
	v_mfma_f32_16x16x32_bf16 v[102:105], v[146:149], v[170:173], v[102:105]
	v_mfma_f32_16x16x32_bf16 v[98:101], v[154:157], v[170:173], v[98:101]
	v_mfma_f32_16x16x32_bf16 v[86:89], v[146:149], v[196:199], v[86:89]
	v_mfma_f32_16x16x32_bf16 v[82:85], v[154:157], v[196:199], v[82:85]
	v_mfma_f32_16x16x32_bf16 v[70:73], v[146:149], v[212:215], v[70:73]
	v_mfma_f32_16x16x32_bf16 v[66:69], v[154:157], v[212:215], v[66:69]
	v_mfma_f32_16x16x32_bf16 v[118:121], v[150:153], v[166:169], v[118:121]
	v_mfma_f32_16x16x32_bf16 v[114:117], v[158:161], v[166:169], v[114:117]
	v_mfma_f32_16x16x32_bf16 v[102:105], v[150:153], v[174:177], v[102:105]
	v_mfma_f32_16x16x32_bf16 v[98:101], v[158:161], v[174:177], v[98:101]
	v_mfma_f32_16x16x32_bf16 v[86:89], v[150:153], v[200:203], v[86:89]
	v_mfma_f32_16x16x32_bf16 v[82:85], v[158:161], v[200:203], v[82:85]
	v_mfma_f32_16x16x32_bf16 v[70:73], v[150:153], v[216:219], v[70:73]
	v_mfma_f32_16x16x32_bf16 v[66:69], v[158:161], v[216:219], v[66:69]
	s_barrier
	s_setprio 0
	s_add_i32 s58, s85, s29
	s_mov_b32 m0, s58
	ds_read_b128 v[162:165], v210 offset:49152
	ds_read_b128 v[166:169], v210 offset:50176
	ds_read_b128 v[170:173], v210 offset:51200
	ds_read_b128 v[174:177], v210 offset:52224
	ds_read_b128 v[196:199], v210 offset:53248
	ds_read_b128 v[200:203], v210 offset:54272
	ds_read_b128 v[212:215], v210 offset:55296
	ds_read_b128 v[216:219], v210 offset:56320
	global_load_lds_dwordx4 v182, s[98:99]
	s_add_i32 m0, s58, 0x2000
	s_add_u32 s56, s56, 0x160080
	s_addc_u32 s57, s57, 0
	s_add_i32 s58, s87, s29
	global_load_lds_dwordx4 v186, s[98:99]
	s_mov_b32 m0, s58
	s_nop 0
	global_load_lds_dwordx4 v182, s[56:57]
	s_add_i32 m0, s58, 0x2000
	s_nop 0
	global_load_lds_dwordx4 v186, s[56:57]
	s_mov_b32 m0, s71
	s_nop 0
	global_load_lds_dwordx4 v180, s[100:101]
	s_mov_b32 m0, s72
	s_nop 0
	global_load_lds_dwordx4 v184, s[100:101]
	s_add_i32 s83, s83, 2
	s_add_u32 s12, s12, 0x100
	s_addc_u32 s13, s13, 0
	s_add_u32 s81, s81, 0x100
	s_addc_u32 s82, s82, 0
	s_cmpk_gt_u32 s83, 0x55
	s_waitcnt vmcnt(8)
	s_waitcnt lgkmcnt(0)
	s_setprio 1
	s_barrier
	v_mfma_f32_16x16x32_bf16 v[62:65], v[130:133], v[162:165], v[62:65]
	v_mfma_f32_16x16x32_bf16 v[58:61], v[138:141], v[162:165], v[58:61]
	v_mfma_f32_16x16x32_bf16 v[46:49], v[130:133], v[170:173], v[46:49]
	v_mfma_f32_16x16x32_bf16 v[42:45], v[138:141], v[170:173], v[42:45]
	v_mfma_f32_16x16x32_bf16 v[30:33], v[130:133], v[196:199], v[30:33]
	v_mfma_f32_16x16x32_bf16 v[26:29], v[138:141], v[196:199], v[26:29]
	v_mfma_f32_16x16x32_bf16 v[14:17], v[130:133], v[212:215], v[14:17]
	v_mfma_f32_16x16x32_bf16 v[10:13], v[138:141], v[212:215], v[10:13]
	v_mfma_f32_16x16x32_bf16 v[62:65], v[134:137], v[166:169], v[62:65]
	v_mfma_f32_16x16x32_bf16 v[58:61], v[142:145], v[166:169], v[58:61]
	v_mfma_f32_16x16x32_bf16 v[46:49], v[134:137], v[174:177], v[46:49]
	v_mfma_f32_16x16x32_bf16 v[42:45], v[142:145], v[174:177], v[42:45]
	v_mfma_f32_16x16x32_bf16 v[30:33], v[134:137], v[200:203], v[30:33]
	v_mfma_f32_16x16x32_bf16 v[26:29], v[142:145], v[200:203], v[26:29]
	v_mfma_f32_16x16x32_bf16 v[14:17], v[134:137], v[216:219], v[14:17]
	v_mfma_f32_16x16x32_bf16 v[10:13], v[142:145], v[216:219], v[10:13]
	s_setprio 0
	s_setprio 1
	v_mfma_f32_16x16x32_bf16 v[54:57], v[146:149], v[162:165], v[54:57]
	v_mfma_f32_16x16x32_bf16 v[50:53], v[154:157], v[162:165], v[50:53]
	v_mfma_f32_16x16x32_bf16 v[38:41], v[146:149], v[170:173], v[38:41]
	v_mfma_f32_16x16x32_bf16 v[34:37], v[154:157], v[170:173], v[34:37]
	v_mfma_f32_16x16x32_bf16 v[22:25], v[146:149], v[196:199], v[22:25]
	v_mfma_f32_16x16x32_bf16 v[18:21], v[154:157], v[196:199], v[18:21]
	v_mfma_f32_16x16x32_bf16 v[6:9], v[146:149], v[212:215], v[6:9]
	v_mfma_f32_16x16x32_bf16 v[2:5], v[154:157], v[212:215], v[2:5]
	v_mfma_f32_16x16x32_bf16 v[54:57], v[150:153], v[166:169], v[54:57]
	v_mfma_f32_16x16x32_bf16 v[50:53], v[158:161], v[166:169], v[50:53]
	v_mfma_f32_16x16x32_bf16 v[38:41], v[150:153], v[174:177], v[38:41]
	v_mfma_f32_16x16x32_bf16 v[34:37], v[158:161], v[174:177], v[34:37]
	v_mfma_f32_16x16x32_bf16 v[22:25], v[150:153], v[200:203], v[22:25]
	v_mfma_f32_16x16x32_bf16 v[18:21], v[158:161], v[200:203], v[18:21]
	v_mfma_f32_16x16x32_bf16 v[6:9], v[150:153], v[216:219], v[6:9]
	v_mfma_f32_16x16x32_bf16 v[2:5], v[158:161], v[216:219], v[2:5]
	s_barrier
	s_setprio 0
	s_cbranch_scc0 .LBB0_379
	s_and_b64 vcc, exec, s[34:35]
	s_cbranch_vccz .LBB0_382
	s_barrier

.LBB0_463:
	s_add_u32 s14, s26, 0x11c00000
	s_addc_u32 s15, s27, 0
	s_add_u32 s16, s26, 0x15c00000
	s_addc_u32 s17, s27, 0
	s_add_u32 s34, s26, 0x19c00000
	s_addc_u32 s35, s27, 0
	s_add_u32 s40, s26, 0x1dc00000
	s_addc_u32 s41, s27, 0
	s_add_u32 s18, s26, 0x21c00000
	s_addc_u32 s19, s27, 0
	v_writelane_b32 v255, s18, 7
	s_mov_b64 s[56:57], 0x80
	v_lshl_add_u64 v[8:9], v[8:9], 0, s[56:57]
	v_writelane_b32 v255, s19, 8
	s_add_u32 s18, s26, 0x23c00000
	s_addc_u32 s19, s27, 0
	v_writelane_b32 v255, s18, 9
	s_and_b32 s7, s4, 3
	s_add_i32 m0, s94, 0x18000
	v_writelane_b32 v255, s19, 10
	v_lshl_or_b32 v192, s3, 6, v189
	s_lshl_b32 s3, s3, 13
	s_lshl_b32 s23, s7, 5
	s_lshl_b32 s11, s7, 12
	s_waitcnt vmcnt(2)
	s_barrier
	global_load_lds_dwordx4 v[8:9], off
	v_lshl_add_u64 v[6:7], v[6:7], 0, s[56:57]
	s_add_i32 m0, s94, 0x1a000
	s_add_i32 s85, s94, 0x8000
	s_add_i32 s18, s94, 0xa000
	global_load_lds_dwordx4 v[6:7], off
	v_lshl_add_u64 v[2:3], v[2:3], 0, s[56:57]
	s_mov_b32 m0, s85
	s_add_u32 s4, s8, 0x80080
	global_load_lds_dwordx4 v[2:3], off
	v_lshl_add_u64 v[2:3], v[4:5], 0, s[56:57]
	s_mov_b32 m0, s18
	s_addc_u32 s5, s9, 0
	global_load_lds_dwordx4 v[2:3], off
	s_add_i32 m0, s94, 0x1c000
	s_nop 0
	global_load_lds_dwordx4 v152, s[4:5]
	v_lshl_add_u64 v[2:3], s[4:5], 0, v[156:157]
	s_add_i32 m0, s94, 0x1e000
	v_lshrrev_b32_e32 v1, 4, v0
	global_load_lds_dwordx4 v[2:3], off
	s_cmpk_lt_u32 s2, 0x100
	v_and_b32_e32 v1, 3, v1
	s_cselect_b64 s[58:59], -1, 0
	s_and_b32 s19, s23, 32
	v_lshlrev_b32_e32 v2, 4, v1
	v_lshlrev_b32_e32 v4, 2, v189
	s_cmp_gt_u32 s7, 1
	v_lshl_or_b32 v3, v189, 6, v2
	v_and_b32_e32 v4, 32, v4
	v_or_b32_e32 v2, v2, v254
	s_cselect_b64 s[64:65], -1, 0
	s_cmp_eq_u32 s7, 0
	v_bitop3_b32 v6, v3, s3, v4 bitop3:0xde
	v_bitop3_b32 v194, s11, v2, v179 bitop3:0xf6
	s_cselect_b64 s[4:5], -1, 0
	v_cmp_gt_u32_e32 vcc, 2, v1
	v_lshlrev_b32_e32 v2, 5, v1
	v_mov_b32_e32 v3, v153
	s_and_b64 s[66:67], s[4:5], vcc
	v_lshl_add_u64 v[4:5], s[26:27], 0, v[2:3]
	s_mov_b64 s[4:5], 0x11800000
	v_lshlrev_b32_e32 v7, 5, v192
	v_lshl_add_u64 v[158:159], v[4:5], 0, s[4:5]
	s_add_i32 s4, 0, 0x20000
	v_add_u32_e32 v195, s4, v7
	s_lshl_b32 s4, s7, 2
	v_lshlrev_b32_e32 v193, 3, v1
	v_cmp_eq_u32_e64 s[2:3], 0, v1
	v_add_u32_e32 v196, s4, v195
	s_add_i32 s4, s4, 0
	v_lshlrev_b32_e32 v1, 9, v0
	s_add_i32 s5, s4, 0x20200
	v_lshl_add_u64 v[160:161], s[52:53], 0, v[2:3]
	v_and_b32_e32 v1, 0x30000, v1
	v_lshlrev_b32_e32 v2, 12, v186
	v_add_u32_e32 v197, s5, v7
	s_add_i32 s5, s4, 0x20400
	v_or3_b32 v1, v184, v1, v2
	v_add_u32_e32 v198, s5, v7
	s_add_i32 s5, s4, 0x20600
	v_add_u32_e32 v162, v1, v185
	v_lshlrev_b32_e32 v1, 5, v188
	v_add_u32_e32 v199, s5, v7
	s_add_i32 s5, s4, 0x21000
	v_and_b32_e32 v1, 0x70000, v1
	s_waitcnt vmcnt(6)
	v_add_u32_e32 v200, s5, v7
	s_add_i32 s5, s4, 0x21200
	v_or3_b32 v1, v184, v1, v2
	v_mov_b32_e32 v166, 1.0
	v_add_u32_e32 v201, s5, v7
	s_add_i32 s5, s4, 0x21400
	s_add_i32 s4, s4, 0x21600
	v_add_u32_e32 v164, v1, v185
	v_mov_b32_e32 v167, v166
	s_add_i32 s53, 0, 0x10000
	s_add_i32 s54, 0, 0x14000
	v_mbcnt_lo_u32_b32 v1, -1, 0
	s_ashr_i32 s42, s33, 31
	s_ashr_i32 s43, s88, 31
	v_add_u32_e32 v202, s5, v7
	v_add_u32_e32 v203, s4, v7
	v_mov_b32_e32 v163, v153
	v_mov_b32_e32 v165, v153
	s_mov_b32 s7, -1
	v_add_u32_e32 v204, s53, v194
	v_add_u32_e32 v205, s54, v194
	v_add_u32_e32 v206, 0, v6
	v_mov_b32_e32 v207, 0x358637bd
	s_mov_b32 s55, 0xf800000
	v_mov_b32_e32 v208, 0x260
	s_mov_b32 s28, 0xbfb8aa3b
	s_mov_b32 s52, 0x3f317218
	v_mbcnt_hi_u32_b32 v209, -1, v1
	v_mov_b64_e32 v[168:169], v[166:167]
	v_mov_b32_e32 v50, v166
	v_mov_b32_e32 v51, v166
	v_mov_b32_e32 v52, v166
	v_mov_b32_e32 v53, v166
	s_barrier
	s_branch .LBB0_466

.LBB0_468:
	s_ashr_i32 s11, s10, 31
	s_lshl_b64 s[70:71], s[10:11], 20
	s_add_u32 s70, s89, s70
	s_addc_u32 s71, s90, s71
	s_and_b64 s[72:73], s[4:5], exec
	s_cselect_b32 s11, s71, s1
	s_cselect_b32 s76, s70, s0
	s_ashr_i32 s69, s68, 31
	s_lshl_b64 s[72:73], s[68:69], 20
	s_add_u32 s72, s91, s72
	s_addc_u32 s73, s92, s73
	s_and_b64 s[74:75], s[4:5], exec
	s_cselect_b32 s69, s73, s9
	s_cselect_b32 s77, s72, s8
	s_add_u32 s0, s0, 0x80080
	s_addc_u32 s1, s1, 0
	s_add_u32 s78, s8, 0x100
	s_addc_u32 s79, s9, 0
	s_mov_b32 s80, -2
	ds_read_b128 v[78:81], v204
	ds_read_b128 v[138:141], v204 offset:1024
	ds_read_b128 v[142:145], v204 offset:2048
	ds_read_b128 v[146:149], v204 offset:3072
	ds_read_b128 v[170:173], v205
	ds_read_b128 v[174:177], v205 offset:1024
	ds_read_b128 v[180:183], v205 offset:2048
	ds_read_b128 v[210:213], v205 offset:3072
	s_add_u32 s8, s0, 0xfff80080
	s_addc_u32 s9, s1, -1
	s_cmp_eq_u32 s80, 28
	s_cselect_b32 s75, s11, s9
	s_cselect_b32 s74, s76, s8
	s_cselect_b32 s9, s69, s79
	s_cselect_b32 s8, s77, s78
	s_add_i32 m0, s94, 0xc000
	ds_read_b128 v[214:217], v206
	ds_read_b128 v[218:221], v206 offset:1024
	ds_read_b128 v[222:225], v206 offset:2048
	ds_read_b128 v[226:229], v206 offset:3072
	ds_read_b128 v[230:233], v206 offset:4096
	ds_read_b128 v[234:237], v206 offset:5120
	ds_read_b128 v[238:241], v206 offset:6144
	ds_read_b128 v[242:245], v206 offset:7168
	global_load_lds_dwordx4 v162, s[0:1]
	s_add_i32 m0, s94, 0xe000
	s_nop 0
	global_load_lds_dwordx4 v164, s[0:1]
	s_waitcnt vmcnt(8)
	s_waitcnt lgkmcnt(0)
	s_setprio 1
	s_barrier
	v_mfma_f32_16x16x32_bf16 v[66:69], v[78:81], v[214:217], 0
	v_mfma_f32_16x16x32_bf16 v[62:65], v[142:145], v[214:217], 0
	v_mfma_f32_16x16x32_bf16 v[58:61], v[78:81], v[222:225], 0
	v_mfma_f32_16x16x32_bf16 v[54:57], v[142:145], v[222:225], 0
	v_mfma_f32_16x16x32_bf16 v[46:49], v[78:81], v[230:233], 0
	v_mfma_f32_16x16x32_bf16 v[42:45], v[142:145], v[230:233], 0
	v_mfma_f32_16x16x32_bf16 v[38:41], v[78:81], v[238:241], 0
	v_mfma_f32_16x16x32_bf16 v[34:37], v[142:145], v[238:241], 0
	v_mfma_f32_16x16x32_bf16 v[66:69], v[138:141], v[218:221], v[66:69]
	v_mfma_f32_16x16x32_bf16 v[62:65], v[146:149], v[218:221], v[62:65]
	v_mfma_f32_16x16x32_bf16 v[58:61], v[138:141], v[226:229], v[58:61]
	v_mfma_f32_16x16x32_bf16 v[54:57], v[146:149], v[226:229], v[54:57]
	v_mfma_f32_16x16x32_bf16 v[46:49], v[138:141], v[234:237], v[46:49]
	v_mfma_f32_16x16x32_bf16 v[42:45], v[146:149], v[234:237], v[42:45]
	v_mfma_f32_16x16x32_bf16 v[38:41], v[138:141], v[242:245], v[38:41]
	v_mfma_f32_16x16x32_bf16 v[34:37], v[146:149], v[242:245], v[34:37]
	s_setprio 0
	s_setprio 1
	v_mfma_f32_16x16x32_bf16 v[134:137], v[170:173], v[214:217], 0
	v_mfma_f32_16x16x32_bf16 v[130:133], v[180:183], v[214:217], 0
	v_mfma_f32_16x16x32_bf16 v[126:129], v[170:173], v[222:225], 0
	v_mfma_f32_16x16x32_bf16 v[122:125], v[180:183], v[222:225], 0
	v_mfma_f32_16x16x32_bf16 v[118:121], v[170:173], v[230:233], 0
	v_mfma_f32_16x16x32_bf16 v[114:117], v[180:183], v[230:233], 0
	v_mfma_f32_16x16x32_bf16 v[110:113], v[170:173], v[238:241], 0
	v_mfma_f32_16x16x32_bf16 v[106:109], v[180:183], v[238:241], 0
	v_mfma_f32_16x16x32_bf16 v[134:137], v[174:177], v[218:221], v[134:137]
	v_mfma_f32_16x16x32_bf16 v[130:133], v[210:213], v[218:221], v[130:133]
	v_mfma_f32_16x16x32_bf16 v[126:129], v[174:177], v[226:229], v[126:129]
	v_mfma_f32_16x16x32_bf16 v[122:125], v[210:213], v[226:229], v[122:125]
	v_mfma_f32_16x16x32_bf16 v[118:121], v[174:177], v[234:237], v[118:121]
	v_mfma_f32_16x16x32_bf16 v[114:117], v[210:213], v[234:237], v[114:117]
	v_mfma_f32_16x16x32_bf16 v[110:113], v[174:177], v[242:245], v[110:113]
	v_mfma_f32_16x16x32_bf16 v[106:109], v[210:213], v[242:245], v[106:109]
	s_barrier
	s_setprio 0
	s_add_i32 s81, s53, s93
	s_add_u32 s98, s8, 0x80
	s_addc_u32 s99, s9, 0
	s_mov_b32 m0, s81
	ds_read_b128 v[214:217], v206 offset:16384
	ds_read_b128 v[218:221], v206 offset:17408
	ds_read_b128 v[222:225], v206 offset:18432
	ds_read_b128 v[226:229], v206 offset:19456
	ds_read_b128 v[230:233], v206 offset:20480
	ds_read_b128 v[234:237], v206 offset:21504
	ds_read_b128 v[238:241], v206 offset:22528
	ds_read_b128 v[242:245], v206 offset:23552
	global_load_lds_dwordx4 v152, s[8:9]
	s_add_i32 m0, s81, 0x2000
	s_add_u32 s82, s8, 0x80000
	s_addc_u32 s83, s9, 0
	s_add_i32 s81, s54, s93
	global_load_lds_dwordx4 v156, s[8:9]
	s_mov_b32 m0, s81
	s_nop 0
	global_load_lds_dwordx4 v152, s[82:83]
	s_add_i32 m0, s81, 0x2000
	s_nop 0
	global_load_lds_dwordx4 v156, s[82:83]
	s_add_u32 s100, s74, 0x80
	s_addc_u32 s101, s75, 0
	s_mov_b32 m0, s94
	s_nop 0
	global_load_lds_dwordx4 v150, s[74:75]
	s_mov_b32 m0, s95
	s_nop 0
	global_load_lds_dwordx4 v154, s[74:75]
	s_waitcnt vmcnt(8)
	s_waitcnt lgkmcnt(0)
	s_setprio 1
	s_barrier
	v_mfma_f32_16x16x32_bf16 v[30:33], v[78:81], v[214:217], 0
	v_mfma_f32_16x16x32_bf16 v[26:29], v[142:145], v[214:217], 0
	v_mfma_f32_16x16x32_bf16 v[22:25], v[78:81], v[222:225], 0
	v_mfma_f32_16x16x32_bf16 v[18:21], v[142:145], v[222:225], 0
	v_mfma_f32_16x16x32_bf16 v[14:17], v[78:81], v[230:233], 0
	v_mfma_f32_16x16x32_bf16 v[10:13], v[142:145], v[230:233], 0
	v_mfma_f32_16x16x32_bf16 v[6:9], v[78:81], v[238:241], 0
	v_mfma_f32_16x16x32_bf16 v[2:5], v[142:145], v[238:241], 0
	v_mfma_f32_16x16x32_bf16 v[30:33], v[138:141], v[218:221], v[30:33]
	v_mfma_f32_16x16x32_bf16 v[26:29], v[146:149], v[218:221], v[26:29]
	v_mfma_f32_16x16x32_bf16 v[22:25], v[138:141], v[226:229], v[22:25]
	v_mfma_f32_16x16x32_bf16 v[18:21], v[146:149], v[226:229], v[18:21]
	v_mfma_f32_16x16x32_bf16 v[14:17], v[138:141], v[234:237], v[14:17]
	v_mfma_f32_16x16x32_bf16 v[10:13], v[146:149], v[234:237], v[10:13]
	v_mfma_f32_16x16x32_bf16 v[6:9], v[138:141], v[242:245], v[6:9]
	v_mfma_f32_16x16x32_bf16 v[2:5], v[146:149], v[242:245], v[2:5]
	s_setprio 0
	s_setprio 1
	v_mfma_f32_16x16x32_bf16 v[98:101], v[180:183], v[214:217], 0
	v_mfma_f32_16x16x32_bf16 v[94:97], v[170:173], v[222:225], 0
	v_mfma_f32_16x16x32_bf16 v[90:93], v[180:183], v[222:225], 0
	v_mfma_f32_16x16x32_bf16 v[86:89], v[170:173], v[230:233], 0
	v_mfma_f32_16x16x32_bf16 v[82:85], v[180:183], v[230:233], 0
	v_mfma_f32_16x16x32_bf16 v[74:77], v[170:173], v[238:241], 0
	v_mfma_f32_16x16x32_bf16 v[70:73], v[180:183], v[238:241], 0
	v_mfma_f32_16x16x32_bf16 v[78:81], v[170:173], v[214:217], 0
	v_mfma_f32_16x16x32_bf16 v[98:101], v[210:213], v[218:221], v[98:101]
	v_mfma_f32_16x16x32_bf16 v[94:97], v[174:177], v[226:229], v[94:97]
	v_mfma_f32_16x16x32_bf16 v[90:93], v[210:213], v[226:229], v[90:93]
	v_mfma_f32_16x16x32_bf16 v[86:89], v[174:177], v[234:237], v[86:89]
	v_mfma_f32_16x16x32_bf16 v[82:85], v[210:213], v[234:237], v[82:85]
	v_mfma_f32_16x16x32_bf16 v[74:77], v[174:177], v[242:245], v[74:77]
	v_mfma_f32_16x16x32_bf16 v[70:73], v[210:213], v[242:245], v[70:73]
	v_mfma_f32_16x16x32_bf16 v[78:81], v[174:177], v[218:221], v[78:81]
	s_barrier
	s_setprio 0
	s_add_i32 s81, 0, 0x18000
	v_add_u32_e32 v1, s81, v194
	s_add_i32 s82, 0, 0x1c000
	ds_read_b128 v[102:105], v1
	ds_read_b128 v[138:141], v1 offset:1024
	ds_read_b128 v[142:145], v1 offset:2048
	ds_read_b128 v[146:149], v1 offset:3072
	v_add_u32_e32 v1, s82, v194
	ds_read_b128 v[170:173], v1
	ds_read_b128 v[174:177], v1 offset:1024
	ds_read_b128 v[180:183], v1 offset:2048
	ds_read_b128 v[210:213], v1 offset:3072
	s_add_u32 s74, s74, 0x80000
	s_addc_u32 s75, s75, 0
	s_mov_b32 m0, s96
	ds_read_b128 v[214:217], v206 offset:32768
	ds_read_b128 v[218:221], v206 offset:33792
	ds_read_b128 v[222:225], v206 offset:34816
	ds_read_b128 v[226:229], v206 offset:35840
	ds_read_b128 v[230:233], v206 offset:36864
	ds_read_b128 v[234:237], v206 offset:37888
	ds_read_b128 v[238:241], v206 offset:38912
	ds_read_b128 v[242:245], v206 offset:39936
	global_load_lds_dwordx4 v150, s[74:75]
	s_mov_b32 m0, s97
	s_nop 0
	global_load_lds_dwordx4 v154, s[74:75]
	s_waitcnt vmcnt(8)
	s_waitcnt lgkmcnt(0)
	s_setprio 1
	s_barrier
	v_mfma_f32_16x16x32_bf16 v[66:69], v[102:105], v[214:217], v[66:69]
	v_mfma_f32_16x16x32_bf16 v[62:65], v[142:145], v[214:217], v[62:65]
	v_mfma_f32_16x16x32_bf16 v[58:61], v[102:105], v[222:225], v[58:61]
	v_mfma_f32_16x16x32_bf16 v[54:57], v[142:145], v[222:225], v[54:57]
	v_mfma_f32_16x16x32_bf16 v[46:49], v[102:105], v[230:233], v[46:49]
	v_mfma_f32_16x16x32_bf16 v[42:45], v[142:145], v[230:233], v[42:45]
	v_mfma_f32_16x16x32_bf16 v[38:41], v[102:105], v[238:241], v[38:41]
	v_mfma_f32_16x16x32_bf16 v[34:37], v[142:145], v[238:241], v[34:37]
	v_mfma_f32_16x16x32_bf16 v[66:69], v[138:141], v[218:221], v[66:69]
	v_mfma_f32_16x16x32_bf16 v[62:65], v[146:149], v[218:221], v[62:65]
	v_mfma_f32_16x16x32_bf16 v[58:61], v[138:141], v[226:229], v[58:61]
	v_mfma_f32_16x16x32_bf16 v[54:57], v[146:149], v[226:229], v[54:57]
	v_mfma_f32_16x16x32_bf16 v[46:49], v[138:141], v[234:237], v[46:49]
	v_mfma_f32_16x16x32_bf16 v[42:45], v[146:149], v[234:237], v[42:45]
	v_mfma_f32_16x16x32_bf16 v[38:41], v[138:141], v[242:245], v[38:41]
	v_mfma_f32_16x16x32_bf16 v[34:37], v[146:149], v[242:245], v[34:37]
	s_setprio 0
	s_setprio 1
	v_mfma_f32_16x16x32_bf16 v[134:137], v[170:173], v[214:217], v[134:137]
	v_mfma_f32_16x16x32_bf16 v[130:133], v[180:183], v[214:217], v[130:133]
	v_mfma_f32_16x16x32_bf16 v[126:129], v[170:173], v[222:225], v[126:129]
	v_mfma_f32_16x16x32_bf16 v[122:125], v[180:183], v[222:225], v[122:125]
	v_mfma_f32_16x16x32_bf16 v[118:121], v[170:173], v[230:233], v[118:121]
	v_mfma_f32_16x16x32_bf16 v[114:117], v[180:183], v[230:233], v[114:117]
	v_mfma_f32_16x16x32_bf16 v[110:113], v[170:173], v[238:241], v[110:113]
	v_mfma_f32_16x16x32_bf16 v[106:109], v[180:183], v[238:241], v[106:109]
	v_mfma_f32_16x16x32_bf16 v[134:137], v[174:177], v[218:221], v[134:137]
	v_mfma_f32_16x16x32_bf16 v[130:133], v[210:213], v[218:221], v[130:133]
	v_mfma_f32_16x16x32_bf16 v[126:129], v[174:177], v[226:229], v[126:129]
	v_mfma_f32_16x16x32_bf16 v[122:125], v[210:213], v[226:229], v[122:125]
	v_mfma_f32_16x16x32_bf16 v[118:121], v[174:177], v[234:237], v[118:121]
	v_mfma_f32_16x16x32_bf16 v[114:117], v[210:213], v[234:237], v[114:117]
	v_mfma_f32_16x16x32_bf16 v[110:113], v[174:177], v[242:245], v[110:113]
	v_mfma_f32_16x16x32_bf16 v[106:109], v[210:213], v[242:245], v[106:109]
	s_barrier
	s_setprio 0
	s_add_i32 s74, s81, s93
	s_mov_b32 m0, s74
	ds_read_b128 v[214:217], v206 offset:49152
	ds_read_b128 v[218:221], v206 offset:50176
	ds_read_b128 v[222:225], v206 offset:51200
	ds_read_b128 v[226:229], v206 offset:52224
	ds_read_b128 v[230:233], v206 offset:53248
	ds_read_b128 v[234:237], v206 offset:54272
	ds_read_b128 v[238:241], v206 offset:55296
	ds_read_b128 v[242:245], v206 offset:56320
	global_load_lds_dwordx4 v152, s[98:99]
	s_add_i32 m0, s74, 0x2000
	s_add_u32 s8, s8, 0x80080
	s_addc_u32 s9, s9, 0
	s_add_i32 s74, s82, s93
	global_load_lds_dwordx4 v156, s[98:99]
	s_mov_b32 m0, s74
	s_nop 0
	global_load_lds_dwordx4 v152, s[8:9]
	s_add_i32 m0, s74, 0x2000
	s_nop 0
	global_load_lds_dwordx4 v156, s[8:9]
	s_mov_b32 m0, s85
	s_nop 0
	global_load_lds_dwordx4 v150, s[100:101]
	s_mov_b32 m0, s18
	s_nop 0
	global_load_lds_dwordx4 v154, s[100:101]
	s_waitcnt vmcnt(8)
	s_waitcnt lgkmcnt(0)
	s_setprio 1
	s_barrier
	v_mfma_f32_16x16x32_bf16 v[30:33], v[102:105], v[214:217], v[30:33]
	v_mfma_f32_16x16x32_bf16 v[26:29], v[142:145], v[214:217], v[26:29]
	v_mfma_f32_16x16x32_bf16 v[22:25], v[102:105], v[222:225], v[22:25]
	v_mfma_f32_16x16x32_bf16 v[18:21], v[142:145], v[222:225], v[18:21]
	v_mfma_f32_16x16x32_bf16 v[14:17], v[102:105], v[230:233], v[14:17]
	v_mfma_f32_16x16x32_bf16 v[10:13], v[142:145], v[230:233], v[10:13]
	v_mfma_f32_16x16x32_bf16 v[6:9], v[102:105], v[238:241], v[6:9]
	v_mfma_f32_16x16x32_bf16 v[2:5], v[142:145], v[238:241], v[2:5]
	v_mfma_f32_16x16x32_bf16 v[30:33], v[138:141], v[218:221], v[30:33]
	v_mfma_f32_16x16x32_bf16 v[26:29], v[146:149], v[218:221], v[26:29]
	v_mfma_f32_16x16x32_bf16 v[22:25], v[138:141], v[226:229], v[22:25]
	v_mfma_f32_16x16x32_bf16 v[18:21], v[146:149], v[226:229], v[18:21]
	v_mfma_f32_16x16x32_bf16 v[14:17], v[138:141], v[234:237], v[14:17]
	v_mfma_f32_16x16x32_bf16 v[10:13], v[146:149], v[234:237], v[10:13]
	v_mfma_f32_16x16x32_bf16 v[6:9], v[138:141], v[242:245], v[6:9]
	v_mfma_f32_16x16x32_bf16 v[2:5], v[146:149], v[242:245], v[2:5]
	s_setprio 0
	s_setprio 1
	v_mfma_f32_16x16x32_bf16 v[78:81], v[170:173], v[214:217], v[78:81]
	v_mfma_f32_16x16x32_bf16 v[102:105], v[174:177], v[218:221], v[78:81]
	v_mfma_f32_16x16x32_bf16 v[78:81], v[180:183], v[214:217], v[98:101]
	v_mfma_f32_16x16x32_bf16 v[98:101], v[210:213], v[218:221], v[78:81]
	v_mfma_f32_16x16x32_bf16 v[78:81], v[170:173], v[222:225], v[94:97]
	v_mfma_f32_16x16x32_bf16 v[94:97], v[174:177], v[226:229], v[78:81]
	v_mfma_f32_16x16x32_bf16 v[78:81], v[180:183], v[222:225], v[90:93]
	v_mfma_f32_16x16x32_bf16 v[90:93], v[210:213], v[226:229], v[78:81]
	v_mfma_f32_16x16x32_bf16 v[78:81], v[170:173], v[230:233], v[86:89]
	v_mfma_f32_16x16x32_bf16 v[86:89], v[174:177], v[234:237], v[78:81]
	v_mfma_f32_16x16x32_bf16 v[78:81], v[180:183], v[230:233], v[82:85]
	v_mfma_f32_16x16x32_bf16 v[74:77], v[170:173], v[238:241], v[74:77]
	v_mfma_f32_16x16x32_bf16 v[70:73], v[180:183], v[238:241], v[70:73]
	v_mfma_f32_16x16x32_bf16 v[82:85], v[210:213], v[234:237], v[78:81]
	v_mfma_f32_16x16x32_bf16 v[74:77], v[174:177], v[242:245], v[74:77]
	v_mfma_f32_16x16x32_bf16 v[70:73], v[210:213], v[242:245], v[70:73]
	s_barrier
	s_setprio 0
	s_add_i32 s80, s80, 2
	s_add_u32 s0, s0, 0x100
	s_addc_u32 s1, s1, 0
	s_add_u32 s78, s78, 0x100
	s_addc_u32 s79, s79, 0
	s_cmp_gt_u32 s80, 29
.LBB0_469:
	ds_read_b128 v[78:81], v204
	ds_read_b128 v[138:141], v204 offset:1024
	ds_read_b128 v[142:145], v204 offset:2048
	ds_read_b128 v[146:149], v204 offset:3072
	ds_read_b128 v[170:173], v205
	ds_read_b128 v[174:177], v205 offset:1024
	ds_read_b128 v[180:183], v205 offset:2048
	ds_read_b128 v[210:213], v205 offset:3072
	s_add_u32 s8, s0, 0xfff80080
	s_addc_u32 s9, s1, -1
	s_cmp_eq_u32 s80, 28
	s_cselect_b32 s75, s11, s9
	s_cselect_b32 s74, s76, s8
	s_cselect_b32 s9, s69, s79
	s_cselect_b32 s8, s77, s78
	s_add_i32 m0, s94, 0xc000
	ds_read_b128 v[214:217], v206
	ds_read_b128 v[218:221], v206 offset:1024
	ds_read_b128 v[222:225], v206 offset:2048
	ds_read_b128 v[226:229], v206 offset:3072
	ds_read_b128 v[230:233], v206 offset:4096
	ds_read_b128 v[234:237], v206 offset:5120
	ds_read_b128 v[238:241], v206 offset:6144
	ds_read_b128 v[242:245], v206 offset:7168
	global_load_lds_dwordx4 v162, s[0:1]
	s_add_i32 m0, s94, 0xe000
	s_nop 0
	global_load_lds_dwordx4 v164, s[0:1]
	s_waitcnt vmcnt(8)
	s_waitcnt lgkmcnt(0)
	s_setprio 1
	s_barrier
	v_mfma_f32_16x16x32_bf16 v[66:69], v[78:81], v[214:217], v[66:69]
	v_mfma_f32_16x16x32_bf16 v[62:65], v[142:145], v[214:217], v[62:65]
	v_mfma_f32_16x16x32_bf16 v[58:61], v[78:81], v[222:225], v[58:61]
	v_mfma_f32_16x16x32_bf16 v[54:57], v[142:145], v[222:225], v[54:57]
	v_mfma_f32_16x16x32_bf16 v[46:49], v[78:81], v[230:233], v[46:49]
	v_mfma_f32_16x16x32_bf16 v[42:45], v[142:145], v[230:233], v[42:45]
	v_mfma_f32_16x16x32_bf16 v[38:41], v[78:81], v[238:241], v[38:41]
	v_mfma_f32_16x16x32_bf16 v[34:37], v[142:145], v[238:241], v[34:37]
	v_mfma_f32_16x16x32_bf16 v[66:69], v[138:141], v[218:221], v[66:69]
	v_mfma_f32_16x16x32_bf16 v[62:65], v[146:149], v[218:221], v[62:65]
	v_mfma_f32_16x16x32_bf16 v[58:61], v[138:141], v[226:229], v[58:61]
	v_mfma_f32_16x16x32_bf16 v[54:57], v[146:149], v[226:229], v[54:57]
	v_mfma_f32_16x16x32_bf16 v[46:49], v[138:141], v[234:237], v[46:49]
	v_mfma_f32_16x16x32_bf16 v[42:45], v[146:149], v[234:237], v[42:45]
	v_mfma_f32_16x16x32_bf16 v[38:41], v[138:141], v[242:245], v[38:41]
	v_mfma_f32_16x16x32_bf16 v[34:37], v[146:149], v[242:245], v[34:37]
	s_setprio 0
	s_setprio 1
	v_mfma_f32_16x16x32_bf16 v[134:137], v[170:173], v[214:217], v[134:137]
	v_mfma_f32_16x16x32_bf16 v[130:133], v[180:183], v[214:217], v[130:133]
	v_mfma_f32_16x16x32_bf16 v[126:129], v[170:173], v[222:225], v[126:129]
	v_mfma_f32_16x16x32_bf16 v[122:125], v[180:183], v[222:225], v[122:125]
	v_mfma_f32_16x16x32_bf16 v[118:121], v[170:173], v[230:233], v[118:121]
	v_mfma_f32_16x16x32_bf16 v[114:117], v[180:183], v[230:233], v[114:117]
	v_mfma_f32_16x16x32_bf16 v[110:113], v[170:173], v[238:241], v[110:113]
	v_mfma_f32_16x16x32_bf16 v[106:109], v[180:183], v[238:241], v[106:109]
	v_mfma_f32_16x16x32_bf16 v[134:137], v[174:177], v[218:221], v[134:137]
	v_mfma_f32_16x16x32_bf16 v[130:133], v[210:213], v[218:221], v[130:133]
	v_mfma_f32_16x16x32_bf16 v[126:129], v[174:177], v[226:229], v[126:129]
	v_mfma_f32_16x16x32_bf16 v[122:125], v[210:213], v[226:229], v[122:125]
	v_mfma_f32_16x16x32_bf16 v[118:121], v[174:177], v[234:237], v[118:121]
	v_mfma_f32_16x16x32_bf16 v[114:117], v[210:213], v[234:237], v[114:117]
	v_mfma_f32_16x16x32_bf16 v[110:113], v[174:177], v[242:245], v[110:113]
	v_mfma_f32_16x16x32_bf16 v[106:109], v[210:213], v[242:245], v[106:109]
	s_barrier
	s_setprio 0
	s_add_i32 s81, s53, s93
	s_add_u32 s98, s8, 0x80
	s_addc_u32 s99, s9, 0
	s_mov_b32 m0, s81
	ds_read_b128 v[214:217], v206 offset:16384
	ds_read_b128 v[218:221], v206 offset:17408
	ds_read_b128 v[222:225], v206 offset:18432
	ds_read_b128 v[226:229], v206 offset:19456
	ds_read_b128 v[230:233], v206 offset:20480
	ds_read_b128 v[234:237], v206 offset:21504
	ds_read_b128 v[238:241], v206 offset:22528
	ds_read_b128 v[242:245], v206 offset:23552
	global_load_lds_dwordx4 v152, s[8:9]
	s_add_i32 m0, s81, 0x2000
	s_add_u32 s82, s8, 0x80000
	s_addc_u32 s83, s9, 0
	s_add_i32 s81, s54, s93
	global_load_lds_dwordx4 v156, s[8:9]
	s_mov_b32 m0, s81
	s_nop 0
	global_load_lds_dwordx4 v152, s[82:83]
	s_add_i32 m0, s81, 0x2000
	s_nop 0
	global_load_lds_dwordx4 v156, s[82:83]
	s_add_u32 s100, s74, 0x80
	s_addc_u32 s101, s75, 0
	s_mov_b32 m0, s94
	s_nop 0
	global_load_lds_dwordx4 v150, s[74:75]
	s_mov_b32 m0, s95
	s_nop 0
	global_load_lds_dwordx4 v154, s[74:75]
	s_waitcnt vmcnt(8)
	s_waitcnt lgkmcnt(0)
	s_setprio 1
	s_barrier
	v_mfma_f32_16x16x32_bf16 v[30:33], v[78:81], v[214:217], v[30:33]
	v_mfma_f32_16x16x32_bf16 v[26:29], v[142:145], v[214:217], v[26:29]
	v_mfma_f32_16x16x32_bf16 v[22:25], v[78:81], v[222:225], v[22:25]
	v_mfma_f32_16x16x32_bf16 v[18:21], v[142:145], v[222:225], v[18:21]
	v_mfma_f32_16x16x32_bf16 v[14:17], v[78:81], v[230:233], v[14:17]
	v_mfma_f32_16x16x32_bf16 v[10:13], v[142:145], v[230:233], v[10:13]
	v_mfma_f32_16x16x32_bf16 v[6:9], v[78:81], v[238:241], v[6:9]
	v_mfma_f32_16x16x32_bf16 v[2:5], v[142:145], v[238:241], v[2:5]
	v_mfma_f32_16x16x32_bf16 v[30:33], v[138:141], v[218:221], v[30:33]
	v_mfma_f32_16x16x32_bf16 v[26:29], v[146:149], v[218:221], v[26:29]
	v_mfma_f32_16x16x32_bf16 v[22:25], v[138:141], v[226:229], v[22:25]
	v_mfma_f32_16x16x32_bf16 v[18:21], v[146:149], v[226:229], v[18:21]
	v_mfma_f32_16x16x32_bf16 v[14:17], v[138:141], v[234:237], v[14:17]
	v_mfma_f32_16x16x32_bf16 v[10:13], v[146:149], v[234:237], v[10:13]
	v_mfma_f32_16x16x32_bf16 v[6:9], v[138:141], v[242:245], v[6:9]
	v_mfma_f32_16x16x32_bf16 v[2:5], v[146:149], v[242:245], v[2:5]
	s_setprio 0
	s_setprio 1
	v_mfma_f32_16x16x32_bf16 v[98:101], v[180:183], v[214:217], v[98:101]
	v_mfma_f32_16x16x32_bf16 v[94:97], v[170:173], v[222:225], v[94:97]
	v_mfma_f32_16x16x32_bf16 v[90:93], v[180:183], v[222:225], v[90:93]
	v_mfma_f32_16x16x32_bf16 v[86:89], v[170:173], v[230:233], v[86:89]
	v_mfma_f32_16x16x32_bf16 v[82:85], v[180:183], v[230:233], v[82:85]
	v_mfma_f32_16x16x32_bf16 v[74:77], v[170:173], v[238:241], v[74:77]
	v_mfma_f32_16x16x32_bf16 v[70:73], v[180:183], v[238:241], v[70:73]
	v_mfma_f32_16x16x32_bf16 v[78:81], v[170:173], v[214:217], v[102:105]
	v_mfma_f32_16x16x32_bf16 v[98:101], v[210:213], v[218:221], v[98:101]
	v_mfma_f32_16x16x32_bf16 v[94:97], v[174:177], v[226:229], v[94:97]
	v_mfma_f32_16x16x32_bf16 v[90:93], v[210:213], v[226:229], v[90:93]
	v_mfma_f32_16x16x32_bf16 v[86:89], v[174:177], v[234:237], v[86:89]
	v_mfma_f32_16x16x32_bf16 v[82:85], v[210:213], v[234:237], v[82:85]
	v_mfma_f32_16x16x32_bf16 v[74:77], v[174:177], v[242:245], v[74:77]
	v_mfma_f32_16x16x32_bf16 v[70:73], v[210:213], v[242:245], v[70:73]
	v_mfma_f32_16x16x32_bf16 v[78:81], v[174:177], v[218:221], v[78:81]
	s_barrier
	s_setprio 0
	s_add_i32 s81, 0, 0x18000
	v_add_u32_e32 v1, s81, v194
	s_add_i32 s82, 0, 0x1c000
	ds_read_b128 v[102:105], v1
	ds_read_b128 v[138:141], v1 offset:1024
	ds_read_b128 v[142:145], v1 offset:2048
	ds_read_b128 v[146:149], v1 offset:3072
	v_add_u32_e32 v1, s82, v194
	ds_read_b128 v[170:173], v1
	ds_read_b128 v[174:177], v1 offset:1024
	ds_read_b128 v[180:183], v1 offset:2048
	ds_read_b128 v[210:213], v1 offset:3072
	s_add_u32 s74, s74, 0x80000
	s_addc_u32 s75, s75, 0
	s_mov_b32 m0, s96
	ds_read_b128 v[214:217], v206 offset:32768
	ds_read_b128 v[218:221], v206 offset:33792
	ds_read_b128 v[222:225], v206 offset:34816
	ds_read_b128 v[226:229], v206 offset:35840
	ds_read_b128 v[230:233], v206 offset:36864
	ds_read_b128 v[234:237], v206 offset:37888
	ds_read_b128 v[238:241], v206 offset:38912
	ds_read_b128 v[242:245], v206 offset:39936
	global_load_lds_dwordx4 v150, s[74:75]
	s_mov_b32 m0, s97
	s_nop 0
	global_load_lds_dwordx4 v154, s[74:75]
	s_waitcnt vmcnt(8)
	s_waitcnt lgkmcnt(0)
	s_setprio 1
	s_barrier
	v_mfma_f32_16x16x32_bf16 v[66:69], v[102:105], v[214:217], v[66:69]
	v_mfma_f32_16x16x32_bf16 v[62:65], v[142:145], v[214:217], v[62:65]
	v_mfma_f32_16x16x32_bf16 v[58:61], v[102:105], v[222:225], v[58:61]
	v_mfma_f32_16x16x32_bf16 v[54:57], v[142:145], v[222:225], v[54:57]
	v_mfma_f32_16x16x32_bf16 v[46:49], v[102:105], v[230:233], v[46:49]
	v_mfma_f32_16x16x32_bf16 v[42:45], v[142:145], v[230:233], v[42:45]
	v_mfma_f32_16x16x32_bf16 v[38:41], v[102:105], v[238:241], v[38:41]
	v_mfma_f32_16x16x32_bf16 v[34:37], v[142:145], v[238:241], v[34:37]
	v_mfma_f32_16x16x32_bf16 v[66:69], v[138:141], v[218:221], v[66:69]
	v_mfma_f32_16x16x32_bf16 v[62:65], v[146:149], v[218:221], v[62:65]
	v_mfma_f32_16x16x32_bf16 v[58:61], v[138:141], v[226:229], v[58:61]
	v_mfma_f32_16x16x32_bf16 v[54:57], v[146:149], v[226:229], v[54:57]
	v_mfma_f32_16x16x32_bf16 v[46:49], v[138:141], v[234:237], v[46:49]
	v_mfma_f32_16x16x32_bf16 v[42:45], v[146:149], v[234:237], v[42:45]
	v_mfma_f32_16x16x32_bf16 v[38:41], v[138:141], v[242:245], v[38:41]
	v_mfma_f32_16x16x32_bf16 v[34:37], v[146:149], v[242:245], v[34:37]
	s_setprio 0
	s_setprio 1
	v_mfma_f32_16x16x32_bf16 v[134:137], v[170:173], v[214:217], v[134:137]
	v_mfma_f32_16x16x32_bf16 v[130:133], v[180:183], v[214:217], v[130:133]
	v_mfma_f32_16x16x32_bf16 v[126:129], v[170:173], v[222:225], v[126:129]
	v_mfma_f32_16x16x32_bf16 v[122:125], v[180:183], v[222:225], v[122:125]
	v_mfma_f32_16x16x32_bf16 v[118:121], v[170:173], v[230:233], v[118:121]
	v_mfma_f32_16x16x32_bf16 v[114:117], v[180:183], v[230:233], v[114:117]
	v_mfma_f32_16x16x32_bf16 v[110:113], v[170:173], v[238:241], v[110:113]
	v_mfma_f32_16x16x32_bf16 v[106:109], v[180:183], v[238:241], v[106:109]
	v_mfma_f32_16x16x32_bf16 v[134:137], v[174:177], v[218:221], v[134:137]
	v_mfma_f32_16x16x32_bf16 v[130:133], v[210:213], v[218:221], v[130:133]
	v_mfma_f32_16x16x32_bf16 v[126:129], v[174:177], v[226:229], v[126:129]
	v_mfma_f32_16x16x32_bf16 v[122:125], v[210:213], v[226:229], v[122:125]
	v_mfma_f32_16x16x32_bf16 v[118:121], v[174:177], v[234:237], v[118:121]
	v_mfma_f32_16x16x32_bf16 v[114:117], v[210:213], v[234:237], v[114:117]
	v_mfma_f32_16x16x32_bf16 v[110:113], v[174:177], v[242:245], v[110:113]
	v_mfma_f32_16x16x32_bf16 v[106:109], v[210:213], v[242:245], v[106:109]
	s_barrier
	s_setprio 0
	s_add_i32 s74, s81, s93
	s_mov_b32 m0, s74
	ds_read_b128 v[214:217], v206 offset:49152
	ds_read_b128 v[218:221], v206 offset:50176
	ds_read_b128 v[222:225], v206 offset:51200
	ds_read_b128 v[226:229], v206 offset:52224
	ds_read_b128 v[230:233], v206 offset:53248
	ds_read_b128 v[234:237], v206 offset:54272
	ds_read_b128 v[238:241], v206 offset:55296
	ds_read_b128 v[242:245], v206 offset:56320
	global_load_lds_dwordx4 v152, s[98:99]
	s_add_i32 m0, s74, 0x2000
	s_add_u32 s8, s8, 0x80080
	s_addc_u32 s9, s9, 0
	s_add_i32 s74, s82, s93
	global_load_lds_dwordx4 v156, s[98:99]
	s_mov_b32 m0, s74
	s_nop 0
	global_load_lds_dwordx4 v152, s[8:9]
	s_add_i32 m0, s74, 0x2000
	s_nop 0
	global_load_lds_dwordx4 v156, s[8:9]
	s_mov_b32 m0, s85
	s_nop 0
	global_load_lds_dwordx4 v150, s[100:101]
	s_mov_b32 m0, s18
	s_nop 0
	global_load_lds_dwordx4 v154, s[100:101]
	s_add_i32 s80, s80, 2
	s_add_u32 s0, s0, 0x100
	s_addc_u32 s1, s1, 0
	s_add_u32 s78, s78, 0x100
	s_addc_u32 s79, s79, 0
	s_cmp_gt_u32 s80, 29
	s_waitcnt vmcnt(8)
	s_waitcnt lgkmcnt(0)
	s_setprio 1
	s_barrier
	v_mfma_f32_16x16x32_bf16 v[30:33], v[102:105], v[214:217], v[30:33]
	v_mfma_f32_16x16x32_bf16 v[26:29], v[142:145], v[214:217], v[26:29]
	v_mfma_f32_16x16x32_bf16 v[22:25], v[102:105], v[222:225], v[22:25]
	v_mfma_f32_16x16x32_bf16 v[18:21], v[142:145], v[222:225], v[18:21]
	v_mfma_f32_16x16x32_bf16 v[14:17], v[102:105], v[230:233], v[14:17]
	v_mfma_f32_16x16x32_bf16 v[10:13], v[142:145], v[230:233], v[10:13]
	v_mfma_f32_16x16x32_bf16 v[6:9], v[102:105], v[238:241], v[6:9]
	v_mfma_f32_16x16x32_bf16 v[2:5], v[142:145], v[238:241], v[2:5]
	v_mfma_f32_16x16x32_bf16 v[30:33], v[138:141], v[218:221], v[30:33]
	v_mfma_f32_16x16x32_bf16 v[26:29], v[146:149], v[218:221], v[26:29]
	v_mfma_f32_16x16x32_bf16 v[22:25], v[138:141], v[226:229], v[22:25]
	v_mfma_f32_16x16x32_bf16 v[18:21], v[146:149], v[226:229], v[18:21]
	v_mfma_f32_16x16x32_bf16 v[14:17], v[138:141], v[234:237], v[14:17]
	v_mfma_f32_16x16x32_bf16 v[10:13], v[146:149], v[234:237], v[10:13]
	v_mfma_f32_16x16x32_bf16 v[6:9], v[138:141], v[242:245], v[6:9]
	v_mfma_f32_16x16x32_bf16 v[2:5], v[146:149], v[242:245], v[2:5]
	s_setprio 0
	s_setprio 1
	v_mfma_f32_16x16x32_bf16 v[78:81], v[170:173], v[214:217], v[78:81]
	v_mfma_f32_16x16x32_bf16 v[102:105], v[174:177], v[218:221], v[78:81]
	v_mfma_f32_16x16x32_bf16 v[78:81], v[180:183], v[214:217], v[98:101]
	v_mfma_f32_16x16x32_bf16 v[98:101], v[210:213], v[218:221], v[78:81]
	v_mfma_f32_16x16x32_bf16 v[78:81], v[170:173], v[222:225], v[94:97]
	v_mfma_f32_16x16x32_bf16 v[94:97], v[174:177], v[226:229], v[78:81]
	v_mfma_f32_16x16x32_bf16 v[78:81], v[180:183], v[222:225], v[90:93]
	v_mfma_f32_16x16x32_bf16 v[90:93], v[210:213], v[226:229], v[78:81]
	v_mfma_f32_16x16x32_bf16 v[78:81], v[170:173], v[230:233], v[86:89]
	v_mfma_f32_16x16x32_bf16 v[86:89], v[174:177], v[234:237], v[78:81]
	v_mfma_f32_16x16x32_bf16 v[78:81], v[180:183], v[230:233], v[82:85]
	v_mfma_f32_16x16x32_bf16 v[74:77], v[170:173], v[238:241], v[74:77]
	v_mfma_f32_16x16x32_bf16 v[70:73], v[180:183], v[238:241], v[70:73]
	v_mfma_f32_16x16x32_bf16 v[82:85], v[210:213], v[234:237], v[78:81]
	v_mfma_f32_16x16x32_bf16 v[74:77], v[174:177], v[242:245], v[74:77]
	v_mfma_f32_16x16x32_bf16 v[70:73], v[210:213], v[242:245], v[70:73]
	s_barrier
	s_setprio 0
	s_cbranch_scc0 .LBB0_469
	s_and_b64 vcc, exec, s[58:59]
	s_cbranch_vccz .LBB0_472
	s_barrier

.LBB0_691:
	s_add_u32 s2, s26, 0x11000000
	s_addc_u32 s3, s27, 0
	s_lshl_b32 s4, s4, 5
	s_and_b32 s12, s4, 0x60
	s_mov_b64 s[4:5], 0x80
	s_add_i32 m0, s53, 0x18000
	v_lshl_add_u64 v[8:9], v[8:9], 0, s[4:5]
	s_lshl_b32 s9, s8, 13
	s_waitcnt vmcnt(2)
	s_barrier
	global_load_lds_dwordx4 v[8:9], off
	v_lshl_add_u64 v[6:7], v[6:7], 0, s[4:5]
	s_add_i32 m0, s53, 0x1a000
	s_add_i32 s65, s53, 0x8000
	s_add_i32 s66, s53, 0xa000
	global_load_lds_dwordx4 v[6:7], off
	v_lshl_add_u64 v[2:3], v[2:3], 0, s[4:5]
	s_mov_b32 m0, s65
	s_add_u32 s10, s56, 0x80080
	global_load_lds_dwordx4 v[2:3], off
	v_lshl_add_u64 v[2:3], v[4:5], 0, s[4:5]
	s_mov_b32 m0, s66
	s_addc_u32 s11, s57, 0
	global_load_lds_dwordx4 v[2:3], off
	s_add_i32 m0, s53, 0x1c000
	s_nop 0
	global_load_lds_dwordx4 v152, s[10:11]
	s_add_i32 m0, s53, 0x1e000
	v_lshl_or_b32 v1, v189, 6, v137
	global_load_lds_dwordx4 v156, s[10:11]
	v_lshlrev_b32_e32 v2, 2, v189
	v_and_b32_e32 v2, 32, v2
	v_bitop3_b32 v1, v1, s9, v2 bitop3:0xde
	v_lshlrev_b32_e32 v2, 9, v0
	v_and_b32_e32 v2, 0x30000, v2
	v_lshlrev_b32_e32 v3, 12, v186
	v_or3_b32 v2, v184, v2, v3
	v_add_u32_e32 v130, v2, v185
	v_lshlrev_b32_e32 v2, 5, v188
	s_waitcnt vmcnt(6)
	s_cmpk_lt_u32 s7, 0x100
	v_and_b32_e32 v2, 0x70000, v2
	s_sext_i32_i8 s74, s6
	v_lshl_or_b32 v139, s12, 7, v136
	s_cselect_b64 s[6:7], -1, 0
	v_or3_b32 v2, v184, v2, v3
	s_add_i32 s68, 0, 0x10000
	s_add_i32 s69, 0, 0x14000
	v_lshl_or_b32 v138, s8, 6, v189
	s_ashr_i32 s67, s33, 31
	v_or_b32_e32 v140, s12, v187
	v_mov_b32_e32 v131, v153
	v_add_u32_e32 v132, v2, v185
	v_mov_b32_e32 v133, v153
	v_add_u32_e32 v141, s68, v139
	v_add_u32_e32 v142, s69, v139
	v_add_u32_e32 v143, 0, v1
	s_mov_b64 s[8:9], 0x20000
	s_mov_b32 s70, 0x20000
	s_mov_b64 s[10:11], 0x24000
	s_mov_b32 s71, 0x24000
	s_mov_b64 s[12:13], 0x28000
	s_mov_b32 s72, 0x28000
	s_mov_b64 s[14:15], 0x2c000
	s_mov_b32 s73, 0x2c000
	s_barrier
	s_branch .LBB0_694

.LBB0_700:
	s_ashr_i32 s37, s36, 31
	s_lshl_b64 s[40:41], s[36:37], 20
	s_add_u32 s40, s18, s40
	s_addc_u32 s41, s19, s41
	s_and_b64 s[42:43], s[16:17], exec
	s_cselect_b32 s37, s41, s55
	s_cselect_b32 s75, s40, s54
	s_ashr_i32 s35, s34, 31
	s_lshl_b64 s[42:43], s[34:35], 20
	s_add_u32 s42, s28, s42
	s_addc_u32 s43, s29, s43
	s_and_b64 s[58:59], s[16:17], exec
	s_cselect_b32 s35, s43, s57
	s_cselect_b32 s76, s42, s56
	s_add_u32 s54, s54, 0x80080
	s_addc_u32 s55, s55, 0
	s_add_u32 s77, s56, 0x100
	s_addc_u32 s78, s57, 0
	s_mov_b32 s79, -2
	ds_read_b128 v[144:147], v141
	ds_read_b128 v[158:161], v141 offset:1024
	ds_read_b128 v[162:165], v141 offset:2048
	ds_read_b128 v[166:169], v141 offset:3072
	ds_read_b128 v[170:173], v142
	ds_read_b128 v[174:177], v142 offset:1024
	ds_read_b128 v[180:183], v142 offset:2048
	ds_read_b128 v[190:193], v142 offset:3072
	s_add_u32 s56, s54, 0xfff80080
	s_addc_u32 s57, s55, -1
	s_cmp_eq_u32 s79, 28
	s_cselect_b32 s59, s37, s57
	s_cselect_b32 s58, s75, s56
	s_cselect_b32 s57, s35, s78
	s_cselect_b32 s56, s76, s77
	s_add_i32 m0, s53, 0xc000
	ds_read_b128 v[194:197], v143
	ds_read_b128 v[198:201], v143 offset:1024
	ds_read_b128 v[202:205], v143 offset:2048
	ds_read_b128 v[206:209], v143 offset:3072
	ds_read_b128 v[210:213], v143 offset:4096
	ds_read_b128 v[214:217], v143 offset:5120
	ds_read_b128 v[218:221], v143 offset:6144
	ds_read_b128 v[222:225], v143 offset:7168
	global_load_lds_dwordx4 v130, s[54:55]
	s_add_i32 m0, s53, 0xe000
	s_nop 0
	global_load_lds_dwordx4 v132, s[54:55]
	s_waitcnt vmcnt(8)
	s_waitcnt lgkmcnt(0)
	s_setprio 1
	s_barrier
	v_mfma_f32_16x16x32_bf16 v[126:129], v[144:147], v[194:197], 0
	v_mfma_f32_16x16x32_bf16 v[122:125], v[162:165], v[194:197], 0
	v_mfma_f32_16x16x32_bf16 v[114:117], v[144:147], v[202:205], 0
	v_mfma_f32_16x16x32_bf16 v[106:109], v[162:165], v[202:205], 0
	v_mfma_f32_16x16x32_bf16 v[98:101], v[144:147], v[210:213], 0
	v_mfma_f32_16x16x32_bf16 v[90:93], v[162:165], v[210:213], 0
	v_mfma_f32_16x16x32_bf16 v[82:85], v[144:147], v[218:221], 0
	v_mfma_f32_16x16x32_bf16 v[74:77], v[162:165], v[218:221], 0
	v_mfma_f32_16x16x32_bf16 v[126:129], v[158:161], v[198:201], v[126:129]
	v_mfma_f32_16x16x32_bf16 v[122:125], v[166:169], v[198:201], v[122:125]
	v_mfma_f32_16x16x32_bf16 v[114:117], v[158:161], v[206:209], v[114:117]
	v_mfma_f32_16x16x32_bf16 v[106:109], v[166:169], v[206:209], v[106:109]
	v_mfma_f32_16x16x32_bf16 v[98:101], v[158:161], v[214:217], v[98:101]
	v_mfma_f32_16x16x32_bf16 v[90:93], v[166:169], v[214:217], v[90:93]
	v_mfma_f32_16x16x32_bf16 v[82:85], v[158:161], v[222:225], v[82:85]
	v_mfma_f32_16x16x32_bf16 v[74:77], v[166:169], v[222:225], v[74:77]
	s_setprio 0
	s_setprio 1
	v_mfma_f32_16x16x32_bf16 v[118:121], v[170:173], v[194:197], 0
	v_mfma_f32_16x16x32_bf16 v[110:113], v[180:183], v[194:197], 0
	v_mfma_f32_16x16x32_bf16 v[102:105], v[170:173], v[202:205], 0
	v_mfma_f32_16x16x32_bf16 v[94:97], v[180:183], v[202:205], 0
	v_mfma_f32_16x16x32_bf16 v[86:89], v[170:173], v[210:213], 0
	v_mfma_f32_16x16x32_bf16 v[78:81], v[180:183], v[210:213], 0
	v_mfma_f32_16x16x32_bf16 v[70:73], v[170:173], v[218:221], 0
	v_mfma_f32_16x16x32_bf16 v[66:69], v[180:183], v[218:221], 0
	v_mfma_f32_16x16x32_bf16 v[118:121], v[174:177], v[198:201], v[118:121]
	v_mfma_f32_16x16x32_bf16 v[110:113], v[190:193], v[198:201], v[110:113]
	v_mfma_f32_16x16x32_bf16 v[102:105], v[174:177], v[206:209], v[102:105]
	v_mfma_f32_16x16x32_bf16 v[94:97], v[190:193], v[206:209], v[94:97]
	v_mfma_f32_16x16x32_bf16 v[86:89], v[174:177], v[214:217], v[86:89]
	v_mfma_f32_16x16x32_bf16 v[78:81], v[190:193], v[214:217], v[78:81]
	v_mfma_f32_16x16x32_bf16 v[70:73], v[174:177], v[222:225], v[70:73]
	v_mfma_f32_16x16x32_bf16 v[66:69], v[190:193], v[222:225], v[66:69]
	s_barrier
	s_setprio 0
	s_add_i32 s80, s68, s60
	s_add_u32 s98, s56, 0x80
	s_addc_u32 s99, s57, 0
	s_mov_b32 m0, s80
	ds_read_b128 v[194:197], v143 offset:16384
	ds_read_b128 v[198:201], v143 offset:17408
	ds_read_b128 v[202:205], v143 offset:18432
	ds_read_b128 v[206:209], v143 offset:19456
	ds_read_b128 v[210:213], v143 offset:20480
	ds_read_b128 v[214:217], v143 offset:21504
	ds_read_b128 v[218:221], v143 offset:22528
	ds_read_b128 v[222:225], v143 offset:23552
	global_load_lds_dwordx4 v152, s[56:57]
	s_add_i32 m0, s80, 0x2000
	s_add_u32 s80, s56, 0x80000
	s_addc_u32 s81, s57, 0
	s_add_i32 s82, s69, s60
	global_load_lds_dwordx4 v156, s[56:57]
	s_mov_b32 m0, s82
	s_nop 0
	global_load_lds_dwordx4 v152, s[80:81]
	s_add_i32 m0, s82, 0x2000
	s_nop 0
	global_load_lds_dwordx4 v156, s[80:81]
	s_add_u32 s100, s58, 0x80
	s_addc_u32 s101, s59, 0
	s_mov_b32 m0, s53
	s_nop 0
	global_load_lds_dwordx4 v150, s[58:59]
	s_mov_b32 m0, s61
	s_nop 0
	global_load_lds_dwordx4 v154, s[58:59]
	s_waitcnt vmcnt(8)
	s_waitcnt lgkmcnt(0)
	s_setprio 1
	s_barrier
	v_mfma_f32_16x16x32_bf16 v[62:65], v[144:147], v[194:197], 0
	v_mfma_f32_16x16x32_bf16 v[58:61], v[162:165], v[194:197], 0
	v_mfma_f32_16x16x32_bf16 v[50:53], v[144:147], v[202:205], 0
	v_mfma_f32_16x16x32_bf16 v[42:45], v[162:165], v[202:205], 0
	v_mfma_f32_16x16x32_bf16 v[34:37], v[144:147], v[210:213], 0
	v_mfma_f32_16x16x32_bf16 v[26:29], v[162:165], v[210:213], 0
	v_mfma_f32_16x16x32_bf16 v[18:21], v[144:147], v[218:221], 0
	v_mfma_f32_16x16x32_bf16 v[10:13], v[162:165], v[218:221], 0
	v_mfma_f32_16x16x32_bf16 v[62:65], v[158:161], v[198:201], v[62:65]
	v_mfma_f32_16x16x32_bf16 v[58:61], v[166:169], v[198:201], v[58:61]
	v_mfma_f32_16x16x32_bf16 v[50:53], v[158:161], v[206:209], v[50:53]
	v_mfma_f32_16x16x32_bf16 v[42:45], v[166:169], v[206:209], v[42:45]
	v_mfma_f32_16x16x32_bf16 v[34:37], v[158:161], v[214:217], v[34:37]
	v_mfma_f32_16x16x32_bf16 v[26:29], v[166:169], v[214:217], v[26:29]
	v_mfma_f32_16x16x32_bf16 v[18:21], v[158:161], v[222:225], v[18:21]
	v_mfma_f32_16x16x32_bf16 v[10:13], v[166:169], v[222:225], v[10:13]
	s_setprio 0
	s_setprio 1
	v_mfma_f32_16x16x32_bf16 v[54:57], v[170:173], v[194:197], 0
	v_mfma_f32_16x16x32_bf16 v[46:49], v[180:183], v[194:197], 0
	v_mfma_f32_16x16x32_bf16 v[38:41], v[170:173], v[202:205], 0
	v_mfma_f32_16x16x32_bf16 v[30:33], v[180:183], v[202:205], 0
	v_mfma_f32_16x16x32_bf16 v[22:25], v[170:173], v[210:213], 0
	v_mfma_f32_16x16x32_bf16 v[14:17], v[180:183], v[210:213], 0
	v_mfma_f32_16x16x32_bf16 v[6:9], v[170:173], v[218:221], 0
	v_mfma_f32_16x16x32_bf16 v[2:5], v[180:183], v[218:221], 0
	v_mfma_f32_16x16x32_bf16 v[54:57], v[174:177], v[198:201], v[54:57]
	v_mfma_f32_16x16x32_bf16 v[46:49], v[190:193], v[198:201], v[46:49]
	v_mfma_f32_16x16x32_bf16 v[38:41], v[174:177], v[206:209], v[38:41]
	v_mfma_f32_16x16x32_bf16 v[30:33], v[190:193], v[206:209], v[30:33]
	v_mfma_f32_16x16x32_bf16 v[22:25], v[174:177], v[214:217], v[22:25]
	v_mfma_f32_16x16x32_bf16 v[14:17], v[190:193], v[214:217], v[14:17]
	v_mfma_f32_16x16x32_bf16 v[6:9], v[174:177], v[222:225], v[6:9]
	v_mfma_f32_16x16x32_bf16 v[2:5], v[190:193], v[222:225], v[2:5]
	s_barrier
	s_setprio 0
	s_add_i32 s80, 0, 0x18000
	v_add_u32_e32 v1, s80, v139
	s_add_i32 s81, 0, 0x1c000
	ds_read_b128 v[144:147], v1
	ds_read_b128 v[158:161], v1 offset:1024
	ds_read_b128 v[162:165], v1 offset:2048
	ds_read_b128 v[166:169], v1 offset:3072
	v_add_u32_e32 v1, s81, v139
	ds_read_b128 v[170:173], v1
	ds_read_b128 v[174:177], v1 offset:1024
	ds_read_b128 v[180:183], v1 offset:2048
	ds_read_b128 v[190:193], v1 offset:3072
	s_add_u32 s58, s58, 0x80000
	s_addc_u32 s59, s59, 0
	s_mov_b32 m0, s62
	ds_read_b128 v[194:197], v143 offset:32768
	ds_read_b128 v[198:201], v143 offset:33792
	ds_read_b128 v[202:205], v143 offset:34816
	ds_read_b128 v[206:209], v143 offset:35840
	ds_read_b128 v[210:213], v143 offset:36864
	ds_read_b128 v[214:217], v143 offset:37888
	ds_read_b128 v[218:221], v143 offset:38912
	ds_read_b128 v[222:225], v143 offset:39936
	global_load_lds_dwordx4 v150, s[58:59]
	s_mov_b32 m0, s63
	s_nop 0
	global_load_lds_dwordx4 v154, s[58:59]
	s_waitcnt vmcnt(8)
	s_waitcnt lgkmcnt(0)
	s_setprio 1
	s_barrier
	v_mfma_f32_16x16x32_bf16 v[126:129], v[144:147], v[194:197], v[126:129]
	v_mfma_f32_16x16x32_bf16 v[122:125], v[162:165], v[194:197], v[122:125]
	v_mfma_f32_16x16x32_bf16 v[114:117], v[144:147], v[202:205], v[114:117]
	v_mfma_f32_16x16x32_bf16 v[106:109], v[162:165], v[202:205], v[106:109]
	v_mfma_f32_16x16x32_bf16 v[98:101], v[144:147], v[210:213], v[98:101]
	v_mfma_f32_16x16x32_bf16 v[90:93], v[162:165], v[210:213], v[90:93]
	v_mfma_f32_16x16x32_bf16 v[82:85], v[144:147], v[218:221], v[82:85]
	v_mfma_f32_16x16x32_bf16 v[74:77], v[162:165], v[218:221], v[74:77]
	v_mfma_f32_16x16x32_bf16 v[126:129], v[158:161], v[198:201], v[126:129]
	v_mfma_f32_16x16x32_bf16 v[122:125], v[166:169], v[198:201], v[122:125]
	v_mfma_f32_16x16x32_bf16 v[114:117], v[158:161], v[206:209], v[114:117]
	v_mfma_f32_16x16x32_bf16 v[106:109], v[166:169], v[206:209], v[106:109]
	v_mfma_f32_16x16x32_bf16 v[98:101], v[158:161], v[214:217], v[98:101]
	v_mfma_f32_16x16x32_bf16 v[90:93], v[166:169], v[214:217], v[90:93]
	v_mfma_f32_16x16x32_bf16 v[82:85], v[158:161], v[222:225], v[82:85]
	v_mfma_f32_16x16x32_bf16 v[74:77], v[166:169], v[222:225], v[74:77]
	s_setprio 0
	s_setprio 1
	v_mfma_f32_16x16x32_bf16 v[118:121], v[170:173], v[194:197], v[118:121]
	v_mfma_f32_16x16x32_bf16 v[110:113], v[180:183], v[194:197], v[110:113]
	v_mfma_f32_16x16x32_bf16 v[102:105], v[170:173], v[202:205], v[102:105]
	v_mfma_f32_16x16x32_bf16 v[94:97], v[180:183], v[202:205], v[94:97]
	v_mfma_f32_16x16x32_bf16 v[86:89], v[170:173], v[210:213], v[86:89]
	v_mfma_f32_16x16x32_bf16 v[78:81], v[180:183], v[210:213], v[78:81]
	v_mfma_f32_16x16x32_bf16 v[70:73], v[170:173], v[218:221], v[70:73]
	v_mfma_f32_16x16x32_bf16 v[66:69], v[180:183], v[218:221], v[66:69]
	v_mfma_f32_16x16x32_bf16 v[118:121], v[174:177], v[198:201], v[118:121]
	v_mfma_f32_16x16x32_bf16 v[110:113], v[190:193], v[198:201], v[110:113]
	v_mfma_f32_16x16x32_bf16 v[102:105], v[174:177], v[206:209], v[102:105]
	v_mfma_f32_16x16x32_bf16 v[94:97], v[190:193], v[206:209], v[94:97]
	v_mfma_f32_16x16x32_bf16 v[86:89], v[174:177], v[214:217], v[86:89]
	v_mfma_f32_16x16x32_bf16 v[78:81], v[190:193], v[214:217], v[78:81]
	v_mfma_f32_16x16x32_bf16 v[70:73], v[174:177], v[222:225], v[70:73]
	v_mfma_f32_16x16x32_bf16 v[66:69], v[190:193], v[222:225], v[66:69]
	s_barrier
	s_setprio 0
	s_add_i32 s58, s80, s60
	s_mov_b32 m0, s58
	ds_read_b128 v[194:197], v143 offset:49152
	ds_read_b128 v[198:201], v143 offset:50176
	ds_read_b128 v[202:205], v143 offset:51200
	ds_read_b128 v[206:209], v143 offset:52224
	ds_read_b128 v[210:213], v143 offset:53248
	ds_read_b128 v[214:217], v143 offset:54272
	ds_read_b128 v[218:221], v143 offset:55296
	ds_read_b128 v[222:225], v143 offset:56320
	global_load_lds_dwordx4 v152, s[98:99]
	s_add_i32 m0, s58, 0x2000
	s_add_u32 s56, s56, 0x80080
	s_addc_u32 s57, s57, 0
	s_add_i32 s58, s81, s60
	global_load_lds_dwordx4 v156, s[98:99]
	s_mov_b32 m0, s58
	s_nop 0
	global_load_lds_dwordx4 v152, s[56:57]
	s_add_i32 m0, s58, 0x2000
	s_nop 0
	global_load_lds_dwordx4 v156, s[56:57]
	s_mov_b32 m0, s65
	s_nop 0
	global_load_lds_dwordx4 v150, s[100:101]
	s_mov_b32 m0, s66
	s_nop 0
	global_load_lds_dwordx4 v154, s[100:101]
	s_waitcnt vmcnt(8)
	s_waitcnt lgkmcnt(0)
	s_setprio 1
	s_barrier
	v_mfma_f32_16x16x32_bf16 v[62:65], v[144:147], v[194:197], v[62:65]
	v_mfma_f32_16x16x32_bf16 v[58:61], v[162:165], v[194:197], v[58:61]
	v_mfma_f32_16x16x32_bf16 v[50:53], v[144:147], v[202:205], v[50:53]
	v_mfma_f32_16x16x32_bf16 v[42:45], v[162:165], v[202:205], v[42:45]
	v_mfma_f32_16x16x32_bf16 v[34:37], v[144:147], v[210:213], v[34:37]
	v_mfma_f32_16x16x32_bf16 v[26:29], v[162:165], v[210:213], v[26:29]
	v_mfma_f32_16x16x32_bf16 v[18:21], v[144:147], v[218:221], v[18:21]
	v_mfma_f32_16x16x32_bf16 v[10:13], v[162:165], v[218:221], v[10:13]
	v_mfma_f32_16x16x32_bf16 v[62:65], v[158:161], v[198:201], v[62:65]
	v_mfma_f32_16x16x32_bf16 v[58:61], v[166:169], v[198:201], v[58:61]
	v_mfma_f32_16x16x32_bf16 v[50:53], v[158:161], v[206:209], v[50:53]
	v_mfma_f32_16x16x32_bf16 v[42:45], v[166:169], v[206:209], v[42:45]
	v_mfma_f32_16x16x32_bf16 v[34:37], v[158:161], v[214:217], v[34:37]
	v_mfma_f32_16x16x32_bf16 v[26:29], v[166:169], v[214:217], v[26:29]
	v_mfma_f32_16x16x32_bf16 v[18:21], v[158:161], v[222:225], v[18:21]
	v_mfma_f32_16x16x32_bf16 v[10:13], v[166:169], v[222:225], v[10:13]
	s_setprio 0
	s_setprio 1
	v_mfma_f32_16x16x32_bf16 v[54:57], v[170:173], v[194:197], v[54:57]
	v_mfma_f32_16x16x32_bf16 v[46:49], v[180:183], v[194:197], v[46:49]
	v_mfma_f32_16x16x32_bf16 v[38:41], v[170:173], v[202:205], v[38:41]
	v_mfma_f32_16x16x32_bf16 v[30:33], v[180:183], v[202:205], v[30:33]
	v_mfma_f32_16x16x32_bf16 v[22:25], v[170:173], v[210:213], v[22:25]
	v_mfma_f32_16x16x32_bf16 v[14:17], v[180:183], v[210:213], v[14:17]
	v_mfma_f32_16x16x32_bf16 v[6:9], v[170:173], v[218:221], v[6:9]
	v_mfma_f32_16x16x32_bf16 v[2:5], v[180:183], v[218:221], v[2:5]
	v_mfma_f32_16x16x32_bf16 v[54:57], v[174:177], v[198:201], v[54:57]
	v_mfma_f32_16x16x32_bf16 v[46:49], v[190:193], v[198:201], v[46:49]
	v_mfma_f32_16x16x32_bf16 v[38:41], v[174:177], v[206:209], v[38:41]
	v_mfma_f32_16x16x32_bf16 v[30:33], v[190:193], v[206:209], v[30:33]
	v_mfma_f32_16x16x32_bf16 v[22:25], v[174:177], v[214:217], v[22:25]
	v_mfma_f32_16x16x32_bf16 v[14:17], v[190:193], v[214:217], v[14:17]
	v_mfma_f32_16x16x32_bf16 v[6:9], v[174:177], v[222:225], v[6:9]
	v_mfma_f32_16x16x32_bf16 v[2:5], v[190:193], v[222:225], v[2:5]
	s_barrier
	s_setprio 0
	s_add_i32 s79, s79, 2
	s_add_u32 s54, s54, 0x100
	s_addc_u32 s55, s55, 0
	s_add_u32 s77, s77, 0x100
	s_addc_u32 s78, s78, 0
	s_cmp_gt_u32 s79, 29
.LBB0_701:
	ds_read_b128 v[144:147], v141
	ds_read_b128 v[158:161], v141 offset:1024
	ds_read_b128 v[162:165], v141 offset:2048
	ds_read_b128 v[166:169], v141 offset:3072
	ds_read_b128 v[170:173], v142
	ds_read_b128 v[174:177], v142 offset:1024
	ds_read_b128 v[180:183], v142 offset:2048
	ds_read_b128 v[190:193], v142 offset:3072
	s_add_u32 s56, s54, 0xfff80080
	s_addc_u32 s57, s55, -1
	s_cmp_eq_u32 s79, 28
	s_cselect_b32 s59, s37, s57
	s_cselect_b32 s58, s75, s56
	s_cselect_b32 s57, s35, s78
	s_cselect_b32 s56, s76, s77
	s_add_i32 m0, s53, 0xc000
	ds_read_b128 v[194:197], v143
	ds_read_b128 v[198:201], v143 offset:1024
	ds_read_b128 v[202:205], v143 offset:2048
	ds_read_b128 v[206:209], v143 offset:3072
	ds_read_b128 v[210:213], v143 offset:4096
	ds_read_b128 v[214:217], v143 offset:5120
	ds_read_b128 v[218:221], v143 offset:6144
	ds_read_b128 v[222:225], v143 offset:7168
	global_load_lds_dwordx4 v130, s[54:55]
	s_add_i32 m0, s53, 0xe000
	s_nop 0
	global_load_lds_dwordx4 v132, s[54:55]
	s_waitcnt vmcnt(8)
	s_waitcnt lgkmcnt(0)
	s_setprio 1
	s_barrier
	v_mfma_f32_16x16x32_bf16 v[126:129], v[144:147], v[194:197], v[126:129]
	v_mfma_f32_16x16x32_bf16 v[122:125], v[162:165], v[194:197], v[122:125]
	v_mfma_f32_16x16x32_bf16 v[114:117], v[144:147], v[202:205], v[114:117]
	v_mfma_f32_16x16x32_bf16 v[106:109], v[162:165], v[202:205], v[106:109]
	v_mfma_f32_16x16x32_bf16 v[98:101], v[144:147], v[210:213], v[98:101]
	v_mfma_f32_16x16x32_bf16 v[90:93], v[162:165], v[210:213], v[90:93]
	v_mfma_f32_16x16x32_bf16 v[82:85], v[144:147], v[218:221], v[82:85]
	v_mfma_f32_16x16x32_bf16 v[74:77], v[162:165], v[218:221], v[74:77]
	v_mfma_f32_16x16x32_bf16 v[126:129], v[158:161], v[198:201], v[126:129]
	v_mfma_f32_16x16x32_bf16 v[122:125], v[166:169], v[198:201], v[122:125]
	v_mfma_f32_16x16x32_bf16 v[114:117], v[158:161], v[206:209], v[114:117]
	v_mfma_f32_16x16x32_bf16 v[106:109], v[166:169], v[206:209], v[106:109]
	v_mfma_f32_16x16x32_bf16 v[98:101], v[158:161], v[214:217], v[98:101]
	v_mfma_f32_16x16x32_bf16 v[90:93], v[166:169], v[214:217], v[90:93]
	v_mfma_f32_16x16x32_bf16 v[82:85], v[158:161], v[222:225], v[82:85]
	v_mfma_f32_16x16x32_bf16 v[74:77], v[166:169], v[222:225], v[74:77]
	s_setprio 0
	s_setprio 1
	v_mfma_f32_16x16x32_bf16 v[118:121], v[170:173], v[194:197], v[118:121]
	v_mfma_f32_16x16x32_bf16 v[110:113], v[180:183], v[194:197], v[110:113]
	v_mfma_f32_16x16x32_bf16 v[102:105], v[170:173], v[202:205], v[102:105]
	v_mfma_f32_16x16x32_bf16 v[94:97], v[180:183], v[202:205], v[94:97]
	v_mfma_f32_16x16x32_bf16 v[86:89], v[170:173], v[210:213], v[86:89]
	v_mfma_f32_16x16x32_bf16 v[78:81], v[180:183], v[210:213], v[78:81]
	v_mfma_f32_16x16x32_bf16 v[70:73], v[170:173], v[218:221], v[70:73]
	v_mfma_f32_16x16x32_bf16 v[66:69], v[180:183], v[218:221], v[66:69]
	v_mfma_f32_16x16x32_bf16 v[118:121], v[174:177], v[198:201], v[118:121]
	v_mfma_f32_16x16x32_bf16 v[110:113], v[190:193], v[198:201], v[110:113]
	v_mfma_f32_16x16x32_bf16 v[102:105], v[174:177], v[206:209], v[102:105]
	v_mfma_f32_16x16x32_bf16 v[94:97], v[190:193], v[206:209], v[94:97]
	v_mfma_f32_16x16x32_bf16 v[86:89], v[174:177], v[214:217], v[86:89]
	v_mfma_f32_16x16x32_bf16 v[78:81], v[190:193], v[214:217], v[78:81]
	v_mfma_f32_16x16x32_bf16 v[70:73], v[174:177], v[222:225], v[70:73]
	v_mfma_f32_16x16x32_bf16 v[66:69], v[190:193], v[222:225], v[66:69]
	s_barrier
	s_setprio 0
	s_add_i32 s80, s68, s60
	s_add_u32 s98, s56, 0x80
	s_addc_u32 s99, s57, 0
	s_mov_b32 m0, s80
	ds_read_b128 v[194:197], v143 offset:16384
	ds_read_b128 v[198:201], v143 offset:17408
	ds_read_b128 v[202:205], v143 offset:18432
	ds_read_b128 v[206:209], v143 offset:19456
	ds_read_b128 v[210:213], v143 offset:20480
	ds_read_b128 v[214:217], v143 offset:21504
	ds_read_b128 v[218:221], v143 offset:22528
	ds_read_b128 v[222:225], v143 offset:23552
	global_load_lds_dwordx4 v152, s[56:57]
	s_add_i32 m0, s80, 0x2000
	s_add_u32 s80, s56, 0x80000
	s_addc_u32 s81, s57, 0
	s_add_i32 s82, s69, s60
	global_load_lds_dwordx4 v156, s[56:57]
	s_mov_b32 m0, s82
	s_nop 0
	global_load_lds_dwordx4 v152, s[80:81]
	s_add_i32 m0, s82, 0x2000
	s_nop 0
	global_load_lds_dwordx4 v156, s[80:81]
	s_add_u32 s100, s58, 0x80
	s_addc_u32 s101, s59, 0
	s_mov_b32 m0, s53
	s_nop 0
	global_load_lds_dwordx4 v150, s[58:59]
	s_mov_b32 m0, s61
	s_nop 0
	global_load_lds_dwordx4 v154, s[58:59]
	s_waitcnt vmcnt(8)
	s_waitcnt lgkmcnt(0)
	s_setprio 1
	s_barrier
	v_mfma_f32_16x16x32_bf16 v[62:65], v[144:147], v[194:197], v[62:65]
	v_mfma_f32_16x16x32_bf16 v[58:61], v[162:165], v[194:197], v[58:61]
	v_mfma_f32_16x16x32_bf16 v[50:53], v[144:147], v[202:205], v[50:53]
	v_mfma_f32_16x16x32_bf16 v[42:45], v[162:165], v[202:205], v[42:45]
	v_mfma_f32_16x16x32_bf16 v[34:37], v[144:147], v[210:213], v[34:37]
	v_mfma_f32_16x16x32_bf16 v[26:29], v[162:165], v[210:213], v[26:29]
	v_mfma_f32_16x16x32_bf16 v[18:21], v[144:147], v[218:221], v[18:21]
	v_mfma_f32_16x16x32_bf16 v[10:13], v[162:165], v[218:221], v[10:13]
	v_mfma_f32_16x16x32_bf16 v[62:65], v[158:161], v[198:201], v[62:65]
	v_mfma_f32_16x16x32_bf16 v[58:61], v[166:169], v[198:201], v[58:61]
	v_mfma_f32_16x16x32_bf16 v[50:53], v[158:161], v[206:209], v[50:53]
	v_mfma_f32_16x16x32_bf16 v[42:45], v[166:169], v[206:209], v[42:45]
	v_mfma_f32_16x16x32_bf16 v[34:37], v[158:161], v[214:217], v[34:37]
	v_mfma_f32_16x16x32_bf16 v[26:29], v[166:169], v[214:217], v[26:29]
	v_mfma_f32_16x16x32_bf16 v[18:21], v[158:161], v[222:225], v[18:21]
	v_mfma_f32_16x16x32_bf16 v[10:13], v[166:169], v[222:225], v[10:13]
	s_setprio 0
	s_setprio 1
	v_mfma_f32_16x16x32_bf16 v[54:57], v[170:173], v[194:197], v[54:57]
	v_mfma_f32_16x16x32_bf16 v[46:49], v[180:183], v[194:197], v[46:49]
	v_mfma_f32_16x16x32_bf16 v[38:41], v[170:173], v[202:205], v[38:41]
	v_mfma_f32_16x16x32_bf16 v[30:33], v[180:183], v[202:205], v[30:33]
	v_mfma_f32_16x16x32_bf16 v[22:25], v[170:173], v[210:213], v[22:25]
	v_mfma_f32_16x16x32_bf16 v[14:17], v[180:183], v[210:213], v[14:17]
	v_mfma_f32_16x16x32_bf16 v[6:9], v[170:173], v[218:221], v[6:9]
	v_mfma_f32_16x16x32_bf16 v[2:5], v[180:183], v[218:221], v[2:5]
	v_mfma_f32_16x16x32_bf16 v[54:57], v[174:177], v[198:201], v[54:57]
	v_mfma_f32_16x16x32_bf16 v[46:49], v[190:193], v[198:201], v[46:49]
	v_mfma_f32_16x16x32_bf16 v[38:41], v[174:177], v[206:209], v[38:41]
	v_mfma_f32_16x16x32_bf16 v[30:33], v[190:193], v[206:209], v[30:33]
	v_mfma_f32_16x16x32_bf16 v[22:25], v[174:177], v[214:217], v[22:25]
	v_mfma_f32_16x16x32_bf16 v[14:17], v[190:193], v[214:217], v[14:17]
	v_mfma_f32_16x16x32_bf16 v[6:9], v[174:177], v[222:225], v[6:9]
	v_mfma_f32_16x16x32_bf16 v[2:5], v[190:193], v[222:225], v[2:5]
	s_barrier
	s_setprio 0
	s_add_i32 s80, 0, 0x18000
	v_add_u32_e32 v1, s80, v139
	s_add_i32 s81, 0, 0x1c000
	ds_read_b128 v[144:147], v1
	ds_read_b128 v[158:161], v1 offset:1024
	ds_read_b128 v[162:165], v1 offset:2048
	ds_read_b128 v[166:169], v1 offset:3072
	v_add_u32_e32 v1, s81, v139
	ds_read_b128 v[170:173], v1
	ds_read_b128 v[174:177], v1 offset:1024
	ds_read_b128 v[180:183], v1 offset:2048
	ds_read_b128 v[190:193], v1 offset:3072
	s_add_u32 s58, s58, 0x80000
	s_addc_u32 s59, s59, 0
	s_mov_b32 m0, s62
	ds_read_b128 v[194:197], v143 offset:32768
	ds_read_b128 v[198:201], v143 offset:33792
	ds_read_b128 v[202:205], v143 offset:34816
	ds_read_b128 v[206:209], v143 offset:35840
	ds_read_b128 v[210:213], v143 offset:36864
	ds_read_b128 v[214:217], v143 offset:37888
	ds_read_b128 v[218:221], v143 offset:38912
	ds_read_b128 v[222:225], v143 offset:39936
	global_load_lds_dwordx4 v150, s[58:59]
	s_mov_b32 m0, s63
	s_nop 0
	global_load_lds_dwordx4 v154, s[58:59]
	s_waitcnt vmcnt(8)
	s_waitcnt lgkmcnt(0)
	s_setprio 1
	s_barrier
	v_mfma_f32_16x16x32_bf16 v[126:129], v[144:147], v[194:197], v[126:129]
	v_mfma_f32_16x16x32_bf16 v[122:125], v[162:165], v[194:197], v[122:125]
	v_mfma_f32_16x16x32_bf16 v[114:117], v[144:147], v[202:205], v[114:117]
	v_mfma_f32_16x16x32_bf16 v[106:109], v[162:165], v[202:205], v[106:109]
	v_mfma_f32_16x16x32_bf16 v[98:101], v[144:147], v[210:213], v[98:101]
	v_mfma_f32_16x16x32_bf16 v[90:93], v[162:165], v[210:213], v[90:93]
	v_mfma_f32_16x16x32_bf16 v[82:85], v[144:147], v[218:221], v[82:85]
	v_mfma_f32_16x16x32_bf16 v[74:77], v[162:165], v[218:221], v[74:77]
	v_mfma_f32_16x16x32_bf16 v[126:129], v[158:161], v[198:201], v[126:129]
	v_mfma_f32_16x16x32_bf16 v[122:125], v[166:169], v[198:201], v[122:125]
	v_mfma_f32_16x16x32_bf16 v[114:117], v[158:161], v[206:209], v[114:117]
	v_mfma_f32_16x16x32_bf16 v[106:109], v[166:169], v[206:209], v[106:109]
	v_mfma_f32_16x16x32_bf16 v[98:101], v[158:161], v[214:217], v[98:101]
	v_mfma_f32_16x16x32_bf16 v[90:93], v[166:169], v[214:217], v[90:93]
	v_mfma_f32_16x16x32_bf16 v[82:85], v[158:161], v[222:225], v[82:85]
	v_mfma_f32_16x16x32_bf16 v[74:77], v[166:169], v[222:225], v[74:77]
	s_setprio 0
	s_setprio 1
	v_mfma_f32_16x16x32_bf16 v[118:121], v[170:173], v[194:197], v[118:121]
	v_mfma_f32_16x16x32_bf16 v[110:113], v[180:183], v[194:197], v[110:113]
	v_mfma_f32_16x16x32_bf16 v[102:105], v[170:173], v[202:205], v[102:105]
	v_mfma_f32_16x16x32_bf16 v[94:97], v[180:183], v[202:205], v[94:97]
	v_mfma_f32_16x16x32_bf16 v[86:89], v[170:173], v[210:213], v[86:89]
	v_mfma_f32_16x16x32_bf16 v[78:81], v[180:183], v[210:213], v[78:81]
	v_mfma_f32_16x16x32_bf16 v[70:73], v[170:173], v[218:221], v[70:73]
	v_mfma_f32_16x16x32_bf16 v[66:69], v[180:183], v[218:221], v[66:69]
	v_mfma_f32_16x16x32_bf16 v[118:121], v[174:177], v[198:201], v[118:121]
	v_mfma_f32_16x16x32_bf16 v[110:113], v[190:193], v[198:201], v[110:113]
	v_mfma_f32_16x16x32_bf16 v[102:105], v[174:177], v[206:209], v[102:105]
	v_mfma_f32_16x16x32_bf16 v[94:97], v[190:193], v[206:209], v[94:97]
	v_mfma_f32_16x16x32_bf16 v[86:89], v[174:177], v[214:217], v[86:89]
	v_mfma_f32_16x16x32_bf16 v[78:81], v[190:193], v[214:217], v[78:81]
	v_mfma_f32_16x16x32_bf16 v[70:73], v[174:177], v[222:225], v[70:73]
	v_mfma_f32_16x16x32_bf16 v[66:69], v[190:193], v[222:225], v[66:69]
	s_barrier
	s_setprio 0
	s_add_i32 s58, s80, s60
	s_mov_b32 m0, s58
	ds_read_b128 v[194:197], v143 offset:49152
	ds_read_b128 v[198:201], v143 offset:50176
	ds_read_b128 v[202:205], v143 offset:51200
	ds_read_b128 v[206:209], v143 offset:52224
	ds_read_b128 v[210:213], v143 offset:53248
	ds_read_b128 v[214:217], v143 offset:54272
	ds_read_b128 v[218:221], v143 offset:55296
	ds_read_b128 v[222:225], v143 offset:56320
	global_load_lds_dwordx4 v152, s[98:99]
	s_add_i32 m0, s58, 0x2000
	s_add_u32 s56, s56, 0x80080
	s_addc_u32 s57, s57, 0
	s_add_i32 s58, s81, s60
	global_load_lds_dwordx4 v156, s[98:99]
	s_mov_b32 m0, s58
	s_nop 0
	global_load_lds_dwordx4 v152, s[56:57]
	s_add_i32 m0, s58, 0x2000
	s_nop 0
	global_load_lds_dwordx4 v156, s[56:57]
	s_mov_b32 m0, s65
	s_nop 0
	global_load_lds_dwordx4 v150, s[100:101]
	s_mov_b32 m0, s66
	s_nop 0
	global_load_lds_dwordx4 v154, s[100:101]
	s_add_i32 s79, s79, 2
	s_add_u32 s54, s54, 0x100
	s_addc_u32 s55, s55, 0
	s_add_u32 s77, s77, 0x100
	s_addc_u32 s78, s78, 0
	s_cmp_gt_u32 s79, 29
	s_waitcnt vmcnt(8)
	s_waitcnt lgkmcnt(0)
	s_setprio 1
	s_barrier
	v_mfma_f32_16x16x32_bf16 v[62:65], v[144:147], v[194:197], v[62:65]
	v_mfma_f32_16x16x32_bf16 v[58:61], v[162:165], v[194:197], v[58:61]
	v_mfma_f32_16x16x32_bf16 v[50:53], v[144:147], v[202:205], v[50:53]
	v_mfma_f32_16x16x32_bf16 v[42:45], v[162:165], v[202:205], v[42:45]
	v_mfma_f32_16x16x32_bf16 v[34:37], v[144:147], v[210:213], v[34:37]
	v_mfma_f32_16x16x32_bf16 v[26:29], v[162:165], v[210:213], v[26:29]
	v_mfma_f32_16x16x32_bf16 v[18:21], v[144:147], v[218:221], v[18:21]
	v_mfma_f32_16x16x32_bf16 v[10:13], v[162:165], v[218:221], v[10:13]
	v_mfma_f32_16x16x32_bf16 v[62:65], v[158:161], v[198:201], v[62:65]
	v_mfma_f32_16x16x32_bf16 v[58:61], v[166:169], v[198:201], v[58:61]
	v_mfma_f32_16x16x32_bf16 v[50:53], v[158:161], v[206:209], v[50:53]
	v_mfma_f32_16x16x32_bf16 v[42:45], v[166:169], v[206:209], v[42:45]
	v_mfma_f32_16x16x32_bf16 v[34:37], v[158:161], v[214:217], v[34:37]
	v_mfma_f32_16x16x32_bf16 v[26:29], v[166:169], v[214:217], v[26:29]
	v_mfma_f32_16x16x32_bf16 v[18:21], v[158:161], v[222:225], v[18:21]
	v_mfma_f32_16x16x32_bf16 v[10:13], v[166:169], v[222:225], v[10:13]
	s_setprio 0
	s_setprio 1
	v_mfma_f32_16x16x32_bf16 v[54:57], v[170:173], v[194:197], v[54:57]
	v_mfma_f32_16x16x32_bf16 v[46:49], v[180:183], v[194:197], v[46:49]
	v_mfma_f32_16x16x32_bf16 v[38:41], v[170:173], v[202:205], v[38:41]
	v_mfma_f32_16x16x32_bf16 v[30:33], v[180:183], v[202:205], v[30:33]
	v_mfma_f32_16x16x32_bf16 v[22:25], v[170:173], v[210:213], v[22:25]
	v_mfma_f32_16x16x32_bf16 v[14:17], v[180:183], v[210:213], v[14:17]
	v_mfma_f32_16x16x32_bf16 v[6:9], v[170:173], v[218:221], v[6:9]
	v_mfma_f32_16x16x32_bf16 v[2:5], v[180:183], v[218:221], v[2:5]
	v_mfma_f32_16x16x32_bf16 v[54:57], v[174:177], v[198:201], v[54:57]
	v_mfma_f32_16x16x32_bf16 v[46:49], v[190:193], v[198:201], v[46:49]
	v_mfma_f32_16x16x32_bf16 v[38:41], v[174:177], v[206:209], v[38:41]
	v_mfma_f32_16x16x32_bf16 v[30:33], v[190:193], v[206:209], v[30:33]
	v_mfma_f32_16x16x32_bf16 v[22:25], v[174:177], v[214:217], v[22:25]
	v_mfma_f32_16x16x32_bf16 v[14:17], v[190:193], v[214:217], v[14:17]
	v_mfma_f32_16x16x32_bf16 v[6:9], v[174:177], v[222:225], v[6:9]
	v_mfma_f32_16x16x32_bf16 v[2:5], v[190:193], v[222:225], v[2:5]
	s_barrier
	s_setprio 0
	s_cbranch_scc0 .LBB0_701
	s_and_b64 vcc, exec, s[6:7]
	s_cbranch_vccz .LBB0_704
	s_barrier

.LBB0_715:
	s_add_u32 s2, s26, 0x11400000
	s_addc_u32 s3, s27, 0
	s_lshl_b32 s4, s4, 5
	s_and_b32 s12, s4, 0x60
	s_mov_b64 s[4:5], 0x80
	s_add_i32 m0, s53, 0x18000
	v_lshl_add_u64 v[8:9], v[8:9], 0, s[4:5]
	s_lshl_b32 s9, s8, 13
	s_waitcnt vmcnt(2)
	s_barrier
	global_load_lds_dwordx4 v[8:9], off
	v_lshl_add_u64 v[6:7], v[6:7], 0, s[4:5]
	s_add_i32 m0, s53, 0x1a000
	s_add_i32 s66, s53, 0x8000
	s_add_i32 s67, s53, 0xa000
	global_load_lds_dwordx4 v[6:7], off
	v_lshl_add_u64 v[2:3], v[2:3], 0, s[4:5]
	s_mov_b32 m0, s66
	s_add_u32 s10, s56, 0x80080
	global_load_lds_dwordx4 v[2:3], off
	v_lshl_add_u64 v[2:3], v[4:5], 0, s[4:5]
	s_mov_b32 m0, s67
	s_addc_u32 s11, s57, 0
	global_load_lds_dwordx4 v[2:3], off
	s_add_i32 m0, s53, 0x1c000
	s_nop 0
	global_load_lds_dwordx4 v152, s[10:11]
	s_add_i32 m0, s53, 0x1e000
	v_lshl_or_b32 v1, v189, 6, v137
	global_load_lds_dwordx4 v156, s[10:11]
	v_lshlrev_b32_e32 v2, 2, v189
	v_and_b32_e32 v2, 32, v2
	v_bitop3_b32 v1, v1, s9, v2 bitop3:0xde
	v_lshlrev_b32_e32 v2, 9, v0
	v_and_b32_e32 v2, 0x30000, v2
	v_lshlrev_b32_e32 v3, 12, v186
	v_or3_b32 v2, v184, v2, v3
	v_add_u32_e32 v130, v2, v185
	v_lshlrev_b32_e32 v2, 5, v188
	s_waitcnt vmcnt(6)
	s_cmpk_lt_u32 s7, 0x100
	v_and_b32_e32 v2, 0x70000, v2
	s_sext_i32_i8 s75, s6
	v_lshl_or_b32 v136, s12, 7, v136
	s_cselect_b64 s[6:7], -1, 0
	v_or3_b32 v2, v184, v2, v3
	s_add_i32 s69, 0, 0x10000
	s_add_i32 s70, 0, 0x14000
	v_lshl_or_b32 v138, s8, 6, v189
	s_ashr_i32 s68, s33, 31
	v_or_b32_e32 v137, s12, v187
	v_mov_b32_e32 v131, v153
	v_add_u32_e32 v132, v2, v185
	v_mov_b32_e32 v133, v153
	v_add_u32_e32 v139, s69, v136
	v_add_u32_e32 v140, s70, v136
	v_add_u32_e32 v141, 0, v1
	s_mov_b64 s[8:9], 0x100000
	s_mov_b32 s71, 0x100000
	s_mov_b64 s[10:11], 0x120000
	s_mov_b32 s72, 0x120000
	s_mov_b64 s[12:13], 0x140000
	s_mov_b32 s73, 0x140000
	s_mov_b64 s[14:15], 0x160000
	s_mov_b32 s74, 0x160000
	s_barrier
	s_branch .LBB0_718

.LBB0_724:
	s_ashr_i32 s37, s36, 31
	s_lshl_b64 s[40:41], s[36:37], 20
	s_add_u32 s40, s31, s40
	s_addc_u32 s41, s60, s41
	s_and_b64 s[42:43], s[16:17], exec
	s_cselect_b32 s37, s41, s55
	s_cselect_b32 s76, s40, s54
	s_ashr_i32 s35, s34, 31
	s_lshl_b64 s[42:43], s[34:35], 20
	s_add_u32 s42, s18, s42
	s_addc_u32 s43, s19, s43
	s_and_b64 s[58:59], s[16:17], exec
	s_cselect_b32 s35, s43, s57
	s_cselect_b32 s77, s42, s56
	s_add_u32 s54, s54, 0x80080
	s_addc_u32 s55, s55, 0
	s_add_u32 s78, s56, 0x100
	s_addc_u32 s79, s57, 0
	s_mov_b32 s80, -2
	ds_read_b128 v[142:145], v139
	ds_read_b128 v[146:149], v139 offset:1024
	ds_read_b128 v[158:161], v139 offset:2048
	ds_read_b128 v[162:165], v139 offset:3072
	ds_read_b128 v[166:169], v140
	ds_read_b128 v[170:173], v140 offset:1024
	ds_read_b128 v[174:177], v140 offset:2048
	ds_read_b128 v[180:183], v140 offset:3072
	s_add_u32 s56, s54, 0xfff80080
	s_addc_u32 s57, s55, -1
	s_cmp_eq_u32 s80, 28
	s_cselect_b32 s59, s37, s57
	s_cselect_b32 s58, s76, s56
	s_cselect_b32 s57, s35, s79
	s_cselect_b32 s56, s77, s78
	s_add_i32 m0, s53, 0xc000
	ds_read_b128 v[184:187], v141
	ds_read_b128 v[188:191], v141 offset:1024
	ds_read_b128 v[192:195], v141 offset:2048
	ds_read_b128 v[196:199], v141 offset:3072
	ds_read_b128 v[200:203], v141 offset:4096
	ds_read_b128 v[204:207], v141 offset:5120
	ds_read_b128 v[208:211], v141 offset:6144
	ds_read_b128 v[212:215], v141 offset:7168
	global_load_lds_dwordx4 v130, s[54:55]
	s_add_i32 m0, s53, 0xe000
	s_nop 0
	global_load_lds_dwordx4 v132, s[54:55]
	s_waitcnt vmcnt(8)
	s_waitcnt lgkmcnt(0)
	s_setprio 1
	s_barrier
	v_mfma_f32_16x16x32_bf16 v[126:129], v[142:145], v[184:187], 0
	v_mfma_f32_16x16x32_bf16 v[122:125], v[158:161], v[184:187], 0
	v_mfma_f32_16x16x32_bf16 v[114:117], v[142:145], v[192:195], 0
	v_mfma_f32_16x16x32_bf16 v[106:109], v[158:161], v[192:195], 0
	v_mfma_f32_16x16x32_bf16 v[98:101], v[142:145], v[200:203], 0
	v_mfma_f32_16x16x32_bf16 v[90:93], v[158:161], v[200:203], 0
	v_mfma_f32_16x16x32_bf16 v[82:85], v[142:145], v[208:211], 0
	v_mfma_f32_16x16x32_bf16 v[74:77], v[158:161], v[208:211], 0
	v_mfma_f32_16x16x32_bf16 v[126:129], v[146:149], v[188:191], v[126:129]
	v_mfma_f32_16x16x32_bf16 v[122:125], v[162:165], v[188:191], v[122:125]
	v_mfma_f32_16x16x32_bf16 v[114:117], v[146:149], v[196:199], v[114:117]
	v_mfma_f32_16x16x32_bf16 v[106:109], v[162:165], v[196:199], v[106:109]
	v_mfma_f32_16x16x32_bf16 v[98:101], v[146:149], v[204:207], v[98:101]
	v_mfma_f32_16x16x32_bf16 v[90:93], v[162:165], v[204:207], v[90:93]
	v_mfma_f32_16x16x32_bf16 v[82:85], v[146:149], v[212:215], v[82:85]
	v_mfma_f32_16x16x32_bf16 v[74:77], v[162:165], v[212:215], v[74:77]
	s_setprio 0
	s_setprio 1
	v_mfma_f32_16x16x32_bf16 v[118:121], v[166:169], v[184:187], 0
	v_mfma_f32_16x16x32_bf16 v[110:113], v[174:177], v[184:187], 0
	v_mfma_f32_16x16x32_bf16 v[102:105], v[166:169], v[192:195], 0
	v_mfma_f32_16x16x32_bf16 v[94:97], v[174:177], v[192:195], 0
	v_mfma_f32_16x16x32_bf16 v[86:89], v[166:169], v[200:203], 0
	v_mfma_f32_16x16x32_bf16 v[78:81], v[174:177], v[200:203], 0
	v_mfma_f32_16x16x32_bf16 v[70:73], v[166:169], v[208:211], 0
	v_mfma_f32_16x16x32_bf16 v[66:69], v[174:177], v[208:211], 0
	v_mfma_f32_16x16x32_bf16 v[118:121], v[170:173], v[188:191], v[118:121]
	v_mfma_f32_16x16x32_bf16 v[110:113], v[180:183], v[188:191], v[110:113]
	v_mfma_f32_16x16x32_bf16 v[102:105], v[170:173], v[196:199], v[102:105]
	v_mfma_f32_16x16x32_bf16 v[94:97], v[180:183], v[196:199], v[94:97]
	v_mfma_f32_16x16x32_bf16 v[86:89], v[170:173], v[204:207], v[86:89]
	v_mfma_f32_16x16x32_bf16 v[78:81], v[180:183], v[204:207], v[78:81]
	v_mfma_f32_16x16x32_bf16 v[70:73], v[170:173], v[212:215], v[70:73]
	v_mfma_f32_16x16x32_bf16 v[66:69], v[180:183], v[212:215], v[66:69]
	s_barrier
	s_setprio 0
	s_add_i32 s81, s69, s61
	s_add_u32 s98, s56, 0x80
	s_addc_u32 s99, s57, 0
	s_mov_b32 m0, s81
	ds_read_b128 v[184:187], v141 offset:16384
	ds_read_b128 v[188:191], v141 offset:17408
	ds_read_b128 v[192:195], v141 offset:18432
	ds_read_b128 v[196:199], v141 offset:19456
	ds_read_b128 v[200:203], v141 offset:20480
	ds_read_b128 v[204:207], v141 offset:21504
	ds_read_b128 v[208:211], v141 offset:22528
	ds_read_b128 v[212:215], v141 offset:23552
	global_load_lds_dwordx4 v152, s[56:57]
	s_add_i32 m0, s81, 0x2000
	s_add_u32 s82, s56, 0x80000
	s_addc_u32 s83, s57, 0
	s_add_i32 s81, s70, s61
	global_load_lds_dwordx4 v156, s[56:57]
	s_mov_b32 m0, s81
	s_nop 0
	global_load_lds_dwordx4 v152, s[82:83]
	s_add_i32 m0, s81, 0x2000
	s_nop 0
	global_load_lds_dwordx4 v156, s[82:83]
	s_add_u32 s100, s58, 0x80
	s_addc_u32 s101, s59, 0
	s_mov_b32 m0, s53
	s_nop 0
	global_load_lds_dwordx4 v150, s[58:59]
	s_mov_b32 m0, s62
	s_nop 0
	global_load_lds_dwordx4 v154, s[58:59]
	s_waitcnt vmcnt(8)
	s_waitcnt lgkmcnt(0)
	s_setprio 1
	s_barrier
	v_mfma_f32_16x16x32_bf16 v[62:65], v[142:145], v[184:187], 0
	v_mfma_f32_16x16x32_bf16 v[58:61], v[158:161], v[184:187], 0
	v_mfma_f32_16x16x32_bf16 v[50:53], v[142:145], v[192:195], 0
	v_mfma_f32_16x16x32_bf16 v[42:45], v[158:161], v[192:195], 0
	v_mfma_f32_16x16x32_bf16 v[34:37], v[142:145], v[200:203], 0
	v_mfma_f32_16x16x32_bf16 v[26:29], v[158:161], v[200:203], 0
	v_mfma_f32_16x16x32_bf16 v[18:21], v[142:145], v[208:211], 0
	v_mfma_f32_16x16x32_bf16 v[10:13], v[158:161], v[208:211], 0
	v_mfma_f32_16x16x32_bf16 v[62:65], v[146:149], v[188:191], v[62:65]
	v_mfma_f32_16x16x32_bf16 v[58:61], v[162:165], v[188:191], v[58:61]
	v_mfma_f32_16x16x32_bf16 v[50:53], v[146:149], v[196:199], v[50:53]
	v_mfma_f32_16x16x32_bf16 v[42:45], v[162:165], v[196:199], v[42:45]
	v_mfma_f32_16x16x32_bf16 v[34:37], v[146:149], v[204:207], v[34:37]
	v_mfma_f32_16x16x32_bf16 v[26:29], v[162:165], v[204:207], v[26:29]
	v_mfma_f32_16x16x32_bf16 v[18:21], v[146:149], v[212:215], v[18:21]
	v_mfma_f32_16x16x32_bf16 v[10:13], v[162:165], v[212:215], v[10:13]
	s_setprio 0
	s_setprio 1
	v_mfma_f32_16x16x32_bf16 v[54:57], v[166:169], v[184:187], 0
	v_mfma_f32_16x16x32_bf16 v[46:49], v[174:177], v[184:187], 0
	v_mfma_f32_16x16x32_bf16 v[38:41], v[166:169], v[192:195], 0
	v_mfma_f32_16x16x32_bf16 v[30:33], v[174:177], v[192:195], 0
	v_mfma_f32_16x16x32_bf16 v[22:25], v[166:169], v[200:203], 0
	v_mfma_f32_16x16x32_bf16 v[14:17], v[174:177], v[200:203], 0
	v_mfma_f32_16x16x32_bf16 v[6:9], v[166:169], v[208:211], 0
	v_mfma_f32_16x16x32_bf16 v[2:5], v[174:177], v[208:211], 0
	v_mfma_f32_16x16x32_bf16 v[54:57], v[170:173], v[188:191], v[54:57]
	v_mfma_f32_16x16x32_bf16 v[46:49], v[180:183], v[188:191], v[46:49]
	v_mfma_f32_16x16x32_bf16 v[38:41], v[170:173], v[196:199], v[38:41]
	v_mfma_f32_16x16x32_bf16 v[30:33], v[180:183], v[196:199], v[30:33]
	v_mfma_f32_16x16x32_bf16 v[22:25], v[170:173], v[204:207], v[22:25]
	v_mfma_f32_16x16x32_bf16 v[14:17], v[180:183], v[204:207], v[14:17]
	v_mfma_f32_16x16x32_bf16 v[6:9], v[170:173], v[212:215], v[6:9]
	v_mfma_f32_16x16x32_bf16 v[2:5], v[180:183], v[212:215], v[2:5]
	s_barrier
	s_setprio 0
	s_add_i32 s81, 0, 0x18000
	v_add_u32_e32 v1, s81, v136
	s_add_i32 s82, 0, 0x1c000
	ds_read_b128 v[142:145], v1
	ds_read_b128 v[146:149], v1 offset:1024
	ds_read_b128 v[158:161], v1 offset:2048
	ds_read_b128 v[162:165], v1 offset:3072
	v_add_u32_e32 v1, s82, v136
	ds_read_b128 v[166:169], v1
	ds_read_b128 v[170:173], v1 offset:1024
	ds_read_b128 v[174:177], v1 offset:2048
	ds_read_b128 v[180:183], v1 offset:3072
	s_add_u32 s58, s58, 0x80000
	s_addc_u32 s59, s59, 0
	s_mov_b32 m0, s63
	ds_read_b128 v[184:187], v141 offset:32768
	ds_read_b128 v[188:191], v141 offset:33792
	ds_read_b128 v[192:195], v141 offset:34816
	ds_read_b128 v[196:199], v141 offset:35840
	ds_read_b128 v[200:203], v141 offset:36864
	ds_read_b128 v[204:207], v141 offset:37888
	ds_read_b128 v[208:211], v141 offset:38912
	ds_read_b128 v[212:215], v141 offset:39936
	global_load_lds_dwordx4 v150, s[58:59]
	s_mov_b32 m0, s64
	s_nop 0
	global_load_lds_dwordx4 v154, s[58:59]
	s_waitcnt vmcnt(8)
	s_waitcnt lgkmcnt(0)
	s_setprio 1
	s_barrier
	v_mfma_f32_16x16x32_bf16 v[126:129], v[142:145], v[184:187], v[126:129]
	v_mfma_f32_16x16x32_bf16 v[122:125], v[158:161], v[184:187], v[122:125]
	v_mfma_f32_16x16x32_bf16 v[114:117], v[142:145], v[192:195], v[114:117]
	v_mfma_f32_16x16x32_bf16 v[106:109], v[158:161], v[192:195], v[106:109]
	v_mfma_f32_16x16x32_bf16 v[98:101], v[142:145], v[200:203], v[98:101]
	v_mfma_f32_16x16x32_bf16 v[90:93], v[158:161], v[200:203], v[90:93]
	v_mfma_f32_16x16x32_bf16 v[82:85], v[142:145], v[208:211], v[82:85]
	v_mfma_f32_16x16x32_bf16 v[74:77], v[158:161], v[208:211], v[74:77]
	v_mfma_f32_16x16x32_bf16 v[126:129], v[146:149], v[188:191], v[126:129]
	v_mfma_f32_16x16x32_bf16 v[122:125], v[162:165], v[188:191], v[122:125]
	v_mfma_f32_16x16x32_bf16 v[114:117], v[146:149], v[196:199], v[114:117]
	v_mfma_f32_16x16x32_bf16 v[106:109], v[162:165], v[196:199], v[106:109]
	v_mfma_f32_16x16x32_bf16 v[98:101], v[146:149], v[204:207], v[98:101]
	v_mfma_f32_16x16x32_bf16 v[90:93], v[162:165], v[204:207], v[90:93]
	v_mfma_f32_16x16x32_bf16 v[82:85], v[146:149], v[212:215], v[82:85]
	v_mfma_f32_16x16x32_bf16 v[74:77], v[162:165], v[212:215], v[74:77]
	s_setprio 0
	s_setprio 1
	v_mfma_f32_16x16x32_bf16 v[118:121], v[166:169], v[184:187], v[118:121]
	v_mfma_f32_16x16x32_bf16 v[110:113], v[174:177], v[184:187], v[110:113]
	v_mfma_f32_16x16x32_bf16 v[102:105], v[166:169], v[192:195], v[102:105]
	v_mfma_f32_16x16x32_bf16 v[94:97], v[174:177], v[192:195], v[94:97]
	v_mfma_f32_16x16x32_bf16 v[86:89], v[166:169], v[200:203], v[86:89]
	v_mfma_f32_16x16x32_bf16 v[78:81], v[174:177], v[200:203], v[78:81]
	v_mfma_f32_16x16x32_bf16 v[70:73], v[166:169], v[208:211], v[70:73]
	v_mfma_f32_16x16x32_bf16 v[66:69], v[174:177], v[208:211], v[66:69]
	v_mfma_f32_16x16x32_bf16 v[118:121], v[170:173], v[188:191], v[118:121]
	v_mfma_f32_16x16x32_bf16 v[110:113], v[180:183], v[188:191], v[110:113]
	v_mfma_f32_16x16x32_bf16 v[102:105], v[170:173], v[196:199], v[102:105]
	v_mfma_f32_16x16x32_bf16 v[94:97], v[180:183], v[196:199], v[94:97]
	v_mfma_f32_16x16x32_bf16 v[86:89], v[170:173], v[204:207], v[86:89]
	v_mfma_f32_16x16x32_bf16 v[78:81], v[180:183], v[204:207], v[78:81]
	v_mfma_f32_16x16x32_bf16 v[70:73], v[170:173], v[212:215], v[70:73]
	v_mfma_f32_16x16x32_bf16 v[66:69], v[180:183], v[212:215], v[66:69]
	s_barrier
	s_setprio 0
	s_add_i32 s58, s81, s61
	s_mov_b32 m0, s58
	ds_read_b128 v[184:187], v141 offset:49152
	ds_read_b128 v[188:191], v141 offset:50176
	ds_read_b128 v[192:195], v141 offset:51200
	ds_read_b128 v[196:199], v141 offset:52224
	ds_read_b128 v[200:203], v141 offset:53248
	ds_read_b128 v[204:207], v141 offset:54272
	ds_read_b128 v[208:211], v141 offset:55296
	ds_read_b128 v[212:215], v141 offset:56320
	global_load_lds_dwordx4 v152, s[98:99]
	s_add_i32 m0, s58, 0x2000
	s_add_u32 s56, s56, 0x80080
	s_addc_u32 s57, s57, 0
	s_add_i32 s58, s82, s61
	global_load_lds_dwordx4 v156, s[98:99]
	s_mov_b32 m0, s58
	s_nop 0
	global_load_lds_dwordx4 v152, s[56:57]
	s_add_i32 m0, s58, 0x2000
	s_nop 0
	global_load_lds_dwordx4 v156, s[56:57]
	s_mov_b32 m0, s66
	s_nop 0
	global_load_lds_dwordx4 v150, s[100:101]
	s_mov_b32 m0, s67
	s_nop 0
	global_load_lds_dwordx4 v154, s[100:101]
	s_waitcnt vmcnt(8)
	s_waitcnt lgkmcnt(0)
	s_setprio 1
	s_barrier
	v_mfma_f32_16x16x32_bf16 v[62:65], v[142:145], v[184:187], v[62:65]
	v_mfma_f32_16x16x32_bf16 v[58:61], v[158:161], v[184:187], v[58:61]
	v_mfma_f32_16x16x32_bf16 v[50:53], v[142:145], v[192:195], v[50:53]
	v_mfma_f32_16x16x32_bf16 v[42:45], v[158:161], v[192:195], v[42:45]
	v_mfma_f32_16x16x32_bf16 v[34:37], v[142:145], v[200:203], v[34:37]
	v_mfma_f32_16x16x32_bf16 v[26:29], v[158:161], v[200:203], v[26:29]
	v_mfma_f32_16x16x32_bf16 v[18:21], v[142:145], v[208:211], v[18:21]
	v_mfma_f32_16x16x32_bf16 v[10:13], v[158:161], v[208:211], v[10:13]
	v_mfma_f32_16x16x32_bf16 v[62:65], v[146:149], v[188:191], v[62:65]
	v_mfma_f32_16x16x32_bf16 v[58:61], v[162:165], v[188:191], v[58:61]
	v_mfma_f32_16x16x32_bf16 v[50:53], v[146:149], v[196:199], v[50:53]
	v_mfma_f32_16x16x32_bf16 v[42:45], v[162:165], v[196:199], v[42:45]
	v_mfma_f32_16x16x32_bf16 v[34:37], v[146:149], v[204:207], v[34:37]
	v_mfma_f32_16x16x32_bf16 v[26:29], v[162:165], v[204:207], v[26:29]
	v_mfma_f32_16x16x32_bf16 v[18:21], v[146:149], v[212:215], v[18:21]
	v_mfma_f32_16x16x32_bf16 v[10:13], v[162:165], v[212:215], v[10:13]
	s_setprio 0
	s_setprio 1
	v_mfma_f32_16x16x32_bf16 v[54:57], v[166:169], v[184:187], v[54:57]
	v_mfma_f32_16x16x32_bf16 v[46:49], v[174:177], v[184:187], v[46:49]
	v_mfma_f32_16x16x32_bf16 v[38:41], v[166:169], v[192:195], v[38:41]
	v_mfma_f32_16x16x32_bf16 v[30:33], v[174:177], v[192:195], v[30:33]
	v_mfma_f32_16x16x32_bf16 v[22:25], v[166:169], v[200:203], v[22:25]
	v_mfma_f32_16x16x32_bf16 v[14:17], v[174:177], v[200:203], v[14:17]
	v_mfma_f32_16x16x32_bf16 v[6:9], v[166:169], v[208:211], v[6:9]
	v_mfma_f32_16x16x32_bf16 v[2:5], v[174:177], v[208:211], v[2:5]
	v_mfma_f32_16x16x32_bf16 v[54:57], v[170:173], v[188:191], v[54:57]
	v_mfma_f32_16x16x32_bf16 v[46:49], v[180:183], v[188:191], v[46:49]
	v_mfma_f32_16x16x32_bf16 v[38:41], v[170:173], v[196:199], v[38:41]
	v_mfma_f32_16x16x32_bf16 v[30:33], v[180:183], v[196:199], v[30:33]
	v_mfma_f32_16x16x32_bf16 v[22:25], v[170:173], v[204:207], v[22:25]
	v_mfma_f32_16x16x32_bf16 v[14:17], v[180:183], v[204:207], v[14:17]
	v_mfma_f32_16x16x32_bf16 v[6:9], v[170:173], v[212:215], v[6:9]
	v_mfma_f32_16x16x32_bf16 v[2:5], v[180:183], v[212:215], v[2:5]
	s_barrier
	s_setprio 0
	s_add_i32 s80, s80, 2
	s_add_u32 s54, s54, 0x100
	s_addc_u32 s55, s55, 0
	s_add_u32 s78, s78, 0x100
	s_addc_u32 s79, s79, 0
	s_cmp_gt_u32 s80, 29
.LBB0_725:
	ds_read_b128 v[142:145], v139
	ds_read_b128 v[146:149], v139 offset:1024
	ds_read_b128 v[158:161], v139 offset:2048
	ds_read_b128 v[162:165], v139 offset:3072
	ds_read_b128 v[166:169], v140
	ds_read_b128 v[170:173], v140 offset:1024
	ds_read_b128 v[174:177], v140 offset:2048
	ds_read_b128 v[180:183], v140 offset:3072
	s_add_u32 s56, s54, 0xfff80080
	s_addc_u32 s57, s55, -1
	s_cmp_eq_u32 s80, 28
	s_cselect_b32 s59, s37, s57
	s_cselect_b32 s58, s76, s56
	s_cselect_b32 s57, s35, s79
	s_cselect_b32 s56, s77, s78
	s_add_i32 m0, s53, 0xc000
	ds_read_b128 v[184:187], v141
	ds_read_b128 v[188:191], v141 offset:1024
	ds_read_b128 v[192:195], v141 offset:2048
	ds_read_b128 v[196:199], v141 offset:3072
	ds_read_b128 v[200:203], v141 offset:4096
	ds_read_b128 v[204:207], v141 offset:5120
	ds_read_b128 v[208:211], v141 offset:6144
	ds_read_b128 v[212:215], v141 offset:7168
	global_load_lds_dwordx4 v130, s[54:55]
	s_add_i32 m0, s53, 0xe000
	s_nop 0
	global_load_lds_dwordx4 v132, s[54:55]
	s_waitcnt vmcnt(8)
	s_waitcnt lgkmcnt(0)
	s_setprio 1
	s_barrier
	v_mfma_f32_16x16x32_bf16 v[126:129], v[142:145], v[184:187], v[126:129]
	v_mfma_f32_16x16x32_bf16 v[122:125], v[158:161], v[184:187], v[122:125]
	v_mfma_f32_16x16x32_bf16 v[114:117], v[142:145], v[192:195], v[114:117]
	v_mfma_f32_16x16x32_bf16 v[106:109], v[158:161], v[192:195], v[106:109]
	v_mfma_f32_16x16x32_bf16 v[98:101], v[142:145], v[200:203], v[98:101]
	v_mfma_f32_16x16x32_bf16 v[90:93], v[158:161], v[200:203], v[90:93]
	v_mfma_f32_16x16x32_bf16 v[82:85], v[142:145], v[208:211], v[82:85]
	v_mfma_f32_16x16x32_bf16 v[74:77], v[158:161], v[208:211], v[74:77]
	v_mfma_f32_16x16x32_bf16 v[126:129], v[146:149], v[188:191], v[126:129]
	v_mfma_f32_16x16x32_bf16 v[122:125], v[162:165], v[188:191], v[122:125]
	v_mfma_f32_16x16x32_bf16 v[114:117], v[146:149], v[196:199], v[114:117]
	v_mfma_f32_16x16x32_bf16 v[106:109], v[162:165], v[196:199], v[106:109]
	v_mfma_f32_16x16x32_bf16 v[98:101], v[146:149], v[204:207], v[98:101]
	v_mfma_f32_16x16x32_bf16 v[90:93], v[162:165], v[204:207], v[90:93]
	v_mfma_f32_16x16x32_bf16 v[82:85], v[146:149], v[212:215], v[82:85]
	v_mfma_f32_16x16x32_bf16 v[74:77], v[162:165], v[212:215], v[74:77]
	s_setprio 0
	s_setprio 1
	v_mfma_f32_16x16x32_bf16 v[118:121], v[166:169], v[184:187], v[118:121]
	v_mfma_f32_16x16x32_bf16 v[110:113], v[174:177], v[184:187], v[110:113]
	v_mfma_f32_16x16x32_bf16 v[102:105], v[166:169], v[192:195], v[102:105]
	v_mfma_f32_16x16x32_bf16 v[94:97], v[174:177], v[192:195], v[94:97]
	v_mfma_f32_16x16x32_bf16 v[86:89], v[166:169], v[200:203], v[86:89]
	v_mfma_f32_16x16x32_bf16 v[78:81], v[174:177], v[200:203], v[78:81]
	v_mfma_f32_16x16x32_bf16 v[70:73], v[166:169], v[208:211], v[70:73]
	v_mfma_f32_16x16x32_bf16 v[66:69], v[174:177], v[208:211], v[66:69]
	v_mfma_f32_16x16x32_bf16 v[118:121], v[170:173], v[188:191], v[118:121]
	v_mfma_f32_16x16x32_bf16 v[110:113], v[180:183], v[188:191], v[110:113]
	v_mfma_f32_16x16x32_bf16 v[102:105], v[170:173], v[196:199], v[102:105]
	v_mfma_f32_16x16x32_bf16 v[94:97], v[180:183], v[196:199], v[94:97]
	v_mfma_f32_16x16x32_bf16 v[86:89], v[170:173], v[204:207], v[86:89]
	v_mfma_f32_16x16x32_bf16 v[78:81], v[180:183], v[204:207], v[78:81]
	v_mfma_f32_16x16x32_bf16 v[70:73], v[170:173], v[212:215], v[70:73]
	v_mfma_f32_16x16x32_bf16 v[66:69], v[180:183], v[212:215], v[66:69]
	s_barrier
	s_setprio 0
	s_add_i32 s81, s69, s61
	s_add_u32 s98, s56, 0x80
	s_addc_u32 s99, s57, 0
	s_mov_b32 m0, s81
	ds_read_b128 v[184:187], v141 offset:16384
	ds_read_b128 v[188:191], v141 offset:17408
	ds_read_b128 v[192:195], v141 offset:18432
	ds_read_b128 v[196:199], v141 offset:19456
	ds_read_b128 v[200:203], v141 offset:20480
	ds_read_b128 v[204:207], v141 offset:21504
	ds_read_b128 v[208:211], v141 offset:22528
	ds_read_b128 v[212:215], v141 offset:23552
	global_load_lds_dwordx4 v152, s[56:57]
	s_add_i32 m0, s81, 0x2000
	s_add_u32 s82, s56, 0x80000
	s_addc_u32 s83, s57, 0
	s_add_i32 s81, s70, s61
	global_load_lds_dwordx4 v156, s[56:57]
	s_mov_b32 m0, s81
	s_nop 0
	global_load_lds_dwordx4 v152, s[82:83]
	s_add_i32 m0, s81, 0x2000
	s_nop 0
	global_load_lds_dwordx4 v156, s[82:83]
	s_add_u32 s100, s58, 0x80
	s_addc_u32 s101, s59, 0
	s_mov_b32 m0, s53
	s_nop 0
	global_load_lds_dwordx4 v150, s[58:59]
	s_mov_b32 m0, s62
	s_nop 0
	global_load_lds_dwordx4 v154, s[58:59]
	s_waitcnt vmcnt(8)
	s_waitcnt lgkmcnt(0)
	s_setprio 1
	s_barrier
	v_mfma_f32_16x16x32_bf16 v[62:65], v[142:145], v[184:187], v[62:65]
	v_mfma_f32_16x16x32_bf16 v[58:61], v[158:161], v[184:187], v[58:61]
	v_mfma_f32_16x16x32_bf16 v[50:53], v[142:145], v[192:195], v[50:53]
	v_mfma_f32_16x16x32_bf16 v[42:45], v[158:161], v[192:195], v[42:45]
	v_mfma_f32_16x16x32_bf16 v[34:37], v[142:145], v[200:203], v[34:37]
	v_mfma_f32_16x16x32_bf16 v[26:29], v[158:161], v[200:203], v[26:29]
	v_mfma_f32_16x16x32_bf16 v[18:21], v[142:145], v[208:211], v[18:21]
	v_mfma_f32_16x16x32_bf16 v[10:13], v[158:161], v[208:211], v[10:13]
	v_mfma_f32_16x16x32_bf16 v[62:65], v[146:149], v[188:191], v[62:65]
	v_mfma_f32_16x16x32_bf16 v[58:61], v[162:165], v[188:191], v[58:61]
	v_mfma_f32_16x16x32_bf16 v[50:53], v[146:149], v[196:199], v[50:53]
	v_mfma_f32_16x16x32_bf16 v[42:45], v[162:165], v[196:199], v[42:45]
	v_mfma_f32_16x16x32_bf16 v[34:37], v[146:149], v[204:207], v[34:37]
	v_mfma_f32_16x16x32_bf16 v[26:29], v[162:165], v[204:207], v[26:29]
	v_mfma_f32_16x16x32_bf16 v[18:21], v[146:149], v[212:215], v[18:21]
	v_mfma_f32_16x16x32_bf16 v[10:13], v[162:165], v[212:215], v[10:13]
	s_setprio 0
	s_setprio 1
	v_mfma_f32_16x16x32_bf16 v[54:57], v[166:169], v[184:187], v[54:57]
	v_mfma_f32_16x16x32_bf16 v[46:49], v[174:177], v[184:187], v[46:49]
	v_mfma_f32_16x16x32_bf16 v[38:41], v[166:169], v[192:195], v[38:41]
	v_mfma_f32_16x16x32_bf16 v[30:33], v[174:177], v[192:195], v[30:33]
	v_mfma_f32_16x16x32_bf16 v[22:25], v[166:169], v[200:203], v[22:25]
	v_mfma_f32_16x16x32_bf16 v[14:17], v[174:177], v[200:203], v[14:17]
	v_mfma_f32_16x16x32_bf16 v[6:9], v[166:169], v[208:211], v[6:9]
	v_mfma_f32_16x16x32_bf16 v[2:5], v[174:177], v[208:211], v[2:5]
	v_mfma_f32_16x16x32_bf16 v[54:57], v[170:173], v[188:191], v[54:57]
	v_mfma_f32_16x16x32_bf16 v[46:49], v[180:183], v[188:191], v[46:49]
	v_mfma_f32_16x16x32_bf16 v[38:41], v[170:173], v[196:199], v[38:41]
	v_mfma_f32_16x16x32_bf16 v[30:33], v[180:183], v[196:199], v[30:33]
	v_mfma_f32_16x16x32_bf16 v[22:25], v[170:173], v[204:207], v[22:25]
	v_mfma_f32_16x16x32_bf16 v[14:17], v[180:183], v[204:207], v[14:17]
	v_mfma_f32_16x16x32_bf16 v[6:9], v[170:173], v[212:215], v[6:9]
	v_mfma_f32_16x16x32_bf16 v[2:5], v[180:183], v[212:215], v[2:5]
	s_barrier
	s_setprio 0
	s_add_i32 s81, 0, 0x18000
	v_add_u32_e32 v1, s81, v136
	s_add_i32 s82, 0, 0x1c000
	ds_read_b128 v[142:145], v1
	ds_read_b128 v[146:149], v1 offset:1024
	ds_read_b128 v[158:161], v1 offset:2048
	ds_read_b128 v[162:165], v1 offset:3072
	v_add_u32_e32 v1, s82, v136
	ds_read_b128 v[166:169], v1
	ds_read_b128 v[170:173], v1 offset:1024
	ds_read_b128 v[174:177], v1 offset:2048
	ds_read_b128 v[180:183], v1 offset:3072
	s_add_u32 s58, s58, 0x80000
	s_addc_u32 s59, s59, 0
	s_mov_b32 m0, s63
	ds_read_b128 v[184:187], v141 offset:32768
	ds_read_b128 v[188:191], v141 offset:33792
	ds_read_b128 v[192:195], v141 offset:34816
	ds_read_b128 v[196:199], v141 offset:35840
	ds_read_b128 v[200:203], v141 offset:36864
	ds_read_b128 v[204:207], v141 offset:37888
	ds_read_b128 v[208:211], v141 offset:38912
	ds_read_b128 v[212:215], v141 offset:39936
	global_load_lds_dwordx4 v150, s[58:59]
	s_mov_b32 m0, s64
	s_nop 0
	global_load_lds_dwordx4 v154, s[58:59]
	s_waitcnt vmcnt(8)
	s_waitcnt lgkmcnt(0)
	s_setprio 1
	s_barrier
	v_mfma_f32_16x16x32_bf16 v[126:129], v[142:145], v[184:187], v[126:129]
	v_mfma_f32_16x16x32_bf16 v[122:125], v[158:161], v[184:187], v[122:125]
	v_mfma_f32_16x16x32_bf16 v[114:117], v[142:145], v[192:195], v[114:117]
	v_mfma_f32_16x16x32_bf16 v[106:109], v[158:161], v[192:195], v[106:109]
	v_mfma_f32_16x16x32_bf16 v[98:101], v[142:145], v[200:203], v[98:101]
	v_mfma_f32_16x16x32_bf16 v[90:93], v[158:161], v[200:203], v[90:93]
	v_mfma_f32_16x16x32_bf16 v[82:85], v[142:145], v[208:211], v[82:85]
	v_mfma_f32_16x16x32_bf16 v[74:77], v[158:161], v[208:211], v[74:77]
	v_mfma_f32_16x16x32_bf16 v[126:129], v[146:149], v[188:191], v[126:129]
	v_mfma_f32_16x16x32_bf16 v[122:125], v[162:165], v[188:191], v[122:125]
	v_mfma_f32_16x16x32_bf16 v[114:117], v[146:149], v[196:199], v[114:117]
	v_mfma_f32_16x16x32_bf16 v[106:109], v[162:165], v[196:199], v[106:109]
	v_mfma_f32_16x16x32_bf16 v[98:101], v[146:149], v[204:207], v[98:101]
	v_mfma_f32_16x16x32_bf16 v[90:93], v[162:165], v[204:207], v[90:93]
	v_mfma_f32_16x16x32_bf16 v[82:85], v[146:149], v[212:215], v[82:85]
	v_mfma_f32_16x16x32_bf16 v[74:77], v[162:165], v[212:215], v[74:77]
	s_setprio 0
	s_setprio 1
	v_mfma_f32_16x16x32_bf16 v[118:121], v[166:169], v[184:187], v[118:121]
	v_mfma_f32_16x16x32_bf16 v[110:113], v[174:177], v[184:187], v[110:113]
	v_mfma_f32_16x16x32_bf16 v[102:105], v[166:169], v[192:195], v[102:105]
	v_mfma_f32_16x16x32_bf16 v[94:97], v[174:177], v[192:195], v[94:97]
	v_mfma_f32_16x16x32_bf16 v[86:89], v[166:169], v[200:203], v[86:89]
	v_mfma_f32_16x16x32_bf16 v[78:81], v[174:177], v[200:203], v[78:81]
	v_mfma_f32_16x16x32_bf16 v[70:73], v[166:169], v[208:211], v[70:73]
	v_mfma_f32_16x16x32_bf16 v[66:69], v[174:177], v[208:211], v[66:69]
	v_mfma_f32_16x16x32_bf16 v[118:121], v[170:173], v[188:191], v[118:121]
	v_mfma_f32_16x16x32_bf16 v[110:113], v[180:183], v[188:191], v[110:113]
	v_mfma_f32_16x16x32_bf16 v[102:105], v[170:173], v[196:199], v[102:105]
	v_mfma_f32_16x16x32_bf16 v[94:97], v[180:183], v[196:199], v[94:97]
	v_mfma_f32_16x16x32_bf16 v[86:89], v[170:173], v[204:207], v[86:89]
	v_mfma_f32_16x16x32_bf16 v[78:81], v[180:183], v[204:207], v[78:81]
	v_mfma_f32_16x16x32_bf16 v[70:73], v[170:173], v[212:215], v[70:73]
	v_mfma_f32_16x16x32_bf16 v[66:69], v[180:183], v[212:215], v[66:69]
	s_barrier
	s_setprio 0
	s_add_i32 s58, s81, s61
	s_mov_b32 m0, s58
	ds_read_b128 v[184:187], v141 offset:49152
	ds_read_b128 v[188:191], v141 offset:50176
	ds_read_b128 v[192:195], v141 offset:51200
	ds_read_b128 v[196:199], v141 offset:52224
	ds_read_b128 v[200:203], v141 offset:53248
	ds_read_b128 v[204:207], v141 offset:54272
	ds_read_b128 v[208:211], v141 offset:55296
	ds_read_b128 v[212:215], v141 offset:56320
	global_load_lds_dwordx4 v152, s[98:99]
	s_add_i32 m0, s58, 0x2000
	s_add_u32 s56, s56, 0x80080
	s_addc_u32 s57, s57, 0
	s_add_i32 s58, s82, s61
	global_load_lds_dwordx4 v156, s[98:99]
	s_mov_b32 m0, s58
	s_nop 0
	global_load_lds_dwordx4 v152, s[56:57]
	s_add_i32 m0, s58, 0x2000
	s_nop 0
	global_load_lds_dwordx4 v156, s[56:57]
	s_mov_b32 m0, s66
	s_nop 0
	global_load_lds_dwordx4 v150, s[100:101]
	s_mov_b32 m0, s67
	s_nop 0
	global_load_lds_dwordx4 v154, s[100:101]
	s_add_i32 s80, s80, 2
	s_add_u32 s54, s54, 0x100
	s_addc_u32 s55, s55, 0
	s_add_u32 s78, s78, 0x100
	s_addc_u32 s79, s79, 0
	s_cmp_gt_u32 s80, 29
	s_waitcnt vmcnt(8)
	s_waitcnt lgkmcnt(0)
	s_setprio 1
	s_barrier
	v_mfma_f32_16x16x32_bf16 v[62:65], v[142:145], v[184:187], v[62:65]
	v_mfma_f32_16x16x32_bf16 v[58:61], v[158:161], v[184:187], v[58:61]
	v_mfma_f32_16x16x32_bf16 v[50:53], v[142:145], v[192:195], v[50:53]
	v_mfma_f32_16x16x32_bf16 v[42:45], v[158:161], v[192:195], v[42:45]
	v_mfma_f32_16x16x32_bf16 v[34:37], v[142:145], v[200:203], v[34:37]
	v_mfma_f32_16x16x32_bf16 v[26:29], v[158:161], v[200:203], v[26:29]
	v_mfma_f32_16x16x32_bf16 v[18:21], v[142:145], v[208:211], v[18:21]
	v_mfma_f32_16x16x32_bf16 v[10:13], v[158:161], v[208:211], v[10:13]
	v_mfma_f32_16x16x32_bf16 v[62:65], v[146:149], v[188:191], v[62:65]
	v_mfma_f32_16x16x32_bf16 v[58:61], v[162:165], v[188:191], v[58:61]
	v_mfma_f32_16x16x32_bf16 v[50:53], v[146:149], v[196:199], v[50:53]
	v_mfma_f32_16x16x32_bf16 v[42:45], v[162:165], v[196:199], v[42:45]
	v_mfma_f32_16x16x32_bf16 v[34:37], v[146:149], v[204:207], v[34:37]
	v_mfma_f32_16x16x32_bf16 v[26:29], v[162:165], v[204:207], v[26:29]
	v_mfma_f32_16x16x32_bf16 v[18:21], v[146:149], v[212:215], v[18:21]
	v_mfma_f32_16x16x32_bf16 v[10:13], v[162:165], v[212:215], v[10:13]
	s_setprio 0
	s_setprio 1
	v_mfma_f32_16x16x32_bf16 v[54:57], v[166:169], v[184:187], v[54:57]
	v_mfma_f32_16x16x32_bf16 v[46:49], v[174:177], v[184:187], v[46:49]
	v_mfma_f32_16x16x32_bf16 v[38:41], v[166:169], v[192:195], v[38:41]
	v_mfma_f32_16x16x32_bf16 v[30:33], v[174:177], v[192:195], v[30:33]
	v_mfma_f32_16x16x32_bf16 v[22:25], v[166:169], v[200:203], v[22:25]
	v_mfma_f32_16x16x32_bf16 v[14:17], v[174:177], v[200:203], v[14:17]
	v_mfma_f32_16x16x32_bf16 v[6:9], v[166:169], v[208:211], v[6:9]
	v_mfma_f32_16x16x32_bf16 v[2:5], v[174:177], v[208:211], v[2:5]
	v_mfma_f32_16x16x32_bf16 v[54:57], v[170:173], v[188:191], v[54:57]
	v_mfma_f32_16x16x32_bf16 v[46:49], v[180:183], v[188:191], v[46:49]
	v_mfma_f32_16x16x32_bf16 v[38:41], v[170:173], v[196:199], v[38:41]
	v_mfma_f32_16x16x32_bf16 v[30:33], v[180:183], v[196:199], v[30:33]
	v_mfma_f32_16x16x32_bf16 v[22:25], v[170:173], v[204:207], v[22:25]
	v_mfma_f32_16x16x32_bf16 v[14:17], v[180:183], v[204:207], v[14:17]
	v_mfma_f32_16x16x32_bf16 v[6:9], v[170:173], v[212:215], v[6:9]
	v_mfma_f32_16x16x32_bf16 v[2:5], v[180:183], v[212:215], v[2:5]
	s_barrier
	s_setprio 0
	s_cbranch_scc0 .LBB0_725
	s_and_b64 vcc, exec, s[6:7]
	s_cbranch_vccz .LBB0_728
	s_barrier

.LBB0_1315:
	s_add_u32 s4, s26, 0x15c00000
	s_addc_u32 s5, s27, 0
	s_add_u32 s6, s26, 0x23c00000
	s_addc_u32 s7, s27, 0
	s_lshl_b32 s49, s8, 6
	s_lshl_b32 s12, s8, 13
	s_lshl_b32 s8, s9, 5
	s_and_b32 s52, s8, 0x60
	s_mov_b64 s[8:9], 0x80
	s_add_i32 m0, s29, 0x18000
	v_lshl_add_u64 v[10:11], v[10:11], 0, s[8:9]
	s_lshl_b32 s13, s52, 7
	s_waitcnt vmcnt(2)
	s_barrier
	global_load_lds_dwordx4 v[10:11], off
	v_lshl_add_u64 v[8:9], v[8:9], 0, s[8:9]
	s_add_i32 m0, s29, 0x1a000
	s_add_i32 s53, s29, 0x8000
	s_add_i32 s54, s29, 0xa000
	global_load_lds_dwordx4 v[8:9], off
	v_lshl_add_u64 v[4:5], v[4:5], 0, s[8:9]
	s_mov_b32 m0, s53
	s_add_u32 s10, s40, 0x80080
	global_load_lds_dwordx4 v[4:5], off
	v_lshl_add_u64 v[4:5], v[6:7], 0, s[8:9]
	s_mov_b32 m0, s54
	s_addc_u32 s11, s41, 0
	global_load_lds_dwordx4 v[4:5], off
	s_add_i32 m0, s29, 0x1c000
	s_nop 0
	global_load_lds_dwordx4 v176, s[10:11]
	v_lshl_add_u64 v[4:5], s[10:11], 0, v[180:181]
	s_add_i32 m0, s29, 0x1e000
	v_bfe_u32 v195, v0, 4, 2
	global_load_lds_dwordx4 v[4:5], off
	v_and_b32_e32 v194, 15, v0
	v_lshlrev_b32_e32 v1, 4, v195
	v_lshlrev_b32_e32 v5, 2, v0
	v_lshl_or_b32 v4, v194, 6, v1
	v_and_b32_e32 v5, 32, v5
	s_sext_i32_i8 s39, s2
	v_bitop3_b32 v6, v4, s12, v5 bitop3:0xde
	v_lshlrev_b32_e32 v4, 6, v0
	s_movk_i32 s2, 0x3c0
	v_and_or_b32 v1, v4, s2, v1
	v_bitop3_b32 v197, s13, v1, v5 bitop3:0xf6
	v_lshlrev_b32_e32 v1, 9, v0
	v_and_b32_e32 v1, 0x30000, v1
	v_lshlrev_b32_e32 v7, 12, v13
	v_or3_b32 v1, v3, v1, v7
	v_add_u32_e32 v4, v1, v12
	v_lshlrev_b32_e32 v1, 5, v14
	v_and_b32_e32 v1, 0x70000, v1
	s_mov_b64 s[12:13], 0x80080
	s_waitcnt vmcnt(6)
	v_mov_b32_e32 v5, v2
	v_or3_b32 v1, v3, v1, v7
	s_cmpk_lt_u32 s3, 0x100
	v_lshl_add_u64 v[182:183], v[4:5], 0, s[12:13]
	v_add_u32_e32 v4, v1, v12
	v_or_b32_e32 v196, s49, v194
	s_cselect_b64 s[10:11], -1, 0
	v_lshl_or_b32 v198, v195, 3, s52
	s_ashr_i32 s55, s33, 31
	v_lshl_add_u64 v[184:185], v[4:5], 0, s[12:13]
	v_mov_b64_e32 v[186:187], 0x400
	v_mov_b64_e32 v[188:189], 0x3ff
	s_movk_i32 s56, 0x1000
	s_movk_i32 s57, 0x3000
	s_add_i32 s58, 0, 0x10000
	s_add_i32 s59, 0, 0x14000
	v_add_u32_e32 v199, 0, v6
	s_mov_b64 s[12:13], 0x2000
	s_barrier
	s_branch .LBB0_1318

.LBB0_1328:
	v_add_u32_e32 v1, s58, v197
	s_add_u32 s40, s36, s38
	ds_read_b128 v[134:137], v1
	ds_read_b128 v[138:141], v1 offset:1024
	ds_read_b128 v[142:145], v1 offset:2048
	ds_read_b128 v[146:149], v1 offset:3072
	v_add_u32_e32 v1, s59, v197
	s_addc_u32 s41, s37, s39
	ds_read_b128 v[150:153], v1
	ds_read_b128 v[154:157], v1 offset:1024
	ds_read_b128 v[158:161], v1 offset:2048
	ds_read_b128 v[162:165], v1 offset:3072
	s_add_u32 s40, s40, 0x100
	s_addc_u32 s41, s41, 0
	s_add_u32 s69, s66, s38
	s_addc_u32 s70, s67, s39
	s_cmpk_eq_i32 s38, 0xf00
	s_cselect_b32 s42, s60, s40
	s_cselect_b32 s40, s63, s69
	s_cselect_b32 s43, s17, s41
	s_cselect_b32 s41, s62, s70
	v_lshl_add_u64 v[4:5], v[190:191], 0, s[38:39]
	s_add_i32 m0, s29, 0xc000
	ds_read_b128 v[166:169], v199
	ds_read_b128 v[170:173], v199 offset:1024
	ds_read_b128 v[200:203], v199 offset:2048
	ds_read_b128 v[204:207], v199 offset:3072
	ds_read_b128 v[208:211], v199 offset:4096
	ds_read_b128 v[212:215], v199 offset:5120
	ds_read_b128 v[216:219], v199 offset:6144
	ds_read_b128 v[220:223], v199 offset:7168
	global_load_lds_dwordx4 v[4:5], off
	v_lshl_add_u64 v[4:5], v[192:193], 0, s[38:39]
	s_add_i32 m0, s29, 0xe000
	s_nop 0
	global_load_lds_dwordx4 v[4:5], off
	s_waitcnt vmcnt(8)
	s_waitcnt lgkmcnt(0)
	s_setprio 1
	s_barrier
	v_mfma_f32_16x16x32_bf16 v[130:133], v[134:137], v[166:169], v[130:133]
	v_mfma_f32_16x16x32_bf16 v[126:129], v[142:145], v[166:169], v[126:129]
	v_mfma_f32_16x16x32_bf16 v[114:117], v[134:137], v[200:203], v[114:117]
	v_mfma_f32_16x16x32_bf16 v[110:113], v[142:145], v[200:203], v[110:113]
	v_mfma_f32_16x16x32_bf16 v[98:101], v[134:137], v[208:211], v[98:101]
	v_mfma_f32_16x16x32_bf16 v[94:97], v[142:145], v[208:211], v[94:97]
	v_mfma_f32_16x16x32_bf16 v[82:85], v[134:137], v[216:219], v[82:85]
	v_mfma_f32_16x16x32_bf16 v[78:81], v[142:145], v[216:219], v[78:81]
	v_mfma_f32_16x16x32_bf16 v[130:133], v[138:141], v[170:173], v[130:133]
	v_mfma_f32_16x16x32_bf16 v[126:129], v[146:149], v[170:173], v[126:129]
	v_mfma_f32_16x16x32_bf16 v[114:117], v[138:141], v[204:207], v[114:117]
	v_mfma_f32_16x16x32_bf16 v[110:113], v[146:149], v[204:207], v[110:113]
	v_mfma_f32_16x16x32_bf16 v[98:101], v[138:141], v[212:215], v[98:101]
	v_mfma_f32_16x16x32_bf16 v[94:97], v[146:149], v[212:215], v[94:97]
	v_mfma_f32_16x16x32_bf16 v[82:85], v[138:141], v[220:223], v[82:85]
	v_mfma_f32_16x16x32_bf16 v[78:81], v[146:149], v[220:223], v[78:81]
	s_setprio 0
	s_setprio 1
	v_mfma_f32_16x16x32_bf16 v[122:125], v[150:153], v[166:169], v[122:125]
	v_mfma_f32_16x16x32_bf16 v[118:121], v[158:161], v[166:169], v[118:121]
	v_mfma_f32_16x16x32_bf16 v[106:109], v[150:153], v[200:203], v[106:109]
	v_mfma_f32_16x16x32_bf16 v[102:105], v[158:161], v[200:203], v[102:105]
	v_mfma_f32_16x16x32_bf16 v[90:93], v[150:153], v[208:211], v[90:93]
	v_mfma_f32_16x16x32_bf16 v[86:89], v[158:161], v[208:211], v[86:89]
	v_mfma_f32_16x16x32_bf16 v[74:77], v[150:153], v[216:219], v[74:77]
	v_mfma_f32_16x16x32_bf16 v[70:73], v[158:161], v[216:219], v[70:73]
	v_mfma_f32_16x16x32_bf16 v[122:125], v[154:157], v[170:173], v[122:125]
	v_mfma_f32_16x16x32_bf16 v[118:121], v[162:165], v[170:173], v[118:121]
	v_mfma_f32_16x16x32_bf16 v[106:109], v[154:157], v[204:207], v[106:109]
	v_mfma_f32_16x16x32_bf16 v[102:105], v[162:165], v[204:207], v[102:105]
	v_mfma_f32_16x16x32_bf16 v[90:93], v[154:157], v[212:215], v[90:93]
	v_mfma_f32_16x16x32_bf16 v[86:89], v[162:165], v[212:215], v[86:89]
	v_mfma_f32_16x16x32_bf16 v[74:77], v[154:157], v[220:223], v[74:77]
	v_mfma_f32_16x16x32_bf16 v[70:73], v[162:165], v[220:223], v[70:73]
	s_barrier
	s_setprio 0
	s_add_i32 s69, s58, s28
	s_add_u32 s98, s40, 0x80
	s_addc_u32 s99, s41, 0
	s_mov_b32 m0, s69
	ds_read_b128 v[166:169], v199 offset:16384
	ds_read_b128 v[170:173], v199 offset:17408
	ds_read_b128 v[200:203], v199 offset:18432
	ds_read_b128 v[204:207], v199 offset:19456
	ds_read_b128 v[208:211], v199 offset:20480
	ds_read_b128 v[212:215], v199 offset:21504
	ds_read_b128 v[216:219], v199 offset:22528
	ds_read_b128 v[220:223], v199 offset:23552
	global_load_lds_dwordx4 v176, s[40:41]
	s_add_i32 m0, s69, 0x2000
	s_add_u32 s70, s40, 0x80000
	s_addc_u32 s71, s41, 0
	s_add_i32 s69, s59, s28
	global_load_lds_dwordx4 v180, s[40:41]
	s_mov_b32 m0, s69
	s_add_u32 s100, s42, 0x80
	s_addc_u32 s101, s43, 0
	global_load_lds_dwordx4 v176, s[70:71]
	v_lshl_add_u64 v[4:5], s[70:71], 0, v[180:181]
	s_add_i32 m0, s69, 0x2000
	s_nop 0
	global_load_lds_dwordx4 v[4:5], off
	s_mov_b32 m0, s29
	s_nop 0
	global_load_lds_dwordx4 v174, s[42:43]
	s_mov_b32 m0, s44
	s_nop 0
	global_load_lds_dwordx4 v178, s[42:43]
	s_waitcnt vmcnt(8)
	s_waitcnt lgkmcnt(0)
	s_setprio 1
	s_barrier
	v_mfma_f32_16x16x32_bf16 v[66:69], v[134:137], v[166:169], v[66:69]
	v_mfma_f32_16x16x32_bf16 v[62:65], v[142:145], v[166:169], v[62:65]
	v_mfma_f32_16x16x32_bf16 v[50:53], v[134:137], v[200:203], v[50:53]
	v_mfma_f32_16x16x32_bf16 v[46:49], v[142:145], v[200:203], v[46:49]
	v_mfma_f32_16x16x32_bf16 v[34:37], v[134:137], v[208:211], v[34:37]
	v_mfma_f32_16x16x32_bf16 v[30:33], v[142:145], v[208:211], v[30:33]
	v_mfma_f32_16x16x32_bf16 v[18:21], v[134:137], v[216:219], v[18:21]
	v_mfma_f32_16x16x32_bf16 v[14:17], v[142:145], v[216:219], v[14:17]
	v_mfma_f32_16x16x32_bf16 v[66:69], v[138:141], v[170:173], v[66:69]
	v_mfma_f32_16x16x32_bf16 v[62:65], v[146:149], v[170:173], v[62:65]
	v_mfma_f32_16x16x32_bf16 v[50:53], v[138:141], v[204:207], v[50:53]
	v_mfma_f32_16x16x32_bf16 v[46:49], v[146:149], v[204:207], v[46:49]
	v_mfma_f32_16x16x32_bf16 v[34:37], v[138:141], v[212:215], v[34:37]
	v_mfma_f32_16x16x32_bf16 v[30:33], v[146:149], v[212:215], v[30:33]
	v_mfma_f32_16x16x32_bf16 v[18:21], v[138:141], v[220:223], v[18:21]
	v_mfma_f32_16x16x32_bf16 v[14:17], v[146:149], v[220:223], v[14:17]
	s_setprio 0
	s_setprio 1
	v_mfma_f32_16x16x32_bf16 v[58:61], v[150:153], v[166:169], v[58:61]
	v_mfma_f32_16x16x32_bf16 v[54:57], v[158:161], v[166:169], v[54:57]
	v_mfma_f32_16x16x32_bf16 v[42:45], v[150:153], v[200:203], v[42:45]
	v_mfma_f32_16x16x32_bf16 v[38:41], v[158:161], v[200:203], v[38:41]
	v_mfma_f32_16x16x32_bf16 v[26:29], v[150:153], v[208:211], v[26:29]
	v_mfma_f32_16x16x32_bf16 v[22:25], v[158:161], v[208:211], v[22:25]
	v_mfma_f32_16x16x32_bf16 v[10:13], v[150:153], v[216:219], v[10:13]
	v_mfma_f32_16x16x32_bf16 v[4:7], v[158:161], v[216:219], v[6:9]
	v_mfma_f32_16x16x32_bf16 v[58:61], v[154:157], v[170:173], v[58:61]
	v_mfma_f32_16x16x32_bf16 v[54:57], v[162:165], v[170:173], v[54:57]
	v_mfma_f32_16x16x32_bf16 v[42:45], v[154:157], v[204:207], v[42:45]
	v_mfma_f32_16x16x32_bf16 v[38:41], v[162:165], v[204:207], v[38:41]
	v_mfma_f32_16x16x32_bf16 v[26:29], v[154:157], v[212:215], v[26:29]
	v_mfma_f32_16x16x32_bf16 v[22:25], v[162:165], v[212:215], v[22:25]
	v_mfma_f32_16x16x32_bf16 v[10:13], v[154:157], v[220:223], v[10:13]
	v_mfma_f32_16x16x32_bf16 v[4:7], v[162:165], v[220:223], v[4:7]
	s_barrier
	s_setprio 0
	s_add_i32 s69, 0, 0x18000
	v_add_u32_e32 v1, s69, v197
	s_add_i32 s70, 0, 0x1c000
	ds_read_b128 v[134:137], v1
	ds_read_b128 v[138:141], v1 offset:1024
	ds_read_b128 v[142:145], v1 offset:2048
	ds_read_b128 v[146:149], v1 offset:3072
	v_add_u32_e32 v1, s70, v197
	ds_read_b128 v[150:153], v1
	ds_read_b128 v[154:157], v1 offset:1024
	ds_read_b128 v[158:161], v1 offset:2048
	ds_read_b128 v[162:165], v1 offset:3072
	s_add_u32 s42, s42, 0x80000
	s_addc_u32 s43, s43, 0
	s_mov_b32 m0, s45
	ds_read_b128 v[166:169], v199 offset:32768
	ds_read_b128 v[170:173], v199 offset:33792
	ds_read_b128 v[200:203], v199 offset:34816
	ds_read_b128 v[204:207], v199 offset:35840
	ds_read_b128 v[208:211], v199 offset:36864
	ds_read_b128 v[212:215], v199 offset:37888
	ds_read_b128 v[216:219], v199 offset:38912
	ds_read_b128 v[220:223], v199 offset:39936
	global_load_lds_dwordx4 v174, s[42:43]
	s_mov_b32 m0, s46
	s_nop 0
	global_load_lds_dwordx4 v178, s[42:43]
	s_waitcnt vmcnt(8)
	s_waitcnt lgkmcnt(0)
	s_setprio 1
	s_barrier
	v_mfma_f32_16x16x32_bf16 v[130:133], v[134:137], v[166:169], v[130:133]
	v_mfma_f32_16x16x32_bf16 v[126:129], v[142:145], v[166:169], v[126:129]
	v_mfma_f32_16x16x32_bf16 v[114:117], v[134:137], v[200:203], v[114:117]
	v_mfma_f32_16x16x32_bf16 v[110:113], v[142:145], v[200:203], v[110:113]
	v_mfma_f32_16x16x32_bf16 v[98:101], v[134:137], v[208:211], v[98:101]
	v_mfma_f32_16x16x32_bf16 v[94:97], v[142:145], v[208:211], v[94:97]
	v_mfma_f32_16x16x32_bf16 v[82:85], v[134:137], v[216:219], v[82:85]
	v_mfma_f32_16x16x32_bf16 v[78:81], v[142:145], v[216:219], v[78:81]
	v_mfma_f32_16x16x32_bf16 v[130:133], v[138:141], v[170:173], v[130:133]
	v_mfma_f32_16x16x32_bf16 v[126:129], v[146:149], v[170:173], v[126:129]
	v_mfma_f32_16x16x32_bf16 v[114:117], v[138:141], v[204:207], v[114:117]
	v_mfma_f32_16x16x32_bf16 v[110:113], v[146:149], v[204:207], v[110:113]
	v_mfma_f32_16x16x32_bf16 v[98:101], v[138:141], v[212:215], v[98:101]
	v_mfma_f32_16x16x32_bf16 v[94:97], v[146:149], v[212:215], v[94:97]
	v_mfma_f32_16x16x32_bf16 v[82:85], v[138:141], v[220:223], v[82:85]
	v_mfma_f32_16x16x32_bf16 v[78:81], v[146:149], v[220:223], v[78:81]
	s_setprio 0
	s_setprio 1
	v_mfma_f32_16x16x32_bf16 v[122:125], v[150:153], v[166:169], v[122:125]
	v_mfma_f32_16x16x32_bf16 v[118:121], v[158:161], v[166:169], v[118:121]
	v_mfma_f32_16x16x32_bf16 v[106:109], v[150:153], v[200:203], v[106:109]
	v_mfma_f32_16x16x32_bf16 v[102:105], v[158:161], v[200:203], v[102:105]
	v_mfma_f32_16x16x32_bf16 v[90:93], v[150:153], v[208:211], v[90:93]
	v_mfma_f32_16x16x32_bf16 v[86:89], v[158:161], v[208:211], v[86:89]
	v_mfma_f32_16x16x32_bf16 v[74:77], v[150:153], v[216:219], v[74:77]
	v_mfma_f32_16x16x32_bf16 v[70:73], v[158:161], v[216:219], v[70:73]
	v_mfma_f32_16x16x32_bf16 v[122:125], v[154:157], v[170:173], v[122:125]
	v_mfma_f32_16x16x32_bf16 v[118:121], v[162:165], v[170:173], v[118:121]
	v_mfma_f32_16x16x32_bf16 v[106:109], v[154:157], v[204:207], v[106:109]
	v_mfma_f32_16x16x32_bf16 v[102:105], v[162:165], v[204:207], v[102:105]
	v_mfma_f32_16x16x32_bf16 v[90:93], v[154:157], v[212:215], v[90:93]
	v_mfma_f32_16x16x32_bf16 v[86:89], v[162:165], v[212:215], v[86:89]
	v_mfma_f32_16x16x32_bf16 v[74:77], v[154:157], v[220:223], v[74:77]
	v_mfma_f32_16x16x32_bf16 v[70:73], v[162:165], v[220:223], v[70:73]
	s_barrier
	s_setprio 0
	s_add_i32 s42, s69, s28
	s_mov_b32 m0, s42
	ds_read_b128 v[166:169], v199 offset:49152
	ds_read_b128 v[170:173], v199 offset:50176
	ds_read_b128 v[200:203], v199 offset:51200
	ds_read_b128 v[204:207], v199 offset:52224
	ds_read_b128 v[208:211], v199 offset:53248
	ds_read_b128 v[212:215], v199 offset:54272
	ds_read_b128 v[216:219], v199 offset:55296
	ds_read_b128 v[220:223], v199 offset:56320
	global_load_lds_dwordx4 v176, s[98:99]
	s_add_i32 m0, s42, 0x2000
	s_add_u32 s40, s40, 0x80080
	s_addc_u32 s41, s41, 0
	s_add_i32 s42, s70, s28
	global_load_lds_dwordx4 v180, s[98:99]
	s_mov_b32 m0, s42
	s_nop 0
	global_load_lds_dwordx4 v176, s[40:41]
	s_add_i32 m0, s42, 0x2000
	s_nop 0
	global_load_lds_dwordx4 v180, s[40:41]
	s_mov_b32 m0, s53
	s_nop 0
	global_load_lds_dwordx4 v174, s[100:101]
	s_mov_b32 m0, s54
	s_nop 0
	global_load_lds_dwordx4 v178, s[100:101]
	s_waitcnt vmcnt(8)
	s_waitcnt lgkmcnt(0)
	s_setprio 1
	s_barrier
	v_mfma_f32_16x16x32_bf16 v[66:69], v[134:137], v[166:169], v[66:69]
	v_mfma_f32_16x16x32_bf16 v[62:65], v[142:145], v[166:169], v[62:65]
	v_mfma_f32_16x16x32_bf16 v[50:53], v[134:137], v[200:203], v[50:53]
	v_mfma_f32_16x16x32_bf16 v[46:49], v[142:145], v[200:203], v[46:49]
	v_mfma_f32_16x16x32_bf16 v[34:37], v[134:137], v[208:211], v[34:37]
	v_mfma_f32_16x16x32_bf16 v[30:33], v[142:145], v[208:211], v[30:33]
	v_mfma_f32_16x16x32_bf16 v[18:21], v[134:137], v[216:219], v[18:21]
	v_mfma_f32_16x16x32_bf16 v[14:17], v[142:145], v[216:219], v[14:17]
	v_mfma_f32_16x16x32_bf16 v[66:69], v[138:141], v[170:173], v[66:69]
	v_mfma_f32_16x16x32_bf16 v[62:65], v[146:149], v[170:173], v[62:65]
	v_mfma_f32_16x16x32_bf16 v[50:53], v[138:141], v[204:207], v[50:53]
	v_mfma_f32_16x16x32_bf16 v[46:49], v[146:149], v[204:207], v[46:49]
	v_mfma_f32_16x16x32_bf16 v[34:37], v[138:141], v[212:215], v[34:37]
	v_mfma_f32_16x16x32_bf16 v[30:33], v[146:149], v[212:215], v[30:33]
	v_mfma_f32_16x16x32_bf16 v[18:21], v[138:141], v[220:223], v[18:21]
	v_mfma_f32_16x16x32_bf16 v[14:17], v[146:149], v[220:223], v[14:17]
	s_setprio 0
	s_setprio 1
	v_mfma_f32_16x16x32_bf16 v[58:61], v[150:153], v[166:169], v[58:61]
	v_mfma_f32_16x16x32_bf16 v[54:57], v[158:161], v[166:169], v[54:57]
	v_mfma_f32_16x16x32_bf16 v[42:45], v[150:153], v[200:203], v[42:45]
	v_mfma_f32_16x16x32_bf16 v[38:41], v[158:161], v[200:203], v[38:41]
	v_mfma_f32_16x16x32_bf16 v[26:29], v[150:153], v[208:211], v[26:29]
	v_mfma_f32_16x16x32_bf16 v[22:25], v[158:161], v[208:211], v[22:25]
	v_mfma_f32_16x16x32_bf16 v[8:11], v[150:153], v[216:219], v[10:13]
	v_mfma_f32_16x16x32_bf16 v[4:7], v[158:161], v[216:219], v[4:7]
	v_mfma_f32_16x16x32_bf16 v[58:61], v[154:157], v[170:173], v[58:61]
	v_mfma_f32_16x16x32_bf16 v[54:57], v[162:165], v[170:173], v[54:57]
	v_mfma_f32_16x16x32_bf16 v[42:45], v[154:157], v[204:207], v[42:45]
	v_mfma_f32_16x16x32_bf16 v[38:41], v[162:165], v[204:207], v[38:41]
	v_mfma_f32_16x16x32_bf16 v[26:29], v[154:157], v[212:215], v[26:29]
	v_mfma_f32_16x16x32_bf16 v[22:25], v[162:165], v[212:215], v[22:25]
	v_mfma_f32_16x16x32_bf16 v[10:13], v[154:157], v[220:223], v[8:11]
	v_mfma_f32_16x16x32_bf16 v[6:9], v[162:165], v[220:223], v[4:7]
	s_barrier
	s_setprio 0
	s_add_i32 s40, s68, 2
	s_add_u32 s38, s38, 0x100
	s_addc_u32 s39, s39, 0
	s_cmp_gt_u32 s68, 29
	s_cbranch_scc1 .LBB0_1330
	s_mov_b32 s68, s40
	s_and_b32 s40, s68, 14
	s_cmp_eq_u32 s40, 8
	s_mov_b64 s[40:41], -1
	s_cbranch_scc0 .LBB0_1325
	s_branch .LBB0_1326

.LBB0_1398:
	s_add_u32 s12, s26, 0x8000000
	s_addc_u32 s13, s27, 0
	s_add_u32 s14, s26, 0x27c00000
	s_addc_u32 s15, s27, 0
	s_add_u32 s16, s26, 0x40000
	s_addc_u32 s17, s27, 0
	s_lshl_b32 s59, s4, 6
	s_lshl_b32 s6, s4, 13
	s_lshl_b32 s4, s5, 5
	s_mov_b64 s[30:31], 0x80
	s_and_b32 s10, s4, 0x60
	s_add_i32 m0, s45, 0x18000
	v_lshl_add_u64 v[8:9], v[8:9], 0, s[30:31]
	s_lshl_b32 s7, s10, 7
	s_waitcnt vmcnt(2)
	s_barrier
	global_load_lds_dwordx4 v[8:9], off
	v_lshl_add_u64 v[6:7], v[6:7], 0, s[30:31]
	s_add_i32 m0, s45, 0x1a000
	s_add_i32 s60, s45, 0x8000
	s_add_i32 s61, s45, 0xa000
	global_load_lds_dwordx4 v[6:7], off
	v_lshl_add_u64 v[2:3], v[2:3], 0, s[30:31]
	s_mov_b32 m0, s60
	s_add_u32 s4, s48, 0x80080
	global_load_lds_dwordx4 v[2:3], off
	v_lshl_add_u64 v[2:3], v[4:5], 0, s[30:31]
	s_mov_b32 m0, s61
	s_addc_u32 s5, s49, 0
	global_load_lds_dwordx4 v[2:3], off
	s_add_i32 m0, s45, 0x1c000
	s_nop 0
	global_load_lds_dwordx4 v148, s[4:5]
	s_add_i32 m0, s45, 0x1e000
	v_bfe_u32 v1, v0, 4, 2
	global_load_lds_dwordx4 v152, s[4:5]
	s_sext_i32_i8 s65, s2
	v_and_b32_e32 v180, 15, v0
	v_lshlrev_b32_e32 v2, 4, v1
	v_lshlrev_b32_e32 v4, 2, v0
	v_lshlrev_b32_e32 v5, 6, v0
	s_movk_i32 s2, 0x3c0
	v_lshl_or_b32 v3, v180, 6, v2
	v_and_b32_e32 v4, 32, v4
	v_and_or_b32 v2, v5, s2, v2
	v_bitop3_b32 v3, v3, s6, v4 bitop3:0xde
	v_bitop3_b32 v181, s7, v2, v4 bitop3:0xf6
	s_cmpk_lt_u32 s3, 0x100
	v_cmp_eq_u32_e64 s[2:3], 0, v1
	v_cmp_eq_u32_e64 s[4:5], 1, v1
	v_cmp_eq_u32_e64 s[6:7], 2, v1
	v_cmp_eq_u32_e64 s[8:9], 3, v1
	v_lshl_or_b32 v182, v1, 3, s10
	v_lshlrev_b32_e32 v1, 9, v0
	v_and_b32_e32 v1, 0x30000, v1
	v_lshlrev_b32_e32 v2, 12, v12
	v_or3_b32 v1, v10, v1, v2
	v_add_u32_e32 v154, v1, v11
	v_lshlrev_b32_e32 v1, 5, v13
	v_and_b32_e32 v1, 0x70000, v1
	s_waitcnt vmcnt(6)
	v_or3_b32 v1, v10, v1, v2
	s_cselect_b64 s[34:35], -1, 0
	v_add_u32_e32 v156, v1, v11
	s_add_i32 s63, 0, 0x10000
	s_add_i32 s64, 0, 0x14000
	v_mbcnt_lo_u32_b32 v1, -1, 0
	s_ashr_i32 s62, s33, 31
	v_mov_b32_e32 v155, v149
	v_mov_b32_e32 v157, v149
	v_mov_b64_e32 v[158:159], 0x400
	v_mov_b64_e32 v[160:161], 0x3ff
	v_add_u32_e32 v183, s63, v181
	v_add_u32_e32 v184, s64, v181
	v_add_u32_e32 v185, 0, v3
	v_mbcnt_hi_u32_b32 v186, -1, v1
	s_barrier
	s_branch .LBB0_1401

.LBB0_1407:
	s_ashr_i32 s39, s38, 31
	s_lshl_b64 s[40:41], s[38:39], 20
	s_add_u32 s40, s22, s40
	s_addc_u32 s41, s23, s41
	s_and_b64 s[42:43], s[10:11], exec
	s_cselect_b32 s39, s41, s47
	s_cselect_b32 s66, s40, s46
	s_ashr_i32 s37, s36, 31
	s_lshl_b64 s[42:43], s[36:37], 20
	s_add_u32 s42, s28, s42
	s_addc_u32 s43, s29, s43
	s_and_b64 s[52:53], s[10:11], exec
	s_cselect_b32 s37, s43, s49
	s_cselect_b32 s67, s42, s48
	s_add_u32 s46, s46, 0x80080
	s_addc_u32 s47, s47, 0
	s_add_u32 s68, s48, 0x100
	s_addc_u32 s69, s49, 0
	s_mov_b32 s70, -2
	ds_read_b128 v[130:133], v183
	ds_read_b128 v[134:137], v183 offset:1024
	ds_read_b128 v[138:141], v183 offset:2048
	ds_read_b128 v[142:145], v183 offset:3072
	ds_read_b128 v[162:165], v184
	ds_read_b128 v[166:169], v184 offset:1024
	ds_read_b128 v[170:173], v184 offset:2048
	ds_read_b128 v[174:177], v184 offset:3072
	s_add_u32 s48, s46, 0xfff80080
	s_addc_u32 s49, s47, -1
	s_cmp_eq_u32 s70, 28
	s_cselect_b32 s53, s39, s49
	s_cselect_b32 s52, s66, s48
	s_cselect_b32 s49, s37, s69
	s_cselect_b32 s48, s67, s68
	s_add_i32 m0, s45, 0xc000
	ds_read_b128 v[188:191], v185
	ds_read_b128 v[192:195], v185 offset:1024
	ds_read_b128 v[196:199], v185 offset:2048
	ds_read_b128 v[200:203], v185 offset:3072
	ds_read_b128 v[204:207], v185 offset:4096
	ds_read_b128 v[208:211], v185 offset:5120
	ds_read_b128 v[212:215], v185 offset:6144
	ds_read_b128 v[216:219], v185 offset:7168
	global_load_lds_dwordx4 v154, s[46:47]
	s_add_i32 m0, s45, 0xe000
	s_nop 0
	global_load_lds_dwordx4 v156, s[46:47]
	s_waitcnt vmcnt(8)
	s_waitcnt lgkmcnt(0)
	s_setprio 1
	s_barrier
	v_mfma_f32_16x16x32_bf16 v[126:129], v[130:133], v[188:191], 0
	v_mfma_f32_16x16x32_bf16 v[122:125], v[138:141], v[188:191], 0
	v_mfma_f32_16x16x32_bf16 v[110:113], v[130:133], v[196:199], 0
	v_mfma_f32_16x16x32_bf16 v[106:109], v[138:141], v[196:199], 0
	v_mfma_f32_16x16x32_bf16 v[94:97], v[130:133], v[204:207], 0
	v_mfma_f32_16x16x32_bf16 v[90:93], v[138:141], v[204:207], 0
	v_mfma_f32_16x16x32_bf16 v[78:81], v[130:133], v[212:215], 0
	v_mfma_f32_16x16x32_bf16 v[74:77], v[138:141], v[212:215], 0
	v_mfma_f32_16x16x32_bf16 v[126:129], v[134:137], v[192:195], v[126:129]
	v_mfma_f32_16x16x32_bf16 v[122:125], v[142:145], v[192:195], v[122:125]
	v_mfma_f32_16x16x32_bf16 v[110:113], v[134:137], v[200:203], v[110:113]
	v_mfma_f32_16x16x32_bf16 v[106:109], v[142:145], v[200:203], v[106:109]
	v_mfma_f32_16x16x32_bf16 v[94:97], v[134:137], v[208:211], v[94:97]
	v_mfma_f32_16x16x32_bf16 v[90:93], v[142:145], v[208:211], v[90:93]
	v_mfma_f32_16x16x32_bf16 v[78:81], v[134:137], v[216:219], v[78:81]
	v_mfma_f32_16x16x32_bf16 v[74:77], v[142:145], v[216:219], v[74:77]
	s_setprio 0
	s_setprio 1
	v_mfma_f32_16x16x32_bf16 v[118:121], v[162:165], v[188:191], 0
	v_mfma_f32_16x16x32_bf16 v[114:117], v[170:173], v[188:191], 0
	v_mfma_f32_16x16x32_bf16 v[102:105], v[162:165], v[196:199], 0
	v_mfma_f32_16x16x32_bf16 v[98:101], v[170:173], v[196:199], 0
	v_mfma_f32_16x16x32_bf16 v[86:89], v[162:165], v[204:207], 0
	v_mfma_f32_16x16x32_bf16 v[82:85], v[170:173], v[204:207], 0
	v_mfma_f32_16x16x32_bf16 v[70:73], v[162:165], v[212:215], 0
	v_mfma_f32_16x16x32_bf16 v[66:69], v[170:173], v[212:215], 0
	v_mfma_f32_16x16x32_bf16 v[118:121], v[166:169], v[192:195], v[118:121]
	v_mfma_f32_16x16x32_bf16 v[114:117], v[174:177], v[192:195], v[114:117]
	v_mfma_f32_16x16x32_bf16 v[102:105], v[166:169], v[200:203], v[102:105]
	v_mfma_f32_16x16x32_bf16 v[98:101], v[174:177], v[200:203], v[98:101]
	v_mfma_f32_16x16x32_bf16 v[86:89], v[166:169], v[208:211], v[86:89]
	v_mfma_f32_16x16x32_bf16 v[82:85], v[174:177], v[208:211], v[82:85]
	v_mfma_f32_16x16x32_bf16 v[70:73], v[166:169], v[216:219], v[70:73]
	v_mfma_f32_16x16x32_bf16 v[66:69], v[174:177], v[216:219], v[66:69]
	s_barrier
	s_setprio 0
	s_add_i32 s71, s63, s54
	s_add_u32 s98, s48, 0x80
	s_addc_u32 s99, s49, 0
	s_mov_b32 m0, s71
	ds_read_b128 v[188:191], v185 offset:16384
	ds_read_b128 v[192:195], v185 offset:17408
	ds_read_b128 v[196:199], v185 offset:18432
	ds_read_b128 v[200:203], v185 offset:19456
	ds_read_b128 v[204:207], v185 offset:20480
	ds_read_b128 v[208:211], v185 offset:21504
	ds_read_b128 v[212:215], v185 offset:22528
	ds_read_b128 v[216:219], v185 offset:23552
	global_load_lds_dwordx4 v148, s[48:49]
	s_add_i32 m0, s71, 0x2000
	s_add_u32 s72, s48, 0x80000
	s_addc_u32 s73, s49, 0
	s_add_i32 s71, s64, s54
	global_load_lds_dwordx4 v152, s[48:49]
	s_mov_b32 m0, s71
	s_nop 0
	global_load_lds_dwordx4 v148, s[72:73]
	s_add_i32 m0, s71, 0x2000
	s_nop 0
	global_load_lds_dwordx4 v152, s[72:73]
	s_add_u32 s100, s52, 0x80
	s_addc_u32 s101, s53, 0
	s_mov_b32 m0, s45
	s_nop 0
	global_load_lds_dwordx4 v146, s[52:53]
	s_mov_b32 m0, s55
	s_nop 0
	global_load_lds_dwordx4 v150, s[52:53]
	s_waitcnt vmcnt(8)
	s_waitcnt lgkmcnt(0)
	s_setprio 1
	s_barrier
	v_mfma_f32_16x16x32_bf16 v[62:65], v[130:133], v[188:191], 0
	v_mfma_f32_16x16x32_bf16 v[58:61], v[138:141], v[188:191], 0
	v_mfma_f32_16x16x32_bf16 v[46:49], v[130:133], v[196:199], 0
	v_mfma_f32_16x16x32_bf16 v[42:45], v[138:141], v[196:199], 0
	v_mfma_f32_16x16x32_bf16 v[30:33], v[130:133], v[204:207], 0
	v_mfma_f32_16x16x32_bf16 v[26:29], v[138:141], v[204:207], 0
	v_mfma_f32_16x16x32_bf16 v[14:17], v[130:133], v[212:215], 0
	v_mfma_f32_16x16x32_bf16 v[10:13], v[138:141], v[212:215], 0
	v_mfma_f32_16x16x32_bf16 v[62:65], v[134:137], v[192:195], v[62:65]
	v_mfma_f32_16x16x32_bf16 v[58:61], v[142:145], v[192:195], v[58:61]
	v_mfma_f32_16x16x32_bf16 v[46:49], v[134:137], v[200:203], v[46:49]
	v_mfma_f32_16x16x32_bf16 v[42:45], v[142:145], v[200:203], v[42:45]
	v_mfma_f32_16x16x32_bf16 v[30:33], v[134:137], v[208:211], v[30:33]
	v_mfma_f32_16x16x32_bf16 v[26:29], v[142:145], v[208:211], v[26:29]
	v_mfma_f32_16x16x32_bf16 v[14:17], v[134:137], v[216:219], v[14:17]
	v_mfma_f32_16x16x32_bf16 v[10:13], v[142:145], v[216:219], v[10:13]
	s_setprio 0
	s_setprio 1
	v_mfma_f32_16x16x32_bf16 v[54:57], v[162:165], v[188:191], 0
	v_mfma_f32_16x16x32_bf16 v[50:53], v[170:173], v[188:191], 0
	v_mfma_f32_16x16x32_bf16 v[38:41], v[162:165], v[196:199], 0
	v_mfma_f32_16x16x32_bf16 v[34:37], v[170:173], v[196:199], 0
	v_mfma_f32_16x16x32_bf16 v[22:25], v[162:165], v[204:207], 0
	v_mfma_f32_16x16x32_bf16 v[18:21], v[170:173], v[204:207], 0
	v_mfma_f32_16x16x32_bf16 v[6:9], v[162:165], v[212:215], 0
	v_mfma_f32_16x16x32_bf16 v[2:5], v[170:173], v[212:215], 0
	v_mfma_f32_16x16x32_bf16 v[54:57], v[166:169], v[192:195], v[54:57]
	v_mfma_f32_16x16x32_bf16 v[50:53], v[174:177], v[192:195], v[50:53]
	v_mfma_f32_16x16x32_bf16 v[38:41], v[166:169], v[200:203], v[38:41]
	v_mfma_f32_16x16x32_bf16 v[34:37], v[174:177], v[200:203], v[34:37]
	v_mfma_f32_16x16x32_bf16 v[22:25], v[166:169], v[208:211], v[22:25]
	v_mfma_f32_16x16x32_bf16 v[18:21], v[174:177], v[208:211], v[18:21]
	v_mfma_f32_16x16x32_bf16 v[6:9], v[166:169], v[216:219], v[6:9]
	v_mfma_f32_16x16x32_bf16 v[2:5], v[174:177], v[216:219], v[2:5]
	s_barrier
	s_setprio 0
	s_add_i32 s71, 0, 0x18000
	v_add_u32_e32 v1, s71, v181
	s_add_i32 s72, 0, 0x1c000
	ds_read_b128 v[130:133], v1
	ds_read_b128 v[134:137], v1 offset:1024
	ds_read_b128 v[138:141], v1 offset:2048
	ds_read_b128 v[142:145], v1 offset:3072
	v_add_u32_e32 v1, s72, v181
	ds_read_b128 v[162:165], v1
	ds_read_b128 v[166:169], v1 offset:1024
	ds_read_b128 v[170:173], v1 offset:2048
	ds_read_b128 v[174:177], v1 offset:3072
	s_add_u32 s52, s52, 0x80000
	s_addc_u32 s53, s53, 0
	s_mov_b32 m0, s56
	ds_read_b128 v[188:191], v185 offset:32768
	ds_read_b128 v[192:195], v185 offset:33792
	ds_read_b128 v[196:199], v185 offset:34816
	ds_read_b128 v[200:203], v185 offset:35840
	ds_read_b128 v[204:207], v185 offset:36864
	ds_read_b128 v[208:211], v185 offset:37888
	ds_read_b128 v[212:215], v185 offset:38912
	ds_read_b128 v[216:219], v185 offset:39936
	global_load_lds_dwordx4 v146, s[52:53]
	s_mov_b32 m0, s57
	s_nop 0
	global_load_lds_dwordx4 v150, s[52:53]
	s_waitcnt vmcnt(8)
	s_waitcnt lgkmcnt(0)
	s_setprio 1
	s_barrier
	v_mfma_f32_16x16x32_bf16 v[126:129], v[130:133], v[188:191], v[126:129]
	v_mfma_f32_16x16x32_bf16 v[122:125], v[138:141], v[188:191], v[122:125]
	v_mfma_f32_16x16x32_bf16 v[110:113], v[130:133], v[196:199], v[110:113]
	v_mfma_f32_16x16x32_bf16 v[106:109], v[138:141], v[196:199], v[106:109]
	v_mfma_f32_16x16x32_bf16 v[94:97], v[130:133], v[204:207], v[94:97]
	v_mfma_f32_16x16x32_bf16 v[90:93], v[138:141], v[204:207], v[90:93]
	v_mfma_f32_16x16x32_bf16 v[78:81], v[130:133], v[212:215], v[78:81]
	v_mfma_f32_16x16x32_bf16 v[74:77], v[138:141], v[212:215], v[74:77]
	v_mfma_f32_16x16x32_bf16 v[126:129], v[134:137], v[192:195], v[126:129]
	v_mfma_f32_16x16x32_bf16 v[122:125], v[142:145], v[192:195], v[122:125]
	v_mfma_f32_16x16x32_bf16 v[110:113], v[134:137], v[200:203], v[110:113]
	v_mfma_f32_16x16x32_bf16 v[106:109], v[142:145], v[200:203], v[106:109]
	v_mfma_f32_16x16x32_bf16 v[94:97], v[134:137], v[208:211], v[94:97]
	v_mfma_f32_16x16x32_bf16 v[90:93], v[142:145], v[208:211], v[90:93]
	v_mfma_f32_16x16x32_bf16 v[78:81], v[134:137], v[216:219], v[78:81]
	v_mfma_f32_16x16x32_bf16 v[74:77], v[142:145], v[216:219], v[74:77]
	s_setprio 0
	s_setprio 1
	v_mfma_f32_16x16x32_bf16 v[118:121], v[162:165], v[188:191], v[118:121]
	v_mfma_f32_16x16x32_bf16 v[114:117], v[170:173], v[188:191], v[114:117]
	v_mfma_f32_16x16x32_bf16 v[102:105], v[162:165], v[196:199], v[102:105]
	v_mfma_f32_16x16x32_bf16 v[98:101], v[170:173], v[196:199], v[98:101]
	v_mfma_f32_16x16x32_bf16 v[86:89], v[162:165], v[204:207], v[86:89]
	v_mfma_f32_16x16x32_bf16 v[82:85], v[170:173], v[204:207], v[82:85]
	v_mfma_f32_16x16x32_bf16 v[70:73], v[162:165], v[212:215], v[70:73]
	v_mfma_f32_16x16x32_bf16 v[66:69], v[170:173], v[212:215], v[66:69]
	v_mfma_f32_16x16x32_bf16 v[118:121], v[166:169], v[192:195], v[118:121]
	v_mfma_f32_16x16x32_bf16 v[114:117], v[174:177], v[192:195], v[114:117]
	v_mfma_f32_16x16x32_bf16 v[102:105], v[166:169], v[200:203], v[102:105]
	v_mfma_f32_16x16x32_bf16 v[98:101], v[174:177], v[200:203], v[98:101]
	v_mfma_f32_16x16x32_bf16 v[86:89], v[166:169], v[208:211], v[86:89]
	v_mfma_f32_16x16x32_bf16 v[82:85], v[174:177], v[208:211], v[82:85]
	v_mfma_f32_16x16x32_bf16 v[70:73], v[166:169], v[216:219], v[70:73]
	v_mfma_f32_16x16x32_bf16 v[66:69], v[174:177], v[216:219], v[66:69]
	s_barrier
	s_setprio 0
	s_add_i32 s52, s71, s54
	s_mov_b32 m0, s52
	ds_read_b128 v[188:191], v185 offset:49152
	ds_read_b128 v[192:195], v185 offset:50176
	ds_read_b128 v[196:199], v185 offset:51200
	ds_read_b128 v[200:203], v185 offset:52224
	ds_read_b128 v[204:207], v185 offset:53248
	ds_read_b128 v[208:211], v185 offset:54272
	ds_read_b128 v[212:215], v185 offset:55296
	ds_read_b128 v[216:219], v185 offset:56320
	global_load_lds_dwordx4 v148, s[98:99]
	s_add_i32 m0, s52, 0x2000
	s_add_u32 s48, s48, 0x80080
	s_addc_u32 s49, s49, 0
	s_add_i32 s52, s72, s54
	global_load_lds_dwordx4 v152, s[98:99]
	s_mov_b32 m0, s52
	s_nop 0
	global_load_lds_dwordx4 v148, s[48:49]
	s_add_i32 m0, s52, 0x2000
	s_nop 0
	global_load_lds_dwordx4 v152, s[48:49]
	s_mov_b32 m0, s60
	s_nop 0
	global_load_lds_dwordx4 v146, s[100:101]
	s_mov_b32 m0, s61
	s_nop 0
	global_load_lds_dwordx4 v150, s[100:101]
	s_waitcnt vmcnt(8)
	s_waitcnt lgkmcnt(0)
	s_setprio 1
	s_barrier
	v_mfma_f32_16x16x32_bf16 v[62:65], v[130:133], v[188:191], v[62:65]
	v_mfma_f32_16x16x32_bf16 v[58:61], v[138:141], v[188:191], v[58:61]
	v_mfma_f32_16x16x32_bf16 v[46:49], v[130:133], v[196:199], v[46:49]
	v_mfma_f32_16x16x32_bf16 v[42:45], v[138:141], v[196:199], v[42:45]
	v_mfma_f32_16x16x32_bf16 v[30:33], v[130:133], v[204:207], v[30:33]
	v_mfma_f32_16x16x32_bf16 v[26:29], v[138:141], v[204:207], v[26:29]
	v_mfma_f32_16x16x32_bf16 v[14:17], v[130:133], v[212:215], v[14:17]
	v_mfma_f32_16x16x32_bf16 v[10:13], v[138:141], v[212:215], v[10:13]
	v_mfma_f32_16x16x32_bf16 v[62:65], v[134:137], v[192:195], v[62:65]
	v_mfma_f32_16x16x32_bf16 v[58:61], v[142:145], v[192:195], v[58:61]
	v_mfma_f32_16x16x32_bf16 v[46:49], v[134:137], v[200:203], v[46:49]
	v_mfma_f32_16x16x32_bf16 v[42:45], v[142:145], v[200:203], v[42:45]
	v_mfma_f32_16x16x32_bf16 v[30:33], v[134:137], v[208:211], v[30:33]
	v_mfma_f32_16x16x32_bf16 v[26:29], v[142:145], v[208:211], v[26:29]
	v_mfma_f32_16x16x32_bf16 v[14:17], v[134:137], v[216:219], v[14:17]
	v_mfma_f32_16x16x32_bf16 v[10:13], v[142:145], v[216:219], v[10:13]
	s_setprio 0
	s_setprio 1
	v_mfma_f32_16x16x32_bf16 v[54:57], v[162:165], v[188:191], v[54:57]
	v_mfma_f32_16x16x32_bf16 v[50:53], v[170:173], v[188:191], v[50:53]
	v_mfma_f32_16x16x32_bf16 v[38:41], v[162:165], v[196:199], v[38:41]
	v_mfma_f32_16x16x32_bf16 v[34:37], v[170:173], v[196:199], v[34:37]
	v_mfma_f32_16x16x32_bf16 v[22:25], v[162:165], v[204:207], v[22:25]
	v_mfma_f32_16x16x32_bf16 v[18:21], v[170:173], v[204:207], v[18:21]
	v_mfma_f32_16x16x32_bf16 v[6:9], v[162:165], v[212:215], v[6:9]
	v_mfma_f32_16x16x32_bf16 v[2:5], v[170:173], v[212:215], v[2:5]
	v_mfma_f32_16x16x32_bf16 v[54:57], v[166:169], v[192:195], v[54:57]
	v_mfma_f32_16x16x32_bf16 v[50:53], v[174:177], v[192:195], v[50:53]
	v_mfma_f32_16x16x32_bf16 v[38:41], v[166:169], v[200:203], v[38:41]
	v_mfma_f32_16x16x32_bf16 v[34:37], v[174:177], v[200:203], v[34:37]
	v_mfma_f32_16x16x32_bf16 v[22:25], v[166:169], v[208:211], v[22:25]
	v_mfma_f32_16x16x32_bf16 v[18:21], v[174:177], v[208:211], v[18:21]
	v_mfma_f32_16x16x32_bf16 v[6:9], v[166:169], v[216:219], v[6:9]
	v_mfma_f32_16x16x32_bf16 v[2:5], v[174:177], v[216:219], v[2:5]
	s_barrier
	s_setprio 0
	s_add_i32 s70, s70, 2
	s_add_u32 s46, s46, 0x100
	s_addc_u32 s47, s47, 0
	s_add_u32 s68, s68, 0x100
	s_addc_u32 s69, s69, 0
	s_cmp_gt_u32 s70, 29
.LBB0_1408:
	ds_read_b128 v[130:133], v183
	ds_read_b128 v[134:137], v183 offset:1024
	ds_read_b128 v[138:141], v183 offset:2048
	ds_read_b128 v[142:145], v183 offset:3072
	ds_read_b128 v[162:165], v184
	ds_read_b128 v[166:169], v184 offset:1024
	ds_read_b128 v[170:173], v184 offset:2048
	ds_read_b128 v[174:177], v184 offset:3072
	s_add_u32 s48, s46, 0xfff80080
	s_addc_u32 s49, s47, -1
	s_cmp_eq_u32 s70, 28
	s_cselect_b32 s53, s39, s49
	s_cselect_b32 s52, s66, s48
	s_cselect_b32 s49, s37, s69
	s_cselect_b32 s48, s67, s68
	s_add_i32 m0, s45, 0xc000
	ds_read_b128 v[188:191], v185
	ds_read_b128 v[192:195], v185 offset:1024
	ds_read_b128 v[196:199], v185 offset:2048
	ds_read_b128 v[200:203], v185 offset:3072
	ds_read_b128 v[204:207], v185 offset:4096
	ds_read_b128 v[208:211], v185 offset:5120
	ds_read_b128 v[212:215], v185 offset:6144
	ds_read_b128 v[216:219], v185 offset:7168
	global_load_lds_dwordx4 v154, s[46:47]
	s_add_i32 m0, s45, 0xe000
	s_nop 0
	global_load_lds_dwordx4 v156, s[46:47]
	s_waitcnt vmcnt(8)
	s_waitcnt lgkmcnt(0)
	s_setprio 1
	s_barrier
	v_mfma_f32_16x16x32_bf16 v[126:129], v[130:133], v[188:191], v[126:129]
	v_mfma_f32_16x16x32_bf16 v[122:125], v[138:141], v[188:191], v[122:125]
	v_mfma_f32_16x16x32_bf16 v[110:113], v[130:133], v[196:199], v[110:113]
	v_mfma_f32_16x16x32_bf16 v[106:109], v[138:141], v[196:199], v[106:109]
	v_mfma_f32_16x16x32_bf16 v[94:97], v[130:133], v[204:207], v[94:97]
	v_mfma_f32_16x16x32_bf16 v[90:93], v[138:141], v[204:207], v[90:93]
	v_mfma_f32_16x16x32_bf16 v[78:81], v[130:133], v[212:215], v[78:81]
	v_mfma_f32_16x16x32_bf16 v[74:77], v[138:141], v[212:215], v[74:77]
	v_mfma_f32_16x16x32_bf16 v[126:129], v[134:137], v[192:195], v[126:129]
	v_mfma_f32_16x16x32_bf16 v[122:125], v[142:145], v[192:195], v[122:125]
	v_mfma_f32_16x16x32_bf16 v[110:113], v[134:137], v[200:203], v[110:113]
	v_mfma_f32_16x16x32_bf16 v[106:109], v[142:145], v[200:203], v[106:109]
	v_mfma_f32_16x16x32_bf16 v[94:97], v[134:137], v[208:211], v[94:97]
	v_mfma_f32_16x16x32_bf16 v[90:93], v[142:145], v[208:211], v[90:93]
	v_mfma_f32_16x16x32_bf16 v[78:81], v[134:137], v[216:219], v[78:81]
	v_mfma_f32_16x16x32_bf16 v[74:77], v[142:145], v[216:219], v[74:77]
	s_setprio 0
	s_setprio 1
	v_mfma_f32_16x16x32_bf16 v[118:121], v[162:165], v[188:191], v[118:121]
	v_mfma_f32_16x16x32_bf16 v[114:117], v[170:173], v[188:191], v[114:117]
	v_mfma_f32_16x16x32_bf16 v[102:105], v[162:165], v[196:199], v[102:105]
	v_mfma_f32_16x16x32_bf16 v[98:101], v[170:173], v[196:199], v[98:101]
	v_mfma_f32_16x16x32_bf16 v[86:89], v[162:165], v[204:207], v[86:89]
	v_mfma_f32_16x16x32_bf16 v[82:85], v[170:173], v[204:207], v[82:85]
	v_mfma_f32_16x16x32_bf16 v[70:73], v[162:165], v[212:215], v[70:73]
	v_mfma_f32_16x16x32_bf16 v[66:69], v[170:173], v[212:215], v[66:69]
	v_mfma_f32_16x16x32_bf16 v[118:121], v[166:169], v[192:195], v[118:121]
	v_mfma_f32_16x16x32_bf16 v[114:117], v[174:177], v[192:195], v[114:117]
	v_mfma_f32_16x16x32_bf16 v[102:105], v[166:169], v[200:203], v[102:105]
	v_mfma_f32_16x16x32_bf16 v[98:101], v[174:177], v[200:203], v[98:101]
	v_mfma_f32_16x16x32_bf16 v[86:89], v[166:169], v[208:211], v[86:89]
	v_mfma_f32_16x16x32_bf16 v[82:85], v[174:177], v[208:211], v[82:85]
	v_mfma_f32_16x16x32_bf16 v[70:73], v[166:169], v[216:219], v[70:73]
	v_mfma_f32_16x16x32_bf16 v[66:69], v[174:177], v[216:219], v[66:69]
	s_barrier
	s_setprio 0
	s_add_i32 s71, s63, s54
	s_add_u32 s98, s48, 0x80
	s_addc_u32 s99, s49, 0
	s_mov_b32 m0, s71
	ds_read_b128 v[188:191], v185 offset:16384
	ds_read_b128 v[192:195], v185 offset:17408
	ds_read_b128 v[196:199], v185 offset:18432
	ds_read_b128 v[200:203], v185 offset:19456
	ds_read_b128 v[204:207], v185 offset:20480
	ds_read_b128 v[208:211], v185 offset:21504
	ds_read_b128 v[212:215], v185 offset:22528
	ds_read_b128 v[216:219], v185 offset:23552
	global_load_lds_dwordx4 v148, s[48:49]
	s_add_i32 m0, s71, 0x2000
	s_add_u32 s72, s48, 0x80000
	s_addc_u32 s73, s49, 0
	s_add_i32 s71, s64, s54
	global_load_lds_dwordx4 v152, s[48:49]
	s_mov_b32 m0, s71
	s_nop 0
	global_load_lds_dwordx4 v148, s[72:73]
	s_add_i32 m0, s71, 0x2000
	s_nop 0
	global_load_lds_dwordx4 v152, s[72:73]
	s_add_u32 s100, s52, 0x80
	s_addc_u32 s101, s53, 0
	s_mov_b32 m0, s45
	s_nop 0
	global_load_lds_dwordx4 v146, s[52:53]
	s_mov_b32 m0, s55
	s_nop 0
	global_load_lds_dwordx4 v150, s[52:53]
	s_waitcnt vmcnt(8)
	s_waitcnt lgkmcnt(0)
	s_setprio 1
	s_barrier
	v_mfma_f32_16x16x32_bf16 v[62:65], v[130:133], v[188:191], v[62:65]
	v_mfma_f32_16x16x32_bf16 v[58:61], v[138:141], v[188:191], v[58:61]
	v_mfma_f32_16x16x32_bf16 v[46:49], v[130:133], v[196:199], v[46:49]
	v_mfma_f32_16x16x32_bf16 v[42:45], v[138:141], v[196:199], v[42:45]
	v_mfma_f32_16x16x32_bf16 v[30:33], v[130:133], v[204:207], v[30:33]
	v_mfma_f32_16x16x32_bf16 v[26:29], v[138:141], v[204:207], v[26:29]
	v_mfma_f32_16x16x32_bf16 v[14:17], v[130:133], v[212:215], v[14:17]
	v_mfma_f32_16x16x32_bf16 v[10:13], v[138:141], v[212:215], v[10:13]
	v_mfma_f32_16x16x32_bf16 v[62:65], v[134:137], v[192:195], v[62:65]
	v_mfma_f32_16x16x32_bf16 v[58:61], v[142:145], v[192:195], v[58:61]
	v_mfma_f32_16x16x32_bf16 v[46:49], v[134:137], v[200:203], v[46:49]
	v_mfma_f32_16x16x32_bf16 v[42:45], v[142:145], v[200:203], v[42:45]
	v_mfma_f32_16x16x32_bf16 v[30:33], v[134:137], v[208:211], v[30:33]
	v_mfma_f32_16x16x32_bf16 v[26:29], v[142:145], v[208:211], v[26:29]
	v_mfma_f32_16x16x32_bf16 v[14:17], v[134:137], v[216:219], v[14:17]
	v_mfma_f32_16x16x32_bf16 v[10:13], v[142:145], v[216:219], v[10:13]
	s_setprio 0
	s_setprio 1
	v_mfma_f32_16x16x32_bf16 v[54:57], v[162:165], v[188:191], v[54:57]
	v_mfma_f32_16x16x32_bf16 v[50:53], v[170:173], v[188:191], v[50:53]
	v_mfma_f32_16x16x32_bf16 v[38:41], v[162:165], v[196:199], v[38:41]
	v_mfma_f32_16x16x32_bf16 v[34:37], v[170:173], v[196:199], v[34:37]
	v_mfma_f32_16x16x32_bf16 v[22:25], v[162:165], v[204:207], v[22:25]
	v_mfma_f32_16x16x32_bf16 v[18:21], v[170:173], v[204:207], v[18:21]
	v_mfma_f32_16x16x32_bf16 v[6:9], v[162:165], v[212:215], v[6:9]
	v_mfma_f32_16x16x32_bf16 v[2:5], v[170:173], v[212:215], v[2:5]
	v_mfma_f32_16x16x32_bf16 v[54:57], v[166:169], v[192:195], v[54:57]
	v_mfma_f32_16x16x32_bf16 v[50:53], v[174:177], v[192:195], v[50:53]
	v_mfma_f32_16x16x32_bf16 v[38:41], v[166:169], v[200:203], v[38:41]
	v_mfma_f32_16x16x32_bf16 v[34:37], v[174:177], v[200:203], v[34:37]
	v_mfma_f32_16x16x32_bf16 v[22:25], v[166:169], v[208:211], v[22:25]
	v_mfma_f32_16x16x32_bf16 v[18:21], v[174:177], v[208:211], v[18:21]
	v_mfma_f32_16x16x32_bf16 v[6:9], v[166:169], v[216:219], v[6:9]
	v_mfma_f32_16x16x32_bf16 v[2:5], v[174:177], v[216:219], v[2:5]
	s_barrier
	s_setprio 0
	s_add_i32 s71, 0, 0x18000
	v_add_u32_e32 v1, s71, v181
	s_add_i32 s72, 0, 0x1c000
	ds_read_b128 v[130:133], v1
	ds_read_b128 v[134:137], v1 offset:1024
	ds_read_b128 v[138:141], v1 offset:2048
	ds_read_b128 v[142:145], v1 offset:3072
	v_add_u32_e32 v1, s72, v181
	ds_read_b128 v[162:165], v1
	ds_read_b128 v[166:169], v1 offset:1024
	ds_read_b128 v[170:173], v1 offset:2048
	ds_read_b128 v[174:177], v1 offset:3072
	s_add_u32 s52, s52, 0x80000
	s_addc_u32 s53, s53, 0
	s_mov_b32 m0, s56
	ds_read_b128 v[188:191], v185 offset:32768
	ds_read_b128 v[192:195], v185 offset:33792
	ds_read_b128 v[196:199], v185 offset:34816
	ds_read_b128 v[200:203], v185 offset:35840
	ds_read_b128 v[204:207], v185 offset:36864
	ds_read_b128 v[208:211], v185 offset:37888
	ds_read_b128 v[212:215], v185 offset:38912
	ds_read_b128 v[216:219], v185 offset:39936
	global_load_lds_dwordx4 v146, s[52:53]
	s_mov_b32 m0, s57
	s_nop 0
	global_load_lds_dwordx4 v150, s[52:53]
	s_waitcnt vmcnt(8)
	s_waitcnt lgkmcnt(0)
	s_setprio 1
	s_barrier
	v_mfma_f32_16x16x32_bf16 v[126:129], v[130:133], v[188:191], v[126:129]
	v_mfma_f32_16x16x32_bf16 v[122:125], v[138:141], v[188:191], v[122:125]
	v_mfma_f32_16x16x32_bf16 v[110:113], v[130:133], v[196:199], v[110:113]
	v_mfma_f32_16x16x32_bf16 v[106:109], v[138:141], v[196:199], v[106:109]
	v_mfma_f32_16x16x32_bf16 v[94:97], v[130:133], v[204:207], v[94:97]
	v_mfma_f32_16x16x32_bf16 v[90:93], v[138:141], v[204:207], v[90:93]
	v_mfma_f32_16x16x32_bf16 v[78:81], v[130:133], v[212:215], v[78:81]
	v_mfma_f32_16x16x32_bf16 v[74:77], v[138:141], v[212:215], v[74:77]
	v_mfma_f32_16x16x32_bf16 v[126:129], v[134:137], v[192:195], v[126:129]
	v_mfma_f32_16x16x32_bf16 v[122:125], v[142:145], v[192:195], v[122:125]
	v_mfma_f32_16x16x32_bf16 v[110:113], v[134:137], v[200:203], v[110:113]
	v_mfma_f32_16x16x32_bf16 v[106:109], v[142:145], v[200:203], v[106:109]
	v_mfma_f32_16x16x32_bf16 v[94:97], v[134:137], v[208:211], v[94:97]
	v_mfma_f32_16x16x32_bf16 v[90:93], v[142:145], v[208:211], v[90:93]
	v_mfma_f32_16x16x32_bf16 v[78:81], v[134:137], v[216:219], v[78:81]
	v_mfma_f32_16x16x32_bf16 v[74:77], v[142:145], v[216:219], v[74:77]
	s_setprio 0
	s_setprio 1
	v_mfma_f32_16x16x32_bf16 v[118:121], v[162:165], v[188:191], v[118:121]
	v_mfma_f32_16x16x32_bf16 v[114:117], v[170:173], v[188:191], v[114:117]
	v_mfma_f32_16x16x32_bf16 v[102:105], v[162:165], v[196:199], v[102:105]
	v_mfma_f32_16x16x32_bf16 v[98:101], v[170:173], v[196:199], v[98:101]
	v_mfma_f32_16x16x32_bf16 v[86:89], v[162:165], v[204:207], v[86:89]
	v_mfma_f32_16x16x32_bf16 v[82:85], v[170:173], v[204:207], v[82:85]
	v_mfma_f32_16x16x32_bf16 v[70:73], v[162:165], v[212:215], v[70:73]
	v_mfma_f32_16x16x32_bf16 v[66:69], v[170:173], v[212:215], v[66:69]
	v_mfma_f32_16x16x32_bf16 v[118:121], v[166:169], v[192:195], v[118:121]
	v_mfma_f32_16x16x32_bf16 v[114:117], v[174:177], v[192:195], v[114:117]
	v_mfma_f32_16x16x32_bf16 v[102:105], v[166:169], v[200:203], v[102:105]
	v_mfma_f32_16x16x32_bf16 v[98:101], v[174:177], v[200:203], v[98:101]
	v_mfma_f32_16x16x32_bf16 v[86:89], v[166:169], v[208:211], v[86:89]
	v_mfma_f32_16x16x32_bf16 v[82:85], v[174:177], v[208:211], v[82:85]
	v_mfma_f32_16x16x32_bf16 v[70:73], v[166:169], v[216:219], v[70:73]
	v_mfma_f32_16x16x32_bf16 v[66:69], v[174:177], v[216:219], v[66:69]
	s_barrier
	s_setprio 0
	s_add_i32 s52, s71, s54
	s_mov_b32 m0, s52
	ds_read_b128 v[188:191], v185 offset:49152
	ds_read_b128 v[192:195], v185 offset:50176
	ds_read_b128 v[196:199], v185 offset:51200
	ds_read_b128 v[200:203], v185 offset:52224
	ds_read_b128 v[204:207], v185 offset:53248
	ds_read_b128 v[208:211], v185 offset:54272
	ds_read_b128 v[212:215], v185 offset:55296
	ds_read_b128 v[216:219], v185 offset:56320
	global_load_lds_dwordx4 v148, s[98:99]
	s_add_i32 m0, s52, 0x2000
	s_add_u32 s48, s48, 0x80080
	s_addc_u32 s49, s49, 0
	s_add_i32 s52, s72, s54
	global_load_lds_dwordx4 v152, s[98:99]
	s_mov_b32 m0, s52
	s_nop 0
	global_load_lds_dwordx4 v148, s[48:49]
	s_add_i32 m0, s52, 0x2000
	s_nop 0
	global_load_lds_dwordx4 v152, s[48:49]
	s_mov_b32 m0, s60
	s_nop 0
	global_load_lds_dwordx4 v146, s[100:101]
	s_mov_b32 m0, s61
	s_nop 0
	global_load_lds_dwordx4 v150, s[100:101]
	s_add_i32 s70, s70, 2
	s_add_u32 s46, s46, 0x100
	s_addc_u32 s47, s47, 0
	s_add_u32 s68, s68, 0x100
	s_addc_u32 s69, s69, 0
	s_cmp_gt_u32 s70, 29
	s_waitcnt vmcnt(8)
	s_waitcnt lgkmcnt(0)
	s_setprio 1
	s_barrier
	v_mfma_f32_16x16x32_bf16 v[62:65], v[130:133], v[188:191], v[62:65]
	v_mfma_f32_16x16x32_bf16 v[58:61], v[138:141], v[188:191], v[58:61]
	v_mfma_f32_16x16x32_bf16 v[46:49], v[130:133], v[196:199], v[46:49]
	v_mfma_f32_16x16x32_bf16 v[42:45], v[138:141], v[196:199], v[42:45]
	v_mfma_f32_16x16x32_bf16 v[30:33], v[130:133], v[204:207], v[30:33]
	v_mfma_f32_16x16x32_bf16 v[26:29], v[138:141], v[204:207], v[26:29]
	v_mfma_f32_16x16x32_bf16 v[14:17], v[130:133], v[212:215], v[14:17]
	v_mfma_f32_16x16x32_bf16 v[10:13], v[138:141], v[212:215], v[10:13]
	v_mfma_f32_16x16x32_bf16 v[62:65], v[134:137], v[192:195], v[62:65]
	v_mfma_f32_16x16x32_bf16 v[58:61], v[142:145], v[192:195], v[58:61]
	v_mfma_f32_16x16x32_bf16 v[46:49], v[134:137], v[200:203], v[46:49]
	v_mfma_f32_16x16x32_bf16 v[42:45], v[142:145], v[200:203], v[42:45]
	v_mfma_f32_16x16x32_bf16 v[30:33], v[134:137], v[208:211], v[30:33]
	v_mfma_f32_16x16x32_bf16 v[26:29], v[142:145], v[208:211], v[26:29]
	v_mfma_f32_16x16x32_bf16 v[14:17], v[134:137], v[216:219], v[14:17]
	v_mfma_f32_16x16x32_bf16 v[10:13], v[142:145], v[216:219], v[10:13]
	s_setprio 0
	s_setprio 1
	v_mfma_f32_16x16x32_bf16 v[54:57], v[162:165], v[188:191], v[54:57]
	v_mfma_f32_16x16x32_bf16 v[50:53], v[170:173], v[188:191], v[50:53]
	v_mfma_f32_16x16x32_bf16 v[38:41], v[162:165], v[196:199], v[38:41]
	v_mfma_f32_16x16x32_bf16 v[34:37], v[170:173], v[196:199], v[34:37]
	v_mfma_f32_16x16x32_bf16 v[22:25], v[162:165], v[204:207], v[22:25]
	v_mfma_f32_16x16x32_bf16 v[18:21], v[170:173], v[204:207], v[18:21]
	v_mfma_f32_16x16x32_bf16 v[6:9], v[162:165], v[212:215], v[6:9]
	v_mfma_f32_16x16x32_bf16 v[2:5], v[170:173], v[212:215], v[2:5]
	v_mfma_f32_16x16x32_bf16 v[54:57], v[166:169], v[192:195], v[54:57]
	v_mfma_f32_16x16x32_bf16 v[50:53], v[174:177], v[192:195], v[50:53]
	v_mfma_f32_16x16x32_bf16 v[38:41], v[166:169], v[200:203], v[38:41]
	v_mfma_f32_16x16x32_bf16 v[34:37], v[174:177], v[200:203], v[34:37]
	v_mfma_f32_16x16x32_bf16 v[22:25], v[166:169], v[208:211], v[22:25]
	v_mfma_f32_16x16x32_bf16 v[18:21], v[174:177], v[208:211], v[18:21]
	v_mfma_f32_16x16x32_bf16 v[6:9], v[166:169], v[216:219], v[6:9]
	v_mfma_f32_16x16x32_bf16 v[2:5], v[174:177], v[216:219], v[2:5]
	s_barrier
	s_setprio 0
	s_cbranch_scc0 .LBB0_1408
	s_and_b64 vcc, exec, s[34:35]
	s_cbranch_vccz .LBB0_1411
	s_barrier

.LBB0_1473:
	s_add_u32 s14, s26, 0x11c00000
	s_addc_u32 s15, s27, 0
	s_add_u32 s16, s26, 0x40000
	s_addc_u32 s17, s27, 0
	s_lshl_b32 s7, s7, 5
	s_mov_b64 s[30:31], 0x80
	s_and_b32 s7, s7, 0x60
	s_add_i32 m0, s44, 0x18000
	v_lshl_add_u64 v[8:9], v[8:9], 0, s[30:31]
	s_lshl_b32 s11, s6, 13
	s_lshl_b32 s34, s7, 7
	s_waitcnt vmcnt(2)
	s_barrier
	global_load_lds_dwordx4 v[8:9], off
	v_lshl_add_u64 v[6:7], v[6:7], 0, s[30:31]
	s_add_i32 m0, s44, 0x1a000
	s_add_i32 s48, s44, 0x8000
	s_add_i32 s49, s44, 0xa000
	global_load_lds_dwordx4 v[6:7], off
	v_lshl_add_u64 v[2:3], v[2:3], 0, s[30:31]
	s_mov_b32 m0, s48
	s_add_u32 s8, s4, 0x80080
	global_load_lds_dwordx4 v[2:3], off
	v_lshl_add_u64 v[2:3], v[4:5], 0, s[30:31]
	s_mov_b32 m0, s49
	s_addc_u32 s9, s5, 0
	global_load_lds_dwordx4 v[2:3], off
	s_add_i32 m0, s44, 0x1c000
	s_nop 0
	global_load_lds_dwordx4 v142, s[8:9]
	s_add_i32 m0, s44, 0x1e000
	s_sext_i32_i16 s59, s2
	global_load_lds_dwordx4 v138, s[8:9]
	v_and_b32_e32 v2, 15, v0
	v_lshlrev_b32_e32 v3, 1, v13
	v_lshlrev_b32_e32 v4, 2, v0
	v_lshlrev_b32_e32 v5, 6, v0
	s_movk_i32 s2, 0x3c0
	v_lshl_or_b32 v1, s6, 6, v2
	v_lshl_or_b32 v2, v2, 6, v3
	v_and_b32_e32 v4, 32, v4
	v_and_or_b32 v3, v5, s2, v3
	v_bitop3_b32 v163, s34, v3, v4 bitop3:0xf6
	v_lshlrev_b32_e32 v3, 9, v0
	v_bitop3_b32 v2, v2, s11, v4 bitop3:0xde
	v_and_b32_e32 v3, 0x30000, v3
	v_lshlrev_b32_e32 v4, 12, v14
	v_or3_b32 v3, v11, v3, v4
	v_add_u32_e32 v146, v3, v12
	v_lshlrev_b32_e32 v3, 5, v10
	s_waitcnt vmcnt(6)
	s_cmpk_lt_u32 s3, 0x100
	v_and_b32_e32 v3, 0x70000, v3
	v_mov_b32_e32 v154, 1.0
	s_cselect_b64 s[34:35], -1, 0
	v_or3_b32 v3, v11, v3, v4
	v_mov_b32_e32 v155, v154
	s_add_i32 s54, 0, 0x10000
	s_add_i32 s55, 0, 0x14000
	s_mov_b32 s52, 0
	s_ashr_i32 s53, s33, 31
	v_or_b32_e32 v165, s7, v13
	v_mov_b32_e32 v147, v143
	v_add_u32_e32 v148, v3, v12
	v_mov_b32_e32 v149, v143
	s_mov_b32 s8, -1
	v_mov_b64_e32 v[150:151], 0x1600
	v_mov_b64_e32 v[152:153], 0x15ff
	v_add_u32_e32 v174, s54, v163
	v_add_u32_e32 v175, s55, v163
	v_add_u32_e32 v176, 0, v2
	v_mov_b32_e32 v177, 0x358637bd
	s_mov_b32 s56, 0xf800000
	v_mov_b32_e32 v178, 0x260
	s_movk_i32 s57, 0x2c00
	v_mov_b64_e32 v[156:157], v[154:155]
	v_mov_b32_e32 v66, v154
	v_mov_b32_e32 v67, v154
	v_mov_b32_e32 v179, v154
	v_mov_b32_e32 v180, v154
	s_barrier
	s_branch .LBB0_1476

.LBB0_1478:
	s_ashr_i32 s11, s10, 31
	s_lshl_b64 s[6:7], s[10:11], 20
	s_add_u32 s38, s19, s6
	s_addc_u32 s39, s22, s7
	s_and_b64 s[6:7], s[2:3], exec
	s_cselect_b32 s9, s39, s1
	s_cselect_b32 s11, s38, s0
	s_ashr_i32 s37, s36, 31
	s_lshl_b64 s[6:7], s[36:37], 20
	s_add_u32 s40, s23, s6
	s_addc_u32 s41, s28, s7
	s_and_b64 s[6:7], s[2:3], exec
	s_cselect_b32 s37, s41, s5
	s_cselect_b32 s60, s40, s4
	s_add_u32 s0, s0, 0x80080
	s_addc_u32 s1, s1, 0
	s_add_u32 s61, s4, 0x100
	s_addc_u32 s62, s5, 0
	s_mov_b32 s63, -2
	ds_read_b128 v[132:135], v174
	ds_read_b128 v[158:161], v174 offset:1024
	ds_read_b128 v[166:169], v174 offset:2048
	ds_read_b128 v[170:173], v174 offset:3072
	ds_read_b128 v[182:185], v175
	ds_read_b128 v[186:189], v175 offset:1024
	ds_read_b128 v[190:193], v175 offset:2048
	ds_read_b128 v[194:197], v175 offset:3072
	s_add_u32 s4, s0, 0xfff80080
	s_addc_u32 s5, s1, -1
	s_cmp_eq_u32 s63, 28
	s_cselect_b32 s7, s9, s5
	s_cselect_b32 s6, s11, s4
	s_cselect_b32 s5, s37, s62
	s_cselect_b32 s4, s60, s61
	s_add_i32 m0, s44, 0xc000
	ds_read_b128 v[198:201], v176
	ds_read_b128 v[202:205], v176 offset:1024
	ds_read_b128 v[206:209], v176 offset:2048
	ds_read_b128 v[210:213], v176 offset:3072
	ds_read_b128 v[214:217], v176 offset:4096
	ds_read_b128 v[218:221], v176 offset:5120
	ds_read_b128 v[222:225], v176 offset:6144
	ds_read_b128 v[226:229], v176 offset:7168
	global_load_lds_dwordx4 v146, s[0:1]
	s_add_i32 m0, s44, 0xe000
	s_nop 0
	global_load_lds_dwordx4 v148, s[0:1]
	s_waitcnt vmcnt(8)
	s_waitcnt lgkmcnt(0)
	s_setprio 1
	s_barrier
	v_mfma_f32_16x16x32_bf16 v[128:131], v[132:135], v[198:201], 0
	v_mfma_f32_16x16x32_bf16 v[124:127], v[166:169], v[198:201], 0
	v_mfma_f32_16x16x32_bf16 v[112:115], v[132:135], v[206:209], 0
	v_mfma_f32_16x16x32_bf16 v[108:111], v[166:169], v[206:209], 0
	v_mfma_f32_16x16x32_bf16 v[96:99], v[132:135], v[214:217], 0
	v_mfma_f32_16x16x32_bf16 v[92:95], v[166:169], v[214:217], 0
	v_mfma_f32_16x16x32_bf16 v[80:83], v[132:135], v[222:225], 0
	v_mfma_f32_16x16x32_bf16 v[76:79], v[166:169], v[222:225], 0
	v_mfma_f32_16x16x32_bf16 v[128:131], v[158:161], v[202:205], v[128:131]
	v_mfma_f32_16x16x32_bf16 v[124:127], v[170:173], v[202:205], v[124:127]
	v_mfma_f32_16x16x32_bf16 v[112:115], v[158:161], v[210:213], v[112:115]
	v_mfma_f32_16x16x32_bf16 v[108:111], v[170:173], v[210:213], v[108:111]
	v_mfma_f32_16x16x32_bf16 v[96:99], v[158:161], v[218:221], v[96:99]
	v_mfma_f32_16x16x32_bf16 v[92:95], v[170:173], v[218:221], v[92:95]
	v_mfma_f32_16x16x32_bf16 v[80:83], v[158:161], v[226:229], v[80:83]
	v_mfma_f32_16x16x32_bf16 v[76:79], v[170:173], v[226:229], v[76:79]
	s_setprio 0
	s_setprio 1
	v_mfma_f32_16x16x32_bf16 v[120:123], v[182:185], v[198:201], 0
	v_mfma_f32_16x16x32_bf16 v[116:119], v[190:193], v[198:201], 0
	v_mfma_f32_16x16x32_bf16 v[104:107], v[182:185], v[206:209], 0
	v_mfma_f32_16x16x32_bf16 v[100:103], v[190:193], v[206:209], 0
	v_mfma_f32_16x16x32_bf16 v[88:91], v[182:185], v[214:217], 0
	v_mfma_f32_16x16x32_bf16 v[84:87], v[190:193], v[214:217], 0
	v_mfma_f32_16x16x32_bf16 v[72:75], v[182:185], v[222:225], 0
	v_mfma_f32_16x16x32_bf16 v[68:71], v[190:193], v[222:225], 0
	v_mfma_f32_16x16x32_bf16 v[120:123], v[186:189], v[202:205], v[120:123]
	v_mfma_f32_16x16x32_bf16 v[116:119], v[194:197], v[202:205], v[116:119]
	v_mfma_f32_16x16x32_bf16 v[104:107], v[186:189], v[210:213], v[104:107]
	v_mfma_f32_16x16x32_bf16 v[100:103], v[194:197], v[210:213], v[100:103]
	v_mfma_f32_16x16x32_bf16 v[88:91], v[186:189], v[218:221], v[88:91]
	v_mfma_f32_16x16x32_bf16 v[84:87], v[194:197], v[218:221], v[84:87]
	v_mfma_f32_16x16x32_bf16 v[72:75], v[186:189], v[226:229], v[72:75]
	v_mfma_f32_16x16x32_bf16 v[68:71], v[194:197], v[226:229], v[68:71]
	s_barrier
	s_setprio 0
	s_add_i32 s64, s54, s29
	s_add_u32 s98, s4, 0x80
	s_addc_u32 s99, s5, 0
	s_mov_b32 m0, s64
	ds_read_b128 v[198:201], v176 offset:16384
	ds_read_b128 v[202:205], v176 offset:17408
	ds_read_b128 v[206:209], v176 offset:18432
	ds_read_b128 v[210:213], v176 offset:19456
	ds_read_b128 v[214:217], v176 offset:20480
	ds_read_b128 v[218:221], v176 offset:21504
	ds_read_b128 v[222:225], v176 offset:22528
	ds_read_b128 v[226:229], v176 offset:23552
	global_load_lds_dwordx4 v142, s[4:5]
	s_add_i32 m0, s64, 0x2000
	s_add_u32 s64, s4, 0x80000
	s_addc_u32 s65, s5, 0
	s_add_i32 s66, s55, s29
	global_load_lds_dwordx4 v138, s[4:5]
	s_mov_b32 m0, s66
	s_nop 0
	global_load_lds_dwordx4 v142, s[64:65]
	s_add_i32 m0, s66, 0x2000
	s_nop 0
	global_load_lds_dwordx4 v138, s[64:65]
	s_add_u32 s100, s6, 0x80
	s_addc_u32 s101, s7, 0
	s_mov_b32 m0, s44
	s_nop 0
	global_load_lds_dwordx4 v144, s[6:7]
	s_mov_b32 m0, s45
	s_nop 0
	global_load_lds_dwordx4 v140, s[6:7]
	s_waitcnt vmcnt(8)
	s_waitcnt lgkmcnt(0)
	s_setprio 1
	s_barrier
	v_mfma_f32_16x16x32_bf16 v[62:65], v[132:135], v[198:201], 0
	v_mfma_f32_16x16x32_bf16 v[58:61], v[166:169], v[198:201], 0
	v_mfma_f32_16x16x32_bf16 v[46:49], v[132:135], v[206:209], 0
	v_mfma_f32_16x16x32_bf16 v[42:45], v[166:169], v[206:209], 0
	v_mfma_f32_16x16x32_bf16 v[30:33], v[132:135], v[214:217], 0
	v_mfma_f32_16x16x32_bf16 v[26:29], v[166:169], v[214:217], 0
	v_mfma_f32_16x16x32_bf16 v[14:17], v[132:135], v[222:225], 0
	v_mfma_f32_16x16x32_bf16 v[10:13], v[166:169], v[222:225], 0
	v_mfma_f32_16x16x32_bf16 v[62:65], v[158:161], v[202:205], v[62:65]
	v_mfma_f32_16x16x32_bf16 v[58:61], v[170:173], v[202:205], v[58:61]
	v_mfma_f32_16x16x32_bf16 v[46:49], v[158:161], v[210:213], v[46:49]
	v_mfma_f32_16x16x32_bf16 v[42:45], v[170:173], v[210:213], v[42:45]
	v_mfma_f32_16x16x32_bf16 v[30:33], v[158:161], v[218:221], v[30:33]
	v_mfma_f32_16x16x32_bf16 v[26:29], v[170:173], v[218:221], v[26:29]
	v_mfma_f32_16x16x32_bf16 v[14:17], v[158:161], v[226:229], v[14:17]
	v_mfma_f32_16x16x32_bf16 v[10:13], v[170:173], v[226:229], v[10:13]
	s_setprio 0
	s_setprio 1
	v_mfma_f32_16x16x32_bf16 v[54:57], v[182:185], v[198:201], 0
	v_mfma_f32_16x16x32_bf16 v[50:53], v[190:193], v[198:201], 0
	v_mfma_f32_16x16x32_bf16 v[38:41], v[182:185], v[206:209], 0
	v_mfma_f32_16x16x32_bf16 v[34:37], v[190:193], v[206:209], 0
	v_mfma_f32_16x16x32_bf16 v[22:25], v[182:185], v[214:217], 0
	v_mfma_f32_16x16x32_bf16 v[18:21], v[190:193], v[214:217], 0
	v_mfma_f32_16x16x32_bf16 v[6:9], v[182:185], v[222:225], 0
	v_mfma_f32_16x16x32_bf16 v[2:5], v[190:193], v[222:225], 0
	v_mfma_f32_16x16x32_bf16 v[54:57], v[186:189], v[202:205], v[54:57]
	v_mfma_f32_16x16x32_bf16 v[50:53], v[194:197], v[202:205], v[50:53]
	v_mfma_f32_16x16x32_bf16 v[38:41], v[186:189], v[210:213], v[38:41]
	v_mfma_f32_16x16x32_bf16 v[34:37], v[194:197], v[210:213], v[34:37]
	v_mfma_f32_16x16x32_bf16 v[22:25], v[186:189], v[218:221], v[22:25]
	v_mfma_f32_16x16x32_bf16 v[18:21], v[194:197], v[218:221], v[18:21]
	v_mfma_f32_16x16x32_bf16 v[6:9], v[186:189], v[226:229], v[6:9]
	v_mfma_f32_16x16x32_bf16 v[2:5], v[194:197], v[226:229], v[2:5]
	s_barrier
	s_setprio 0
	s_add_i32 s64, 0, 0x18000
	v_add_u32_e32 v162, s64, v163
	s_add_i32 s65, 0, 0x1c000
	ds_read_b128 v[132:135], v162
	ds_read_b128 v[158:161], v162 offset:1024
	ds_read_b128 v[166:169], v162 offset:2048
	ds_read_b128 v[170:173], v162 offset:3072
	v_add_u32_e32 v162, s65, v163
	ds_read_b128 v[182:185], v162
	ds_read_b128 v[186:189], v162 offset:1024
	ds_read_b128 v[190:193], v162 offset:2048
	ds_read_b128 v[194:197], v162 offset:3072
	s_add_u32 s6, s6, 0x80000
	s_addc_u32 s7, s7, 0
	s_mov_b32 m0, s46
	ds_read_b128 v[198:201], v176 offset:32768
	ds_read_b128 v[202:205], v176 offset:33792
	ds_read_b128 v[206:209], v176 offset:34816
	ds_read_b128 v[210:213], v176 offset:35840
	ds_read_b128 v[214:217], v176 offset:36864
	ds_read_b128 v[218:221], v176 offset:37888
	ds_read_b128 v[222:225], v176 offset:38912
	ds_read_b128 v[226:229], v176 offset:39936
	global_load_lds_dwordx4 v144, s[6:7]
	s_mov_b32 m0, s47
	s_nop 0
	global_load_lds_dwordx4 v140, s[6:7]
	s_waitcnt vmcnt(8)
	s_waitcnt lgkmcnt(0)
	s_setprio 1
	s_barrier
	v_mfma_f32_16x16x32_bf16 v[128:131], v[132:135], v[198:201], v[128:131]
	v_mfma_f32_16x16x32_bf16 v[124:127], v[166:169], v[198:201], v[124:127]
	v_mfma_f32_16x16x32_bf16 v[112:115], v[132:135], v[206:209], v[112:115]
	v_mfma_f32_16x16x32_bf16 v[108:111], v[166:169], v[206:209], v[108:111]
	v_mfma_f32_16x16x32_bf16 v[96:99], v[132:135], v[214:217], v[96:99]
	v_mfma_f32_16x16x32_bf16 v[92:95], v[166:169], v[214:217], v[92:95]
	v_mfma_f32_16x16x32_bf16 v[80:83], v[132:135], v[222:225], v[80:83]
	v_mfma_f32_16x16x32_bf16 v[76:79], v[166:169], v[222:225], v[76:79]
	v_mfma_f32_16x16x32_bf16 v[128:131], v[158:161], v[202:205], v[128:131]
	v_mfma_f32_16x16x32_bf16 v[124:127], v[170:173], v[202:205], v[124:127]
	v_mfma_f32_16x16x32_bf16 v[112:115], v[158:161], v[210:213], v[112:115]
	v_mfma_f32_16x16x32_bf16 v[108:111], v[170:173], v[210:213], v[108:111]
	v_mfma_f32_16x16x32_bf16 v[96:99], v[158:161], v[218:221], v[96:99]
	v_mfma_f32_16x16x32_bf16 v[92:95], v[170:173], v[218:221], v[92:95]
	v_mfma_f32_16x16x32_bf16 v[80:83], v[158:161], v[226:229], v[80:83]
	v_mfma_f32_16x16x32_bf16 v[76:79], v[170:173], v[226:229], v[76:79]
	s_setprio 0
	s_setprio 1
	v_mfma_f32_16x16x32_bf16 v[120:123], v[182:185], v[198:201], v[120:123]
	v_mfma_f32_16x16x32_bf16 v[116:119], v[190:193], v[198:201], v[116:119]
	v_mfma_f32_16x16x32_bf16 v[104:107], v[182:185], v[206:209], v[104:107]
	v_mfma_f32_16x16x32_bf16 v[100:103], v[190:193], v[206:209], v[100:103]
	v_mfma_f32_16x16x32_bf16 v[88:91], v[182:185], v[214:217], v[88:91]
	v_mfma_f32_16x16x32_bf16 v[84:87], v[190:193], v[214:217], v[84:87]
	v_mfma_f32_16x16x32_bf16 v[72:75], v[182:185], v[222:225], v[72:75]
	v_mfma_f32_16x16x32_bf16 v[68:71], v[190:193], v[222:225], v[68:71]
	v_mfma_f32_16x16x32_bf16 v[120:123], v[186:189], v[202:205], v[120:123]
	v_mfma_f32_16x16x32_bf16 v[116:119], v[194:197], v[202:205], v[116:119]
	v_mfma_f32_16x16x32_bf16 v[104:107], v[186:189], v[210:213], v[104:107]
	v_mfma_f32_16x16x32_bf16 v[100:103], v[194:197], v[210:213], v[100:103]
	v_mfma_f32_16x16x32_bf16 v[88:91], v[186:189], v[218:221], v[88:91]
	v_mfma_f32_16x16x32_bf16 v[84:87], v[194:197], v[218:221], v[84:87]
	v_mfma_f32_16x16x32_bf16 v[72:75], v[186:189], v[226:229], v[72:75]
	v_mfma_f32_16x16x32_bf16 v[68:71], v[194:197], v[226:229], v[68:71]
	s_barrier
	s_setprio 0
	s_add_i32 s6, s64, s29
	s_mov_b32 m0, s6
	ds_read_b128 v[198:201], v176 offset:49152
	ds_read_b128 v[202:205], v176 offset:50176
	ds_read_b128 v[206:209], v176 offset:51200
	ds_read_b128 v[210:213], v176 offset:52224
	ds_read_b128 v[214:217], v176 offset:53248
	ds_read_b128 v[218:221], v176 offset:54272
	ds_read_b128 v[222:225], v176 offset:55296
	ds_read_b128 v[226:229], v176 offset:56320
	global_load_lds_dwordx4 v142, s[98:99]
	s_add_i32 m0, s6, 0x2000
	s_add_u32 s4, s4, 0x80080
	s_addc_u32 s5, s5, 0
	s_add_i32 s6, s65, s29
	global_load_lds_dwordx4 v138, s[98:99]
	s_mov_b32 m0, s6
	s_nop 0
	global_load_lds_dwordx4 v142, s[4:5]
	s_add_i32 m0, s6, 0x2000
	s_nop 0
	global_load_lds_dwordx4 v138, s[4:5]
	s_mov_b32 m0, s48
	s_nop 0
	global_load_lds_dwordx4 v144, s[100:101]
	s_mov_b32 m0, s49
	s_nop 0
	global_load_lds_dwordx4 v140, s[100:101]
	s_waitcnt vmcnt(8)
	s_waitcnt lgkmcnt(0)
	s_setprio 1
	s_barrier
	v_mfma_f32_16x16x32_bf16 v[62:65], v[132:135], v[198:201], v[62:65]
	v_mfma_f32_16x16x32_bf16 v[58:61], v[166:169], v[198:201], v[58:61]
	v_mfma_f32_16x16x32_bf16 v[46:49], v[132:135], v[206:209], v[46:49]
	v_mfma_f32_16x16x32_bf16 v[42:45], v[166:169], v[206:209], v[42:45]
	v_mfma_f32_16x16x32_bf16 v[30:33], v[132:135], v[214:217], v[30:33]
	v_mfma_f32_16x16x32_bf16 v[26:29], v[166:169], v[214:217], v[26:29]
	v_mfma_f32_16x16x32_bf16 v[14:17], v[132:135], v[222:225], v[14:17]
	v_mfma_f32_16x16x32_bf16 v[10:13], v[166:169], v[222:225], v[10:13]
	v_mfma_f32_16x16x32_bf16 v[62:65], v[158:161], v[202:205], v[62:65]
	v_mfma_f32_16x16x32_bf16 v[58:61], v[170:173], v[202:205], v[58:61]
	v_mfma_f32_16x16x32_bf16 v[46:49], v[158:161], v[210:213], v[46:49]
	v_mfma_f32_16x16x32_bf16 v[42:45], v[170:173], v[210:213], v[42:45]
	v_mfma_f32_16x16x32_bf16 v[30:33], v[158:161], v[218:221], v[30:33]
	v_mfma_f32_16x16x32_bf16 v[26:29], v[170:173], v[218:221], v[26:29]
	v_mfma_f32_16x16x32_bf16 v[14:17], v[158:161], v[226:229], v[14:17]
	v_mfma_f32_16x16x32_bf16 v[10:13], v[170:173], v[226:229], v[10:13]
	s_setprio 0
	s_setprio 1
	v_mfma_f32_16x16x32_bf16 v[54:57], v[182:185], v[198:201], v[54:57]
	v_mfma_f32_16x16x32_bf16 v[50:53], v[190:193], v[198:201], v[50:53]
	v_mfma_f32_16x16x32_bf16 v[38:41], v[182:185], v[206:209], v[38:41]
	v_mfma_f32_16x16x32_bf16 v[34:37], v[190:193], v[206:209], v[34:37]
	v_mfma_f32_16x16x32_bf16 v[22:25], v[182:185], v[214:217], v[22:25]
	v_mfma_f32_16x16x32_bf16 v[18:21], v[190:193], v[214:217], v[18:21]
	v_mfma_f32_16x16x32_bf16 v[6:9], v[182:185], v[222:225], v[6:9]
	v_mfma_f32_16x16x32_bf16 v[2:5], v[190:193], v[222:225], v[2:5]
	v_mfma_f32_16x16x32_bf16 v[54:57], v[186:189], v[202:205], v[54:57]
	v_mfma_f32_16x16x32_bf16 v[50:53], v[194:197], v[202:205], v[50:53]
	v_mfma_f32_16x16x32_bf16 v[38:41], v[186:189], v[210:213], v[38:41]
	v_mfma_f32_16x16x32_bf16 v[34:37], v[194:197], v[210:213], v[34:37]
	v_mfma_f32_16x16x32_bf16 v[22:25], v[186:189], v[218:221], v[22:25]
	v_mfma_f32_16x16x32_bf16 v[18:21], v[194:197], v[218:221], v[18:21]
	v_mfma_f32_16x16x32_bf16 v[6:9], v[186:189], v[226:229], v[6:9]
	v_mfma_f32_16x16x32_bf16 v[2:5], v[194:197], v[226:229], v[2:5]
	s_barrier
	s_setprio 0
	s_add_i32 s63, s63, 2
	s_add_u32 s0, s0, 0x100
	s_addc_u32 s1, s1, 0
	s_add_u32 s61, s61, 0x100
	s_addc_u32 s62, s62, 0
	s_cmp_gt_u32 s63, 29
.LBB0_1479:
	ds_read_b128 v[132:135], v174
	ds_read_b128 v[158:161], v174 offset:1024
	ds_read_b128 v[166:169], v174 offset:2048
	ds_read_b128 v[170:173], v174 offset:3072
	ds_read_b128 v[182:185], v175
	ds_read_b128 v[186:189], v175 offset:1024
	ds_read_b128 v[190:193], v175 offset:2048
	ds_read_b128 v[194:197], v175 offset:3072
	s_add_u32 s4, s0, 0xfff80080
	s_addc_u32 s5, s1, -1
	s_cmp_eq_u32 s63, 28
	s_cselect_b32 s7, s9, s5
	s_cselect_b32 s6, s11, s4
	s_cselect_b32 s5, s37, s62
	s_cselect_b32 s4, s60, s61
	s_add_i32 m0, s44, 0xc000
	ds_read_b128 v[198:201], v176
	ds_read_b128 v[202:205], v176 offset:1024
	ds_read_b128 v[206:209], v176 offset:2048
	ds_read_b128 v[210:213], v176 offset:3072
	ds_read_b128 v[214:217], v176 offset:4096
	ds_read_b128 v[218:221], v176 offset:5120
	ds_read_b128 v[222:225], v176 offset:6144
	ds_read_b128 v[226:229], v176 offset:7168
	global_load_lds_dwordx4 v146, s[0:1]
	s_add_i32 m0, s44, 0xe000
	s_nop 0
	global_load_lds_dwordx4 v148, s[0:1]
	s_waitcnt vmcnt(8)
	s_waitcnt lgkmcnt(0)
	s_setprio 1
	s_barrier
	v_mfma_f32_16x16x32_bf16 v[128:131], v[132:135], v[198:201], v[128:131]
	v_mfma_f32_16x16x32_bf16 v[124:127], v[166:169], v[198:201], v[124:127]
	v_mfma_f32_16x16x32_bf16 v[112:115], v[132:135], v[206:209], v[112:115]
	v_mfma_f32_16x16x32_bf16 v[108:111], v[166:169], v[206:209], v[108:111]
	v_mfma_f32_16x16x32_bf16 v[96:99], v[132:135], v[214:217], v[96:99]
	v_mfma_f32_16x16x32_bf16 v[92:95], v[166:169], v[214:217], v[92:95]
	v_mfma_f32_16x16x32_bf16 v[80:83], v[132:135], v[222:225], v[80:83]
	v_mfma_f32_16x16x32_bf16 v[76:79], v[166:169], v[222:225], v[76:79]
	v_mfma_f32_16x16x32_bf16 v[128:131], v[158:161], v[202:205], v[128:131]
	v_mfma_f32_16x16x32_bf16 v[124:127], v[170:173], v[202:205], v[124:127]
	v_mfma_f32_16x16x32_bf16 v[112:115], v[158:161], v[210:213], v[112:115]
	v_mfma_f32_16x16x32_bf16 v[108:111], v[170:173], v[210:213], v[108:111]
	v_mfma_f32_16x16x32_bf16 v[96:99], v[158:161], v[218:221], v[96:99]
	v_mfma_f32_16x16x32_bf16 v[92:95], v[170:173], v[218:221], v[92:95]
	v_mfma_f32_16x16x32_bf16 v[80:83], v[158:161], v[226:229], v[80:83]
	v_mfma_f32_16x16x32_bf16 v[76:79], v[170:173], v[226:229], v[76:79]
	s_setprio 0
	s_setprio 1
	v_mfma_f32_16x16x32_bf16 v[120:123], v[182:185], v[198:201], v[120:123]
	v_mfma_f32_16x16x32_bf16 v[116:119], v[190:193], v[198:201], v[116:119]
	v_mfma_f32_16x16x32_bf16 v[104:107], v[182:185], v[206:209], v[104:107]
	v_mfma_f32_16x16x32_bf16 v[100:103], v[190:193], v[206:209], v[100:103]
	v_mfma_f32_16x16x32_bf16 v[88:91], v[182:185], v[214:217], v[88:91]
	v_mfma_f32_16x16x32_bf16 v[84:87], v[190:193], v[214:217], v[84:87]
	v_mfma_f32_16x16x32_bf16 v[72:75], v[182:185], v[222:225], v[72:75]
	v_mfma_f32_16x16x32_bf16 v[68:71], v[190:193], v[222:225], v[68:71]
	v_mfma_f32_16x16x32_bf16 v[120:123], v[186:189], v[202:205], v[120:123]
	v_mfma_f32_16x16x32_bf16 v[116:119], v[194:197], v[202:205], v[116:119]
	v_mfma_f32_16x16x32_bf16 v[104:107], v[186:189], v[210:213], v[104:107]
	v_mfma_f32_16x16x32_bf16 v[100:103], v[194:197], v[210:213], v[100:103]
	v_mfma_f32_16x16x32_bf16 v[88:91], v[186:189], v[218:221], v[88:91]
	v_mfma_f32_16x16x32_bf16 v[84:87], v[194:197], v[218:221], v[84:87]
	v_mfma_f32_16x16x32_bf16 v[72:75], v[186:189], v[226:229], v[72:75]
	v_mfma_f32_16x16x32_bf16 v[68:71], v[194:197], v[226:229], v[68:71]
	s_barrier
	s_setprio 0
	s_add_i32 s64, s54, s29
	s_add_u32 s98, s4, 0x80
	s_addc_u32 s99, s5, 0
	s_mov_b32 m0, s64
	ds_read_b128 v[198:201], v176 offset:16384
	ds_read_b128 v[202:205], v176 offset:17408
	ds_read_b128 v[206:209], v176 offset:18432
	ds_read_b128 v[210:213], v176 offset:19456
	ds_read_b128 v[214:217], v176 offset:20480
	ds_read_b128 v[218:221], v176 offset:21504
	ds_read_b128 v[222:225], v176 offset:22528
	ds_read_b128 v[226:229], v176 offset:23552
	global_load_lds_dwordx4 v142, s[4:5]
	s_add_i32 m0, s64, 0x2000
	s_add_u32 s64, s4, 0x80000
	s_addc_u32 s65, s5, 0
	s_add_i32 s66, s55, s29
	global_load_lds_dwordx4 v138, s[4:5]
	s_mov_b32 m0, s66
	s_nop 0
	global_load_lds_dwordx4 v142, s[64:65]
	s_add_i32 m0, s66, 0x2000
	s_nop 0
	global_load_lds_dwordx4 v138, s[64:65]
	s_add_u32 s100, s6, 0x80
	s_addc_u32 s101, s7, 0
	s_mov_b32 m0, s44
	s_nop 0
	global_load_lds_dwordx4 v144, s[6:7]
	s_mov_b32 m0, s45
	s_nop 0
	global_load_lds_dwordx4 v140, s[6:7]
	s_waitcnt vmcnt(8)
	s_waitcnt lgkmcnt(0)
	s_setprio 1
	s_barrier
	v_mfma_f32_16x16x32_bf16 v[62:65], v[132:135], v[198:201], v[62:65]
	v_mfma_f32_16x16x32_bf16 v[58:61], v[166:169], v[198:201], v[58:61]
	v_mfma_f32_16x16x32_bf16 v[46:49], v[132:135], v[206:209], v[46:49]
	v_mfma_f32_16x16x32_bf16 v[42:45], v[166:169], v[206:209], v[42:45]
	v_mfma_f32_16x16x32_bf16 v[30:33], v[132:135], v[214:217], v[30:33]
	v_mfma_f32_16x16x32_bf16 v[26:29], v[166:169], v[214:217], v[26:29]
	v_mfma_f32_16x16x32_bf16 v[14:17], v[132:135], v[222:225], v[14:17]
	v_mfma_f32_16x16x32_bf16 v[10:13], v[166:169], v[222:225], v[10:13]
	v_mfma_f32_16x16x32_bf16 v[62:65], v[158:161], v[202:205], v[62:65]
	v_mfma_f32_16x16x32_bf16 v[58:61], v[170:173], v[202:205], v[58:61]
	v_mfma_f32_16x16x32_bf16 v[46:49], v[158:161], v[210:213], v[46:49]
	v_mfma_f32_16x16x32_bf16 v[42:45], v[170:173], v[210:213], v[42:45]
	v_mfma_f32_16x16x32_bf16 v[30:33], v[158:161], v[218:221], v[30:33]
	v_mfma_f32_16x16x32_bf16 v[26:29], v[170:173], v[218:221], v[26:29]
	v_mfma_f32_16x16x32_bf16 v[14:17], v[158:161], v[226:229], v[14:17]
	v_mfma_f32_16x16x32_bf16 v[10:13], v[170:173], v[226:229], v[10:13]
	s_setprio 0
	s_setprio 1
	v_mfma_f32_16x16x32_bf16 v[54:57], v[182:185], v[198:201], v[54:57]
	v_mfma_f32_16x16x32_bf16 v[50:53], v[190:193], v[198:201], v[50:53]
	v_mfma_f32_16x16x32_bf16 v[38:41], v[182:185], v[206:209], v[38:41]
	v_mfma_f32_16x16x32_bf16 v[34:37], v[190:193], v[206:209], v[34:37]
	v_mfma_f32_16x16x32_bf16 v[22:25], v[182:185], v[214:217], v[22:25]
	v_mfma_f32_16x16x32_bf16 v[18:21], v[190:193], v[214:217], v[18:21]
	v_mfma_f32_16x16x32_bf16 v[6:9], v[182:185], v[222:225], v[6:9]
	v_mfma_f32_16x16x32_bf16 v[2:5], v[190:193], v[222:225], v[2:5]
	v_mfma_f32_16x16x32_bf16 v[54:57], v[186:189], v[202:205], v[54:57]
	v_mfma_f32_16x16x32_bf16 v[50:53], v[194:197], v[202:205], v[50:53]
	v_mfma_f32_16x16x32_bf16 v[38:41], v[186:189], v[210:213], v[38:41]
	v_mfma_f32_16x16x32_bf16 v[34:37], v[194:197], v[210:213], v[34:37]
	v_mfma_f32_16x16x32_bf16 v[22:25], v[186:189], v[218:221], v[22:25]
	v_mfma_f32_16x16x32_bf16 v[18:21], v[194:197], v[218:221], v[18:21]
	v_mfma_f32_16x16x32_bf16 v[6:9], v[186:189], v[226:229], v[6:9]
	v_mfma_f32_16x16x32_bf16 v[2:5], v[194:197], v[226:229], v[2:5]
	s_barrier
	s_setprio 0
	s_add_i32 s64, 0, 0x18000
	v_add_u32_e32 v162, s64, v163
	s_add_i32 s65, 0, 0x1c000
	ds_read_b128 v[132:135], v162
	ds_read_b128 v[158:161], v162 offset:1024
	ds_read_b128 v[166:169], v162 offset:2048
	ds_read_b128 v[170:173], v162 offset:3072
	v_add_u32_e32 v162, s65, v163
	ds_read_b128 v[182:185], v162
	ds_read_b128 v[186:189], v162 offset:1024
	ds_read_b128 v[190:193], v162 offset:2048
	ds_read_b128 v[194:197], v162 offset:3072
	s_add_u32 s6, s6, 0x80000
	s_addc_u32 s7, s7, 0
	s_mov_b32 m0, s46
	ds_read_b128 v[198:201], v176 offset:32768
	ds_read_b128 v[202:205], v176 offset:33792
	ds_read_b128 v[206:209], v176 offset:34816
	ds_read_b128 v[210:213], v176 offset:35840
	ds_read_b128 v[214:217], v176 offset:36864
	ds_read_b128 v[218:221], v176 offset:37888
	ds_read_b128 v[222:225], v176 offset:38912
	ds_read_b128 v[226:229], v176 offset:39936
	global_load_lds_dwordx4 v144, s[6:7]
	s_mov_b32 m0, s47
	s_nop 0
	global_load_lds_dwordx4 v140, s[6:7]
	s_waitcnt vmcnt(8)
	s_waitcnt lgkmcnt(0)
	s_setprio 1
	s_barrier
	v_mfma_f32_16x16x32_bf16 v[128:131], v[132:135], v[198:201], v[128:131]
	v_mfma_f32_16x16x32_bf16 v[124:127], v[166:169], v[198:201], v[124:127]
	v_mfma_f32_16x16x32_bf16 v[112:115], v[132:135], v[206:209], v[112:115]
	v_mfma_f32_16x16x32_bf16 v[108:111], v[166:169], v[206:209], v[108:111]
	v_mfma_f32_16x16x32_bf16 v[96:99], v[132:135], v[214:217], v[96:99]
	v_mfma_f32_16x16x32_bf16 v[92:95], v[166:169], v[214:217], v[92:95]
	v_mfma_f32_16x16x32_bf16 v[80:83], v[132:135], v[222:225], v[80:83]
	v_mfma_f32_16x16x32_bf16 v[76:79], v[166:169], v[222:225], v[76:79]
	v_mfma_f32_16x16x32_bf16 v[128:131], v[158:161], v[202:205], v[128:131]
	v_mfma_f32_16x16x32_bf16 v[124:127], v[170:173], v[202:205], v[124:127]
	v_mfma_f32_16x16x32_bf16 v[112:115], v[158:161], v[210:213], v[112:115]
	v_mfma_f32_16x16x32_bf16 v[108:111], v[170:173], v[210:213], v[108:111]
	v_mfma_f32_16x16x32_bf16 v[96:99], v[158:161], v[218:221], v[96:99]
	v_mfma_f32_16x16x32_bf16 v[92:95], v[170:173], v[218:221], v[92:95]
	v_mfma_f32_16x16x32_bf16 v[80:83], v[158:161], v[226:229], v[80:83]
	v_mfma_f32_16x16x32_bf16 v[76:79], v[170:173], v[226:229], v[76:79]
	s_setprio 0
	s_setprio 1
	v_mfma_f32_16x16x32_bf16 v[120:123], v[182:185], v[198:201], v[120:123]
	v_mfma_f32_16x16x32_bf16 v[116:119], v[190:193], v[198:201], v[116:119]
	v_mfma_f32_16x16x32_bf16 v[104:107], v[182:185], v[206:209], v[104:107]
	v_mfma_f32_16x16x32_bf16 v[100:103], v[190:193], v[206:209], v[100:103]
	v_mfma_f32_16x16x32_bf16 v[88:91], v[182:185], v[214:217], v[88:91]
	v_mfma_f32_16x16x32_bf16 v[84:87], v[190:193], v[214:217], v[84:87]
	v_mfma_f32_16x16x32_bf16 v[72:75], v[182:185], v[222:225], v[72:75]
	v_mfma_f32_16x16x32_bf16 v[68:71], v[190:193], v[222:225], v[68:71]
	v_mfma_f32_16x16x32_bf16 v[120:123], v[186:189], v[202:205], v[120:123]
	v_mfma_f32_16x16x32_bf16 v[116:119], v[194:197], v[202:205], v[116:119]
	v_mfma_f32_16x16x32_bf16 v[104:107], v[186:189], v[210:213], v[104:107]
	v_mfma_f32_16x16x32_bf16 v[100:103], v[194:197], v[210:213], v[100:103]
	v_mfma_f32_16x16x32_bf16 v[88:91], v[186:189], v[218:221], v[88:91]
	v_mfma_f32_16x16x32_bf16 v[84:87], v[194:197], v[218:221], v[84:87]
	v_mfma_f32_16x16x32_bf16 v[72:75], v[186:189], v[226:229], v[72:75]
	v_mfma_f32_16x16x32_bf16 v[68:71], v[194:197], v[226:229], v[68:71]
	s_barrier
	s_setprio 0
	s_add_i32 s6, s64, s29
	s_mov_b32 m0, s6
	ds_read_b128 v[198:201], v176 offset:49152
	ds_read_b128 v[202:205], v176 offset:50176
	ds_read_b128 v[206:209], v176 offset:51200
	ds_read_b128 v[210:213], v176 offset:52224
	ds_read_b128 v[214:217], v176 offset:53248
	ds_read_b128 v[218:221], v176 offset:54272
	ds_read_b128 v[222:225], v176 offset:55296
	ds_read_b128 v[226:229], v176 offset:56320
	global_load_lds_dwordx4 v142, s[98:99]
	s_add_i32 m0, s6, 0x2000
	s_add_u32 s4, s4, 0x80080
	s_addc_u32 s5, s5, 0
	s_add_i32 s6, s65, s29
	global_load_lds_dwordx4 v138, s[98:99]
	s_mov_b32 m0, s6
	s_nop 0
	global_load_lds_dwordx4 v142, s[4:5]
	s_add_i32 m0, s6, 0x2000
	s_nop 0
	global_load_lds_dwordx4 v138, s[4:5]
	s_mov_b32 m0, s48
	s_nop 0
	global_load_lds_dwordx4 v144, s[100:101]
	s_mov_b32 m0, s49
	s_nop 0
	global_load_lds_dwordx4 v140, s[100:101]
	s_add_i32 s63, s63, 2
	s_add_u32 s0, s0, 0x100
	s_addc_u32 s1, s1, 0
	s_add_u32 s61, s61, 0x100
	s_addc_u32 s62, s62, 0
	s_cmp_gt_u32 s63, 29
	s_waitcnt vmcnt(8)
	s_waitcnt lgkmcnt(0)
	s_setprio 1
	s_barrier
	v_mfma_f32_16x16x32_bf16 v[62:65], v[132:135], v[198:201], v[62:65]
	v_mfma_f32_16x16x32_bf16 v[58:61], v[166:169], v[198:201], v[58:61]
	v_mfma_f32_16x16x32_bf16 v[46:49], v[132:135], v[206:209], v[46:49]
	v_mfma_f32_16x16x32_bf16 v[42:45], v[166:169], v[206:209], v[42:45]
	v_mfma_f32_16x16x32_bf16 v[30:33], v[132:135], v[214:217], v[30:33]
	v_mfma_f32_16x16x32_bf16 v[26:29], v[166:169], v[214:217], v[26:29]
	v_mfma_f32_16x16x32_bf16 v[14:17], v[132:135], v[222:225], v[14:17]
	v_mfma_f32_16x16x32_bf16 v[10:13], v[166:169], v[222:225], v[10:13]
	v_mfma_f32_16x16x32_bf16 v[62:65], v[158:161], v[202:205], v[62:65]
	v_mfma_f32_16x16x32_bf16 v[58:61], v[170:173], v[202:205], v[58:61]
	v_mfma_f32_16x16x32_bf16 v[46:49], v[158:161], v[210:213], v[46:49]
	v_mfma_f32_16x16x32_bf16 v[42:45], v[170:173], v[210:213], v[42:45]
	v_mfma_f32_16x16x32_bf16 v[30:33], v[158:161], v[218:221], v[30:33]
	v_mfma_f32_16x16x32_bf16 v[26:29], v[170:173], v[218:221], v[26:29]
	v_mfma_f32_16x16x32_bf16 v[14:17], v[158:161], v[226:229], v[14:17]
	v_mfma_f32_16x16x32_bf16 v[10:13], v[170:173], v[226:229], v[10:13]
	s_setprio 0
	s_setprio 1
	v_mfma_f32_16x16x32_bf16 v[54:57], v[182:185], v[198:201], v[54:57]
	v_mfma_f32_16x16x32_bf16 v[50:53], v[190:193], v[198:201], v[50:53]
	v_mfma_f32_16x16x32_bf16 v[38:41], v[182:185], v[206:209], v[38:41]
	v_mfma_f32_16x16x32_bf16 v[34:37], v[190:193], v[206:209], v[34:37]
	v_mfma_f32_16x16x32_bf16 v[22:25], v[182:185], v[214:217], v[22:25]
	v_mfma_f32_16x16x32_bf16 v[18:21], v[190:193], v[214:217], v[18:21]
	v_mfma_f32_16x16x32_bf16 v[6:9], v[182:185], v[222:225], v[6:9]
	v_mfma_f32_16x16x32_bf16 v[2:5], v[190:193], v[222:225], v[2:5]
	v_mfma_f32_16x16x32_bf16 v[54:57], v[186:189], v[202:205], v[54:57]
	v_mfma_f32_16x16x32_bf16 v[50:53], v[194:197], v[202:205], v[50:53]
	v_mfma_f32_16x16x32_bf16 v[38:41], v[186:189], v[210:213], v[38:41]
	v_mfma_f32_16x16x32_bf16 v[34:37], v[194:197], v[210:213], v[34:37]
	v_mfma_f32_16x16x32_bf16 v[22:25], v[186:189], v[218:221], v[22:25]
	v_mfma_f32_16x16x32_bf16 v[18:21], v[194:197], v[218:221], v[18:21]
	v_mfma_f32_16x16x32_bf16 v[6:9], v[186:189], v[226:229], v[6:9]
	v_mfma_f32_16x16x32_bf16 v[2:5], v[194:197], v[226:229], v[2:5]
	s_barrier
	s_setprio 0
	s_cbranch_scc0 .LBB0_1479
	s_and_b64 vcc, exec, s[34:35]
	s_cbranch_vccz .LBB0_1482
	s_barrier

.LBB0_1552:
	s_add_u32 s6, s26, 0x27c00000
	s_addc_u32 s7, s27, 0
	s_lshl_b32 s5, s5, 5
	s_mov_b64 s[8:9], 0x80
	s_and_b32 s5, s5, 0x60
	s_add_i32 m0, s30, 0x18000
	v_lshl_add_u64 v[8:9], v[8:9], 0, s[8:9]
	s_lshl_b32 s12, s3, 13
	s_lshl_b32 s13, s5, 7
	s_waitcnt vmcnt(2)
	s_barrier
	global_load_lds_dwordx4 v[8:9], off
	v_lshl_add_u64 v[6:7], v[6:7], 0, s[8:9]
	s_add_i32 m0, s30, 0x1a000
	s_add_i32 s37, s30, 0x8000
	s_add_i32 s38, s30, 0xa000
	global_load_lds_dwordx4 v[6:7], off
	v_lshl_add_u64 v[2:3], v[2:3], 0, s[8:9]
	s_mov_b32 m0, s37
	s_add_u32 s10, s20, 0x160080
	global_load_lds_dwordx4 v[2:3], off
	v_lshl_add_u64 v[2:3], v[4:5], 0, s[8:9]
	s_mov_b32 m0, s38
	s_addc_u32 s11, s21, 0
	global_load_lds_dwordx4 v[2:3], off
	s_add_i32 m0, s30, 0x1c000
	s_nop 0
	global_load_lds_dwordx4 v130, s[10:11]
	s_add_i32 m0, s30, 0x1e000
	v_lshlrev_b32_e32 v5, 2, v0
	global_load_lds_dwordx4 v134, s[10:11]
	v_bfe_u32 v2, v0, 4, 2
	v_and_b32_e32 v3, 15, v0
	v_lshl_or_b32 v148, s3, 6, v3
	v_lshlrev_b32_e32 v4, 4, v2
	v_lshlrev_b32_e32 v0, 6, v0
	s_movk_i32 s3, 0x3c0
	s_cmpk_lt_u32 s2, 0x100
	v_and_b32_e32 v5, 32, v5
	v_and_or_b32 v0, v0, s3, v4
	s_cselect_b64 s[10:11], -1, 0
	s_ashr_i32 s39, s33, 31
	v_lshl_or_b32 v3, v3, 6, v4
	v_bitop3_b32 v149, s13, v0, v5 bitop3:0xf6
	s_waitcnt vmcnt(6)
	s_cmp_lg_u64 s[50:51], 0
	v_add_u16_e32 v0, v1, v10
	v_bitop3_b32 v3, v3, s12, v5 bitop3:0xde
	s_cselect_b64 s[12:13], -1, 0
	v_lshrrev_b16_e32 v0, 1, v0
	s_add_i32 s40, 0, 0x10000
	s_add_i32 s41, 0, 0x14000
	s_sext_i32_i8 s45, s4
	v_lshl_or_b32 v150, v2, 3, s5
	v_add_lshl_u32 v136, v11, v0, 1
	v_mov_b32_e32 v137, v131
	v_add_lshl_u32 v138, v12, v0, 1
	v_mov_b32_e32 v139, v131
	v_mov_b64_e32 v[140:141], 0x400
	v_mov_b64_e32 v[142:143], 0x3ff
	v_add_u32_e32 v151, s40, v149
	v_add_u32_e32 v152, s41, v149
	v_add_u32_e32 v153, 0, v3
	s_barrier
	s_branch .LBB0_1555

.LBB0_1565:
	s_add_u32 s16, s16, 0x160080
	s_addc_u32 s17, s17, 0
	s_add_u32 s46, s20, 0x100
	s_addc_u32 s47, s21, 0
	s_mov_b32 s48, -2
	ds_read_b128 v[144:147], v151
	ds_read_b128 v[154:157], v151 offset:1024
	ds_read_b128 v[158:161], v151 offset:2048
	ds_read_b128 v[162:165], v151 offset:3072
	ds_read_b128 v[166:169], v152
	ds_read_b128 v[170:173], v152 offset:1024
	ds_read_b128 v[174:177], v152 offset:2048
	ds_read_b128 v[178:181], v152 offset:3072
	s_add_u32 s20, s16, 0xffea0080
	s_addc_u32 s21, s17, -1
	s_cmpk_eq_i32 s48, 0x54
	s_cselect_b32 s27, s5, s21
	s_cselect_b32 s26, s4, s20
	s_cselect_b32 s21, s15, s47
	s_cselect_b32 s20, s14, s46
	s_add_i32 m0, s30, 0xc000
	ds_read_b128 v[182:185], v153
	ds_read_b128 v[186:189], v153 offset:1024
	ds_read_b128 v[190:193], v153 offset:2048
	ds_read_b128 v[194:197], v153 offset:3072
	ds_read_b128 v[198:201], v153 offset:4096
	ds_read_b128 v[202:205], v153 offset:5120
	ds_read_b128 v[206:209], v153 offset:6144
	ds_read_b128 v[210:213], v153 offset:7168
	global_load_lds_dwordx4 v136, s[16:17]
	s_add_i32 m0, s30, 0xe000
	s_nop 0
	global_load_lds_dwordx4 v138, s[16:17]
	s_waitcnt vmcnt(8)
	s_waitcnt lgkmcnt(0)
	s_setprio 1
	s_barrier
	v_mfma_f32_16x16x32_bf16 v[124:127], v[144:147], v[182:185], 0
	v_mfma_f32_16x16x32_bf16 v[120:123], v[158:161], v[182:185], 0
	v_mfma_f32_16x16x32_bf16 v[108:111], v[144:147], v[190:193], 0
	v_mfma_f32_16x16x32_bf16 v[104:107], v[158:161], v[190:193], 0
	v_mfma_f32_16x16x32_bf16 v[88:91], v[144:147], v[198:201], 0
	v_mfma_f32_16x16x32_bf16 v[92:95], v[158:161], v[198:201], 0
	v_mfma_f32_16x16x32_bf16 v[72:75], v[144:147], v[206:209], 0
	v_mfma_f32_16x16x32_bf16 v[76:79], v[158:161], v[206:209], 0
	v_mfma_f32_16x16x32_bf16 v[124:127], v[154:157], v[186:189], v[124:127]
	v_mfma_f32_16x16x32_bf16 v[120:123], v[162:165], v[186:189], v[120:123]
	v_mfma_f32_16x16x32_bf16 v[108:111], v[154:157], v[194:197], v[108:111]
	v_mfma_f32_16x16x32_bf16 v[104:107], v[162:165], v[194:197], v[104:107]
	v_mfma_f32_16x16x32_bf16 v[88:91], v[154:157], v[202:205], v[88:91]
	v_mfma_f32_16x16x32_bf16 v[92:95], v[162:165], v[202:205], v[92:95]
	v_mfma_f32_16x16x32_bf16 v[72:75], v[154:157], v[210:213], v[72:75]
	v_mfma_f32_16x16x32_bf16 v[76:79], v[162:165], v[210:213], v[76:79]
	s_setprio 0
	s_setprio 1
	v_mfma_f32_16x16x32_bf16 v[116:119], v[166:169], v[182:185], 0
	v_mfma_f32_16x16x32_bf16 v[112:115], v[174:177], v[182:185], 0
	v_mfma_f32_16x16x32_bf16 v[96:99], v[166:169], v[190:193], 0
	v_mfma_f32_16x16x32_bf16 v[100:103], v[174:177], v[190:193], 0
	v_mfma_f32_16x16x32_bf16 v[80:83], v[166:169], v[198:201], 0
	v_mfma_f32_16x16x32_bf16 v[84:87], v[174:177], v[198:201], 0
	v_mfma_f32_16x16x32_bf16 v[64:67], v[166:169], v[206:209], 0
	v_mfma_f32_16x16x32_bf16 v[68:71], v[174:177], v[206:209], 0
	v_mfma_f32_16x16x32_bf16 v[116:119], v[170:173], v[186:189], v[116:119]
	v_mfma_f32_16x16x32_bf16 v[112:115], v[178:181], v[186:189], v[112:115]
	v_mfma_f32_16x16x32_bf16 v[96:99], v[170:173], v[194:197], v[96:99]
	v_mfma_f32_16x16x32_bf16 v[100:103], v[178:181], v[194:197], v[100:103]
	v_mfma_f32_16x16x32_bf16 v[80:83], v[170:173], v[202:205], v[80:83]
	v_mfma_f32_16x16x32_bf16 v[84:87], v[178:181], v[202:205], v[84:87]
	v_mfma_f32_16x16x32_bf16 v[64:67], v[170:173], v[210:213], v[64:67]
	v_mfma_f32_16x16x32_bf16 v[68:71], v[178:181], v[210:213], v[68:71]
	s_barrier
	s_setprio 0
	s_add_i32 s49, s40, s29
	s_add_u32 s98, s20, 0x80
	s_addc_u32 s99, s21, 0
	s_mov_b32 m0, s49
	ds_read_b128 v[182:185], v153 offset:16384
	ds_read_b128 v[186:189], v153 offset:17408
	ds_read_b128 v[190:193], v153 offset:18432
	ds_read_b128 v[194:197], v153 offset:19456
	ds_read_b128 v[198:201], v153 offset:20480
	ds_read_b128 v[202:205], v153 offset:21504
	ds_read_b128 v[206:209], v153 offset:22528
	ds_read_b128 v[210:213], v153 offset:23552
	global_load_lds_dwordx4 v130, s[20:21]
	s_add_i32 m0, s49, 0x2000
	s_add_u32 s52, s20, 0x160000
	s_addc_u32 s53, s21, 0
	s_add_i32 s49, s41, s29
	global_load_lds_dwordx4 v134, s[20:21]
	s_mov_b32 m0, s49
	s_nop 0
	global_load_lds_dwordx4 v130, s[52:53]
	s_add_i32 m0, s49, 0x2000
	s_nop 0
	global_load_lds_dwordx4 v134, s[52:53]
	s_add_u32 s100, s26, 0x80
	s_addc_u32 s101, s27, 0
	s_mov_b32 m0, s30
	s_nop 0
	global_load_lds_dwordx4 v128, s[26:27]
	s_mov_b32 m0, s31
	s_nop 0
	global_load_lds_dwordx4 v132, s[26:27]
	s_waitcnt vmcnt(8)
	s_waitcnt lgkmcnt(0)
	s_setprio 1
	s_barrier
	v_mfma_f32_16x16x32_bf16 v[56:59], v[144:147], v[182:185], 0
	v_mfma_f32_16x16x32_bf16 v[60:63], v[158:161], v[182:185], 0
	v_mfma_f32_16x16x32_bf16 v[40:43], v[144:147], v[190:193], 0
	v_mfma_f32_16x16x32_bf16 v[44:47], v[158:161], v[190:193], 0
	v_mfma_f32_16x16x32_bf16 v[24:27], v[144:147], v[198:201], 0
	v_mfma_f32_16x16x32_bf16 v[28:31], v[158:161], v[198:201], 0
	v_mfma_f32_16x16x32_bf16 v[8:11], v[144:147], v[206:209], 0
	v_mfma_f32_16x16x32_bf16 v[12:15], v[158:161], v[206:209], 0
	v_mfma_f32_16x16x32_bf16 v[56:59], v[154:157], v[186:189], v[56:59]
	v_mfma_f32_16x16x32_bf16 v[60:63], v[162:165], v[186:189], v[60:63]
	v_mfma_f32_16x16x32_bf16 v[40:43], v[154:157], v[194:197], v[40:43]
	v_mfma_f32_16x16x32_bf16 v[44:47], v[162:165], v[194:197], v[44:47]
	v_mfma_f32_16x16x32_bf16 v[24:27], v[154:157], v[202:205], v[24:27]
	v_mfma_f32_16x16x32_bf16 v[28:31], v[162:165], v[202:205], v[28:31]
	v_mfma_f32_16x16x32_bf16 v[8:11], v[154:157], v[210:213], v[8:11]
	v_mfma_f32_16x16x32_bf16 v[12:15], v[162:165], v[210:213], v[12:15]
	s_setprio 0
	s_setprio 1
	v_mfma_f32_16x16x32_bf16 v[48:51], v[166:169], v[182:185], 0
	v_mfma_f32_16x16x32_bf16 v[52:55], v[174:177], v[182:185], 0
	v_mfma_f32_16x16x32_bf16 v[32:35], v[166:169], v[190:193], 0
	v_mfma_f32_16x16x32_bf16 v[36:39], v[174:177], v[190:193], 0
	v_mfma_f32_16x16x32_bf16 v[16:19], v[166:169], v[198:201], 0
	v_mfma_f32_16x16x32_bf16 v[20:23], v[174:177], v[198:201], 0
	v_mfma_f32_16x16x32_bf16 v[0:3], v[166:169], v[206:209], 0
	v_mfma_f32_16x16x32_bf16 v[4:7], v[174:177], v[206:209], 0
	v_mfma_f32_16x16x32_bf16 v[48:51], v[170:173], v[186:189], v[48:51]
	v_mfma_f32_16x16x32_bf16 v[52:55], v[178:181], v[186:189], v[52:55]
	v_mfma_f32_16x16x32_bf16 v[32:35], v[170:173], v[194:197], v[32:35]
	v_mfma_f32_16x16x32_bf16 v[36:39], v[178:181], v[194:197], v[36:39]
	v_mfma_f32_16x16x32_bf16 v[16:19], v[170:173], v[202:205], v[16:19]
	v_mfma_f32_16x16x32_bf16 v[20:23], v[178:181], v[202:205], v[20:23]
	v_mfma_f32_16x16x32_bf16 v[0:3], v[170:173], v[210:213], v[0:3]
	v_mfma_f32_16x16x32_bf16 v[4:7], v[178:181], v[210:213], v[4:7]
	s_barrier
	s_setprio 0
	s_add_i32 s49, 0, 0x18000
	s_add_i32 s52, 0, 0x1c000
	v_add_u32_e32 v162, s49, v149
	v_add_u32_e32 v178, s52, v149
	ds_read_b128 v[144:147], v162
	ds_read_b128 v[154:157], v162 offset:1024
	ds_read_b128 v[158:161], v162 offset:2048
	ds_read_b128 v[162:165], v162 offset:3072
	ds_read_b128 v[166:169], v178
	ds_read_b128 v[170:173], v178 offset:1024
	ds_read_b128 v[174:177], v178 offset:2048
	ds_read_b128 v[178:181], v178 offset:3072
	s_add_u32 s26, s26, 0x160000
	s_addc_u32 s27, s27, 0
	s_mov_b32 m0, s34
	ds_read_b128 v[182:185], v153 offset:32768
	ds_read_b128 v[186:189], v153 offset:33792
	ds_read_b128 v[190:193], v153 offset:34816
	ds_read_b128 v[194:197], v153 offset:35840
	ds_read_b128 v[198:201], v153 offset:36864
	ds_read_b128 v[202:205], v153 offset:37888
	ds_read_b128 v[206:209], v153 offset:38912
	ds_read_b128 v[210:213], v153 offset:39936
	global_load_lds_dwordx4 v128, s[26:27]
	s_mov_b32 m0, s35
	s_nop 0
	global_load_lds_dwordx4 v132, s[26:27]
	s_waitcnt vmcnt(8)
	s_waitcnt lgkmcnt(0)
	s_setprio 1
	s_barrier
	v_mfma_f32_16x16x32_bf16 v[124:127], v[144:147], v[182:185], v[124:127]
	v_mfma_f32_16x16x32_bf16 v[120:123], v[158:161], v[182:185], v[120:123]
	v_mfma_f32_16x16x32_bf16 v[108:111], v[144:147], v[190:193], v[108:111]
	v_mfma_f32_16x16x32_bf16 v[104:107], v[158:161], v[190:193], v[104:107]
	v_mfma_f32_16x16x32_bf16 v[88:91], v[144:147], v[198:201], v[88:91]
	v_mfma_f32_16x16x32_bf16 v[92:95], v[158:161], v[198:201], v[92:95]
	v_mfma_f32_16x16x32_bf16 v[72:75], v[144:147], v[206:209], v[72:75]
	v_mfma_f32_16x16x32_bf16 v[76:79], v[158:161], v[206:209], v[76:79]
	v_mfma_f32_16x16x32_bf16 v[124:127], v[154:157], v[186:189], v[124:127]
	v_mfma_f32_16x16x32_bf16 v[120:123], v[162:165], v[186:189], v[120:123]
	v_mfma_f32_16x16x32_bf16 v[108:111], v[154:157], v[194:197], v[108:111]
	v_mfma_f32_16x16x32_bf16 v[104:107], v[162:165], v[194:197], v[104:107]
	v_mfma_f32_16x16x32_bf16 v[88:91], v[154:157], v[202:205], v[88:91]
	v_mfma_f32_16x16x32_bf16 v[92:95], v[162:165], v[202:205], v[92:95]
	v_mfma_f32_16x16x32_bf16 v[72:75], v[154:157], v[210:213], v[72:75]
	v_mfma_f32_16x16x32_bf16 v[76:79], v[162:165], v[210:213], v[76:79]
	s_setprio 0
	s_setprio 1
	v_mfma_f32_16x16x32_bf16 v[116:119], v[166:169], v[182:185], v[116:119]
	v_mfma_f32_16x16x32_bf16 v[112:115], v[174:177], v[182:185], v[112:115]
	v_mfma_f32_16x16x32_bf16 v[96:99], v[166:169], v[190:193], v[96:99]
	v_mfma_f32_16x16x32_bf16 v[100:103], v[174:177], v[190:193], v[100:103]
	v_mfma_f32_16x16x32_bf16 v[80:83], v[166:169], v[198:201], v[80:83]
	v_mfma_f32_16x16x32_bf16 v[84:87], v[174:177], v[198:201], v[84:87]
	v_mfma_f32_16x16x32_bf16 v[64:67], v[166:169], v[206:209], v[64:67]
	v_mfma_f32_16x16x32_bf16 v[68:71], v[174:177], v[206:209], v[68:71]
	v_mfma_f32_16x16x32_bf16 v[116:119], v[170:173], v[186:189], v[116:119]
	v_mfma_f32_16x16x32_bf16 v[112:115], v[178:181], v[186:189], v[112:115]
	v_mfma_f32_16x16x32_bf16 v[96:99], v[170:173], v[194:197], v[96:99]
	v_mfma_f32_16x16x32_bf16 v[100:103], v[178:181], v[194:197], v[100:103]
	v_mfma_f32_16x16x32_bf16 v[80:83], v[170:173], v[202:205], v[80:83]
	v_mfma_f32_16x16x32_bf16 v[84:87], v[178:181], v[202:205], v[84:87]
	v_mfma_f32_16x16x32_bf16 v[64:67], v[170:173], v[210:213], v[64:67]
	v_mfma_f32_16x16x32_bf16 v[68:71], v[178:181], v[210:213], v[68:71]
	s_barrier
	s_setprio 0
	s_add_i32 s26, s49, s29
	s_mov_b32 m0, s26
	ds_read_b128 v[182:185], v153 offset:49152
	ds_read_b128 v[186:189], v153 offset:50176
	ds_read_b128 v[190:193], v153 offset:51200
	ds_read_b128 v[194:197], v153 offset:52224
	ds_read_b128 v[198:201], v153 offset:53248
	ds_read_b128 v[202:205], v153 offset:54272
	ds_read_b128 v[206:209], v153 offset:55296
	ds_read_b128 v[210:213], v153 offset:56320
	global_load_lds_dwordx4 v130, s[98:99]
	s_add_i32 m0, s26, 0x2000
	s_add_u32 s20, s20, 0x160080
	s_addc_u32 s21, s21, 0
	s_add_i32 s26, s52, s29
	global_load_lds_dwordx4 v134, s[98:99]
	s_mov_b32 m0, s26
	s_nop 0
	global_load_lds_dwordx4 v130, s[20:21]
	s_add_i32 m0, s26, 0x2000
	s_nop 0
	global_load_lds_dwordx4 v134, s[20:21]
	s_mov_b32 m0, s37
	s_nop 0
	global_load_lds_dwordx4 v128, s[100:101]
	s_mov_b32 m0, s38
	s_nop 0
	global_load_lds_dwordx4 v132, s[100:101]
	s_waitcnt vmcnt(8)
	s_waitcnt lgkmcnt(0)
	s_setprio 1
	s_barrier
	v_mfma_f32_16x16x32_bf16 v[56:59], v[144:147], v[182:185], v[56:59]
	v_mfma_f32_16x16x32_bf16 v[60:63], v[158:161], v[182:185], v[60:63]
	v_mfma_f32_16x16x32_bf16 v[40:43], v[144:147], v[190:193], v[40:43]
	v_mfma_f32_16x16x32_bf16 v[44:47], v[158:161], v[190:193], v[44:47]
	v_mfma_f32_16x16x32_bf16 v[24:27], v[144:147], v[198:201], v[24:27]
	v_mfma_f32_16x16x32_bf16 v[28:31], v[158:161], v[198:201], v[28:31]
	v_mfma_f32_16x16x32_bf16 v[8:11], v[144:147], v[206:209], v[8:11]
	v_mfma_f32_16x16x32_bf16 v[12:15], v[158:161], v[206:209], v[12:15]
	v_mfma_f32_16x16x32_bf16 v[56:59], v[154:157], v[186:189], v[56:59]
	v_mfma_f32_16x16x32_bf16 v[60:63], v[162:165], v[186:189], v[60:63]
	v_mfma_f32_16x16x32_bf16 v[40:43], v[154:157], v[194:197], v[40:43]
	v_mfma_f32_16x16x32_bf16 v[44:47], v[162:165], v[194:197], v[44:47]
	v_mfma_f32_16x16x32_bf16 v[24:27], v[154:157], v[202:205], v[24:27]
	v_mfma_f32_16x16x32_bf16 v[28:31], v[162:165], v[202:205], v[28:31]
	v_mfma_f32_16x16x32_bf16 v[8:11], v[154:157], v[210:213], v[8:11]
	v_mfma_f32_16x16x32_bf16 v[12:15], v[162:165], v[210:213], v[12:15]
	s_setprio 0
	s_setprio 1
	v_mfma_f32_16x16x32_bf16 v[48:51], v[166:169], v[182:185], v[48:51]
	v_mfma_f32_16x16x32_bf16 v[52:55], v[174:177], v[182:185], v[52:55]
	v_mfma_f32_16x16x32_bf16 v[32:35], v[166:169], v[190:193], v[32:35]
	v_mfma_f32_16x16x32_bf16 v[36:39], v[174:177], v[190:193], v[36:39]
	v_mfma_f32_16x16x32_bf16 v[16:19], v[166:169], v[198:201], v[16:19]
	v_mfma_f32_16x16x32_bf16 v[20:23], v[174:177], v[198:201], v[20:23]
	v_mfma_f32_16x16x32_bf16 v[0:3], v[166:169], v[206:209], v[0:3]
	v_mfma_f32_16x16x32_bf16 v[4:7], v[174:177], v[206:209], v[4:7]
	v_mfma_f32_16x16x32_bf16 v[48:51], v[170:173], v[186:189], v[48:51]
	v_mfma_f32_16x16x32_bf16 v[52:55], v[178:181], v[186:189], v[52:55]
	v_mfma_f32_16x16x32_bf16 v[32:35], v[170:173], v[194:197], v[32:35]
	v_mfma_f32_16x16x32_bf16 v[36:39], v[178:181], v[194:197], v[36:39]
	v_mfma_f32_16x16x32_bf16 v[16:19], v[170:173], v[202:205], v[16:19]
	v_mfma_f32_16x16x32_bf16 v[20:23], v[178:181], v[202:205], v[20:23]
	v_mfma_f32_16x16x32_bf16 v[0:3], v[170:173], v[210:213], v[0:3]
	v_mfma_f32_16x16x32_bf16 v[4:7], v[178:181], v[210:213], v[4:7]
	s_barrier
	s_setprio 0
	s_add_i32 s48, s48, 2
	s_add_u32 s16, s16, 0x100
	s_addc_u32 s17, s17, 0
	s_add_u32 s46, s46, 0x100
	s_addc_u32 s47, s47, 0
	s_cmpk_gt_u32 s48, 0x55
.LBB0_1566:
	ds_read_b128 v[144:147], v151
	ds_read_b128 v[154:157], v151 offset:1024
	ds_read_b128 v[158:161], v151 offset:2048
	ds_read_b128 v[162:165], v151 offset:3072
	ds_read_b128 v[166:169], v152
	ds_read_b128 v[170:173], v152 offset:1024
	ds_read_b128 v[174:177], v152 offset:2048
	ds_read_b128 v[178:181], v152 offset:3072
	s_add_u32 s20, s16, 0xffea0080
	s_addc_u32 s21, s17, -1
	s_cmpk_eq_i32 s48, 0x54
	s_cselect_b32 s27, s5, s21
	s_cselect_b32 s26, s4, s20
	s_cselect_b32 s21, s15, s47
	s_cselect_b32 s20, s14, s46
	s_add_i32 m0, s30, 0xc000
	ds_read_b128 v[182:185], v153
	ds_read_b128 v[186:189], v153 offset:1024
	ds_read_b128 v[190:193], v153 offset:2048
	ds_read_b128 v[194:197], v153 offset:3072
	ds_read_b128 v[198:201], v153 offset:4096
	ds_read_b128 v[202:205], v153 offset:5120
	ds_read_b128 v[206:209], v153 offset:6144
	ds_read_b128 v[210:213], v153 offset:7168
	global_load_lds_dwordx4 v136, s[16:17]
	s_add_i32 m0, s30, 0xe000
	s_nop 0
	global_load_lds_dwordx4 v138, s[16:17]
	s_waitcnt vmcnt(8)
	s_waitcnt lgkmcnt(0)
	s_setprio 1
	s_barrier
	v_mfma_f32_16x16x32_bf16 v[124:127], v[144:147], v[182:185], v[124:127]
	v_mfma_f32_16x16x32_bf16 v[120:123], v[158:161], v[182:185], v[120:123]
	v_mfma_f32_16x16x32_bf16 v[108:111], v[144:147], v[190:193], v[108:111]
	v_mfma_f32_16x16x32_bf16 v[104:107], v[158:161], v[190:193], v[104:107]
	v_mfma_f32_16x16x32_bf16 v[88:91], v[144:147], v[198:201], v[88:91]
	v_mfma_f32_16x16x32_bf16 v[92:95], v[158:161], v[198:201], v[92:95]
	v_mfma_f32_16x16x32_bf16 v[72:75], v[144:147], v[206:209], v[72:75]
	v_mfma_f32_16x16x32_bf16 v[76:79], v[158:161], v[206:209], v[76:79]
	v_mfma_f32_16x16x32_bf16 v[124:127], v[154:157], v[186:189], v[124:127]
	v_mfma_f32_16x16x32_bf16 v[120:123], v[162:165], v[186:189], v[120:123]
	v_mfma_f32_16x16x32_bf16 v[108:111], v[154:157], v[194:197], v[108:111]
	v_mfma_f32_16x16x32_bf16 v[104:107], v[162:165], v[194:197], v[104:107]
	v_mfma_f32_16x16x32_bf16 v[88:91], v[154:157], v[202:205], v[88:91]
	v_mfma_f32_16x16x32_bf16 v[92:95], v[162:165], v[202:205], v[92:95]
	v_mfma_f32_16x16x32_bf16 v[72:75], v[154:157], v[210:213], v[72:75]
	v_mfma_f32_16x16x32_bf16 v[76:79], v[162:165], v[210:213], v[76:79]
	s_setprio 0
	s_setprio 1
	v_mfma_f32_16x16x32_bf16 v[116:119], v[166:169], v[182:185], v[116:119]
	v_mfma_f32_16x16x32_bf16 v[112:115], v[174:177], v[182:185], v[112:115]
	v_mfma_f32_16x16x32_bf16 v[96:99], v[166:169], v[190:193], v[96:99]
	v_mfma_f32_16x16x32_bf16 v[100:103], v[174:177], v[190:193], v[100:103]
	v_mfma_f32_16x16x32_bf16 v[80:83], v[166:169], v[198:201], v[80:83]
	v_mfma_f32_16x16x32_bf16 v[84:87], v[174:177], v[198:201], v[84:87]
	v_mfma_f32_16x16x32_bf16 v[64:67], v[166:169], v[206:209], v[64:67]
	v_mfma_f32_16x16x32_bf16 v[68:71], v[174:177], v[206:209], v[68:71]
	v_mfma_f32_16x16x32_bf16 v[116:119], v[170:173], v[186:189], v[116:119]
	v_mfma_f32_16x16x32_bf16 v[112:115], v[178:181], v[186:189], v[112:115]
	v_mfma_f32_16x16x32_bf16 v[96:99], v[170:173], v[194:197], v[96:99]
	v_mfma_f32_16x16x32_bf16 v[100:103], v[178:181], v[194:197], v[100:103]
	v_mfma_f32_16x16x32_bf16 v[80:83], v[170:173], v[202:205], v[80:83]
	v_mfma_f32_16x16x32_bf16 v[84:87], v[178:181], v[202:205], v[84:87]
	v_mfma_f32_16x16x32_bf16 v[64:67], v[170:173], v[210:213], v[64:67]
	v_mfma_f32_16x16x32_bf16 v[68:71], v[178:181], v[210:213], v[68:71]
	s_barrier
	s_setprio 0
	s_add_i32 s49, s40, s29
	s_add_u32 s98, s20, 0x80
	s_addc_u32 s99, s21, 0
	s_mov_b32 m0, s49
	ds_read_b128 v[182:185], v153 offset:16384
	ds_read_b128 v[186:189], v153 offset:17408
	ds_read_b128 v[190:193], v153 offset:18432
	ds_read_b128 v[194:197], v153 offset:19456
	ds_read_b128 v[198:201], v153 offset:20480
	ds_read_b128 v[202:205], v153 offset:21504
	ds_read_b128 v[206:209], v153 offset:22528
	ds_read_b128 v[210:213], v153 offset:23552
	global_load_lds_dwordx4 v130, s[20:21]
	s_add_i32 m0, s49, 0x2000
	s_add_u32 s52, s20, 0x160000
	s_addc_u32 s53, s21, 0
	s_add_i32 s49, s41, s29
	global_load_lds_dwordx4 v134, s[20:21]
	s_mov_b32 m0, s49
	s_nop 0
	global_load_lds_dwordx4 v130, s[52:53]
	s_add_i32 m0, s49, 0x2000
	s_nop 0
	global_load_lds_dwordx4 v134, s[52:53]
	s_add_u32 s100, s26, 0x80
	s_addc_u32 s101, s27, 0
	s_mov_b32 m0, s30
	s_nop 0
	global_load_lds_dwordx4 v128, s[26:27]
	s_mov_b32 m0, s31
	s_nop 0
	global_load_lds_dwordx4 v132, s[26:27]
	s_waitcnt vmcnt(8)
	s_waitcnt lgkmcnt(0)
	s_setprio 1
	s_barrier
	v_mfma_f32_16x16x32_bf16 v[56:59], v[144:147], v[182:185], v[56:59]
	v_mfma_f32_16x16x32_bf16 v[60:63], v[158:161], v[182:185], v[60:63]
	v_mfma_f32_16x16x32_bf16 v[40:43], v[144:147], v[190:193], v[40:43]
	v_mfma_f32_16x16x32_bf16 v[44:47], v[158:161], v[190:193], v[44:47]
	v_mfma_f32_16x16x32_bf16 v[24:27], v[144:147], v[198:201], v[24:27]
	v_mfma_f32_16x16x32_bf16 v[28:31], v[158:161], v[198:201], v[28:31]
	v_mfma_f32_16x16x32_bf16 v[8:11], v[144:147], v[206:209], v[8:11]
	v_mfma_f32_16x16x32_bf16 v[12:15], v[158:161], v[206:209], v[12:15]
	v_mfma_f32_16x16x32_bf16 v[56:59], v[154:157], v[186:189], v[56:59]
	v_mfma_f32_16x16x32_bf16 v[60:63], v[162:165], v[186:189], v[60:63]
	v_mfma_f32_16x16x32_bf16 v[40:43], v[154:157], v[194:197], v[40:43]
	v_mfma_f32_16x16x32_bf16 v[44:47], v[162:165], v[194:197], v[44:47]
	v_mfma_f32_16x16x32_bf16 v[24:27], v[154:157], v[202:205], v[24:27]
	v_mfma_f32_16x16x32_bf16 v[28:31], v[162:165], v[202:205], v[28:31]
	v_mfma_f32_16x16x32_bf16 v[8:11], v[154:157], v[210:213], v[8:11]
	v_mfma_f32_16x16x32_bf16 v[12:15], v[162:165], v[210:213], v[12:15]
	s_setprio 0
	s_setprio 1
	v_mfma_f32_16x16x32_bf16 v[48:51], v[166:169], v[182:185], v[48:51]
	v_mfma_f32_16x16x32_bf16 v[52:55], v[174:177], v[182:185], v[52:55]
	v_mfma_f32_16x16x32_bf16 v[32:35], v[166:169], v[190:193], v[32:35]
	v_mfma_f32_16x16x32_bf16 v[36:39], v[174:177], v[190:193], v[36:39]
	v_mfma_f32_16x16x32_bf16 v[16:19], v[166:169], v[198:201], v[16:19]
	v_mfma_f32_16x16x32_bf16 v[20:23], v[174:177], v[198:201], v[20:23]
	v_mfma_f32_16x16x32_bf16 v[0:3], v[166:169], v[206:209], v[0:3]
	v_mfma_f32_16x16x32_bf16 v[4:7], v[174:177], v[206:209], v[4:7]
	v_mfma_f32_16x16x32_bf16 v[48:51], v[170:173], v[186:189], v[48:51]
	v_mfma_f32_16x16x32_bf16 v[52:55], v[178:181], v[186:189], v[52:55]
	v_mfma_f32_16x16x32_bf16 v[32:35], v[170:173], v[194:197], v[32:35]
	v_mfma_f32_16x16x32_bf16 v[36:39], v[178:181], v[194:197], v[36:39]
	v_mfma_f32_16x16x32_bf16 v[16:19], v[170:173], v[202:205], v[16:19]
	v_mfma_f32_16x16x32_bf16 v[20:23], v[178:181], v[202:205], v[20:23]
	v_mfma_f32_16x16x32_bf16 v[0:3], v[170:173], v[210:213], v[0:3]
	v_mfma_f32_16x16x32_bf16 v[4:7], v[178:181], v[210:213], v[4:7]
	s_barrier
	s_setprio 0
	s_add_i32 s49, 0, 0x18000
	s_add_i32 s52, 0, 0x1c000
	v_add_u32_e32 v162, s49, v149
	v_add_u32_e32 v178, s52, v149
	ds_read_b128 v[144:147], v162
	ds_read_b128 v[154:157], v162 offset:1024
	ds_read_b128 v[158:161], v162 offset:2048
	ds_read_b128 v[162:165], v162 offset:3072
	ds_read_b128 v[166:169], v178
	ds_read_b128 v[170:173], v178 offset:1024
	ds_read_b128 v[174:177], v178 offset:2048
	ds_read_b128 v[178:181], v178 offset:3072
	s_add_u32 s26, s26, 0x160000
	s_addc_u32 s27, s27, 0
	s_mov_b32 m0, s34
	ds_read_b128 v[182:185], v153 offset:32768
	ds_read_b128 v[186:189], v153 offset:33792
	ds_read_b128 v[190:193], v153 offset:34816
	ds_read_b128 v[194:197], v153 offset:35840
	ds_read_b128 v[198:201], v153 offset:36864
	ds_read_b128 v[202:205], v153 offset:37888
	ds_read_b128 v[206:209], v153 offset:38912
	ds_read_b128 v[210:213], v153 offset:39936
	global_load_lds_dwordx4 v128, s[26:27]
	s_mov_b32 m0, s35
	s_nop 0
	global_load_lds_dwordx4 v132, s[26:27]
	s_waitcnt vmcnt(8)
	s_waitcnt lgkmcnt(0)
	s_setprio 1
	s_barrier
	v_mfma_f32_16x16x32_bf16 v[124:127], v[144:147], v[182:185], v[124:127]
	v_mfma_f32_16x16x32_bf16 v[120:123], v[158:161], v[182:185], v[120:123]
	v_mfma_f32_16x16x32_bf16 v[108:111], v[144:147], v[190:193], v[108:111]
	v_mfma_f32_16x16x32_bf16 v[104:107], v[158:161], v[190:193], v[104:107]
	v_mfma_f32_16x16x32_bf16 v[88:91], v[144:147], v[198:201], v[88:91]
	v_mfma_f32_16x16x32_bf16 v[92:95], v[158:161], v[198:201], v[92:95]
	v_mfma_f32_16x16x32_bf16 v[72:75], v[144:147], v[206:209], v[72:75]
	v_mfma_f32_16x16x32_bf16 v[76:79], v[158:161], v[206:209], v[76:79]
	v_mfma_f32_16x16x32_bf16 v[124:127], v[154:157], v[186:189], v[124:127]
	v_mfma_f32_16x16x32_bf16 v[120:123], v[162:165], v[186:189], v[120:123]
	v_mfma_f32_16x16x32_bf16 v[108:111], v[154:157], v[194:197], v[108:111]
	v_mfma_f32_16x16x32_bf16 v[104:107], v[162:165], v[194:197], v[104:107]
	v_mfma_f32_16x16x32_bf16 v[88:91], v[154:157], v[202:205], v[88:91]
	v_mfma_f32_16x16x32_bf16 v[92:95], v[162:165], v[202:205], v[92:95]
	v_mfma_f32_16x16x32_bf16 v[72:75], v[154:157], v[210:213], v[72:75]
	v_mfma_f32_16x16x32_bf16 v[76:79], v[162:165], v[210:213], v[76:79]
	s_setprio 0
	s_setprio 1
	v_mfma_f32_16x16x32_bf16 v[116:119], v[166:169], v[182:185], v[116:119]
	v_mfma_f32_16x16x32_bf16 v[112:115], v[174:177], v[182:185], v[112:115]
	v_mfma_f32_16x16x32_bf16 v[96:99], v[166:169], v[190:193], v[96:99]
	v_mfma_f32_16x16x32_bf16 v[100:103], v[174:177], v[190:193], v[100:103]
	v_mfma_f32_16x16x32_bf16 v[80:83], v[166:169], v[198:201], v[80:83]
	v_mfma_f32_16x16x32_bf16 v[84:87], v[174:177], v[198:201], v[84:87]
	v_mfma_f32_16x16x32_bf16 v[64:67], v[166:169], v[206:209], v[64:67]
	v_mfma_f32_16x16x32_bf16 v[68:71], v[174:177], v[206:209], v[68:71]
	v_mfma_f32_16x16x32_bf16 v[116:119], v[170:173], v[186:189], v[116:119]
	v_mfma_f32_16x16x32_bf16 v[112:115], v[178:181], v[186:189], v[112:115]
	v_mfma_f32_16x16x32_bf16 v[96:99], v[170:173], v[194:197], v[96:99]
	v_mfma_f32_16x16x32_bf16 v[100:103], v[178:181], v[194:197], v[100:103]
	v_mfma_f32_16x16x32_bf16 v[80:83], v[170:173], v[202:205], v[80:83]
	v_mfma_f32_16x16x32_bf16 v[84:87], v[178:181], v[202:205], v[84:87]
	v_mfma_f32_16x16x32_bf16 v[64:67], v[170:173], v[210:213], v[64:67]
	v_mfma_f32_16x16x32_bf16 v[68:71], v[178:181], v[210:213], v[68:71]
	s_barrier
	s_setprio 0
	s_add_i32 s26, s49, s29
	s_mov_b32 m0, s26
	ds_read_b128 v[182:185], v153 offset:49152
	ds_read_b128 v[186:189], v153 offset:50176
	ds_read_b128 v[190:193], v153 offset:51200
	ds_read_b128 v[194:197], v153 offset:52224
	ds_read_b128 v[198:201], v153 offset:53248
	ds_read_b128 v[202:205], v153 offset:54272
	ds_read_b128 v[206:209], v153 offset:55296
	ds_read_b128 v[210:213], v153 offset:56320
	global_load_lds_dwordx4 v130, s[98:99]
	s_add_i32 m0, s26, 0x2000
	s_add_u32 s20, s20, 0x160080
	s_addc_u32 s21, s21, 0
	s_add_i32 s26, s52, s29
	global_load_lds_dwordx4 v134, s[98:99]
	s_mov_b32 m0, s26
	s_nop 0
	global_load_lds_dwordx4 v130, s[20:21]
	s_add_i32 m0, s26, 0x2000
	s_nop 0
	global_load_lds_dwordx4 v134, s[20:21]
	s_mov_b32 m0, s37
	s_nop 0
	global_load_lds_dwordx4 v128, s[100:101]
	s_mov_b32 m0, s38
	s_nop 0
	global_load_lds_dwordx4 v132, s[100:101]
	s_add_i32 s48, s48, 2
	s_add_u32 s16, s16, 0x100
	s_addc_u32 s17, s17, 0
	s_add_u32 s46, s46, 0x100
	s_addc_u32 s47, s47, 0
	s_cmpk_gt_u32 s48, 0x55
	s_waitcnt vmcnt(8)
	s_waitcnt lgkmcnt(0)
	s_setprio 1
	s_barrier
	v_mfma_f32_16x16x32_bf16 v[56:59], v[144:147], v[182:185], v[56:59]
	v_mfma_f32_16x16x32_bf16 v[60:63], v[158:161], v[182:185], v[60:63]
	v_mfma_f32_16x16x32_bf16 v[40:43], v[144:147], v[190:193], v[40:43]
	v_mfma_f32_16x16x32_bf16 v[44:47], v[158:161], v[190:193], v[44:47]
	v_mfma_f32_16x16x32_bf16 v[24:27], v[144:147], v[198:201], v[24:27]
	v_mfma_f32_16x16x32_bf16 v[28:31], v[158:161], v[198:201], v[28:31]
	v_mfma_f32_16x16x32_bf16 v[8:11], v[144:147], v[206:209], v[8:11]
	v_mfma_f32_16x16x32_bf16 v[12:15], v[158:161], v[206:209], v[12:15]
	v_mfma_f32_16x16x32_bf16 v[56:59], v[154:157], v[186:189], v[56:59]
	v_mfma_f32_16x16x32_bf16 v[60:63], v[162:165], v[186:189], v[60:63]
	v_mfma_f32_16x16x32_bf16 v[40:43], v[154:157], v[194:197], v[40:43]
	v_mfma_f32_16x16x32_bf16 v[44:47], v[162:165], v[194:197], v[44:47]
	v_mfma_f32_16x16x32_bf16 v[24:27], v[154:157], v[202:205], v[24:27]
	v_mfma_f32_16x16x32_bf16 v[28:31], v[162:165], v[202:205], v[28:31]
	v_mfma_f32_16x16x32_bf16 v[8:11], v[154:157], v[210:213], v[8:11]
	v_mfma_f32_16x16x32_bf16 v[12:15], v[162:165], v[210:213], v[12:15]
	s_setprio 0
	s_setprio 1
	v_mfma_f32_16x16x32_bf16 v[48:51], v[166:169], v[182:185], v[48:51]
	v_mfma_f32_16x16x32_bf16 v[52:55], v[174:177], v[182:185], v[52:55]
	v_mfma_f32_16x16x32_bf16 v[32:35], v[166:169], v[190:193], v[32:35]
	v_mfma_f32_16x16x32_bf16 v[36:39], v[174:177], v[190:193], v[36:39]
	v_mfma_f32_16x16x32_bf16 v[16:19], v[166:169], v[198:201], v[16:19]
	v_mfma_f32_16x16x32_bf16 v[20:23], v[174:177], v[198:201], v[20:23]
	v_mfma_f32_16x16x32_bf16 v[0:3], v[166:169], v[206:209], v[0:3]
	v_mfma_f32_16x16x32_bf16 v[4:7], v[174:177], v[206:209], v[4:7]
	v_mfma_f32_16x16x32_bf16 v[48:51], v[170:173], v[186:189], v[48:51]
	v_mfma_f32_16x16x32_bf16 v[52:55], v[178:181], v[186:189], v[52:55]
	v_mfma_f32_16x16x32_bf16 v[32:35], v[170:173], v[194:197], v[32:35]
	v_mfma_f32_16x16x32_bf16 v[36:39], v[178:181], v[194:197], v[36:39]
	v_mfma_f32_16x16x32_bf16 v[16:19], v[170:173], v[202:205], v[16:19]
	v_mfma_f32_16x16x32_bf16 v[20:23], v[178:181], v[202:205], v[20:23]
	v_mfma_f32_16x16x32_bf16 v[0:3], v[170:173], v[210:213], v[0:3]
	v_mfma_f32_16x16x32_bf16 v[4:7], v[178:181], v[210:213], v[4:7]
	s_barrier
	s_setprio 0
	s_cbranch_scc0 .LBB0_1566
	s_and_b64 vcc, exec, s[10:11]
	s_cbranch_vccz .LBB0_1569
	s_barrier

	.amdhsa_kernel _Z6mk_fwd4Args
		.amdhsa_group_segment_fixed_size 0
		.amdhsa_private_segment_fixed_size 0
		.amdhsa_kernarg_size 464
		.amdhsa_user_sgpr_count 2
		.amdhsa_user_sgpr_dispatch_ptr 0
		.amdhsa_user_sgpr_queue_ptr 0
		.amdhsa_user_sgpr_kernarg_segment_ptr 1
		.amdhsa_user_sgpr_dispatch_id 0
		.amdhsa_user_sgpr_kernarg_preload_length 0
		.amdhsa_user_sgpr_kernarg_preload_offset 0
		.amdhsa_user_sgpr_private_segment_size 0
		.amdhsa_uses_dynamic_stack 0
		.amdhsa_enable_private_segment 0
		.amdhsa_system_sgpr_workgroup_id_x 1
		.amdhsa_system_sgpr_workgroup_id_y 0
		.amdhsa_system_sgpr_workgroup_id_z 0
		.amdhsa_system_sgpr_workgroup_info 0
		.amdhsa_system_vgpr_workitem_id 0
		.amdhsa_next_free_vgpr 256
		.amdhsa_next_free_sgpr 102
		.amdhsa_accum_offset 256
		.amdhsa_reserve_vcc 1
		.amdhsa_float_round_mode_32 0
		.amdhsa_float_round_mode_16_64 0
		.amdhsa_float_denorm_mode_32 3
		.amdhsa_float_denorm_mode_16_64 3
		.amdhsa_dx10_clamp 1
		.amdhsa_ieee_mode 1
		.amdhsa_fp16_overflow 0
		.amdhsa_tg_split 0
		.amdhsa_exception_fp_ieee_invalid_op 0
		.amdhsa_exception_fp_denorm_src 0
		.amdhsa_exception_fp_ieee_div_zero 0
		.amdhsa_exception_fp_ieee_overflow 0
		.amdhsa_exception_fp_ieee_underflow 0
		.amdhsa_exception_fp_ieee_inexact 0
		.amdhsa_exception_int_div_zero 0
	.end_amdhsa_kernel

amdhsa.kernels:
  - .agpr_count:     0
    .args:
      - .offset:         0
        .size:           208
        .value_kind:     by_value
      - .offset:         208
        .size:           4
        .value_kind:     hidden_block_count_x
      - .offset:         212
        .size:           4
        .value_kind:     hidden_block_count_y
      - .offset:         216
        .size:           4
        .value_kind:     hidden_block_count_z
      - .offset:         220
        .size:           2
        .value_kind:     hidden_group_size_x
      - .offset:         222
        .size:           2
        .value_kind:     hidden_group_size_y
      - .offset:         224
        .size:           2
        .value_kind:     hidden_group_size_z
      - .offset:         226
        .size:           2
        .value_kind:     hidden_remainder_x
      - .offset:         228
        .size:           2
        .value_kind:     hidden_remainder_y
      - .offset:         230
        .size:           2
        .value_kind:     hidden_remainder_z
      - .offset:         248
        .size:           8
        .value_kind:     hidden_global_offset_x
      - .offset:         256
        .size:           8
        .value_kind:     hidden_global_offset_y
      - .offset:         264
        .size:           8
        .value_kind:     hidden_global_offset_z
      - .offset:         272
        .size:           2
        .value_kind:     hidden_grid_dims
      - .offset:         296
        .size:           8
        .value_kind:     hidden_multigrid_sync_arg
      - .offset:         328
        .size:           4
        .value_kind:     hidden_dynamic_lds_size
    .group_segment_fixed_size: 0
    .kernarg_segment_align: 8
    .kernarg_segment_size: 464
    .language:       OpenCL C
    .language_version:
      - 2
      - 0
    .max_flat_workgroup_size: 512
    .name:           _Z6mk_fwd4Args
    .private_segment_fixed_size: 0
    .sgpr_count:     108
    .sgpr_spill_count: 11
    .symbol:         _Z6mk_fwd4Args.kd
    .uniform_work_group_size: 1
    .uses_dynamic_stack: false
    .vgpr_count:     256
    .vgpr_spill_count: 0
    .wavefront_size: 64
